# stack: GEMM K-loop edge rotation (SALU updates + test before closing barrier) on top of setprio-pair removal
# baseline (speedup 1.0000x reference)
; #define PG8_STAGE(bufoff, gbase, voff) do { _Pragma("unroll") for (int _i = 0; _i < 2; ++_i) \
;         __builtin_amdgcn_global_load_lds((const unsigned*)((const char*)(gbase) + (voff)[_i]), (LAS unsigned*)(lds + (bufoff) + ldsw + _i * 8192), 16, 0, 0); } while (0)
; #define PG8_LDA(dst, b, h) do { _Pragma("unroll") for (int m = 0; m < 4; ++m) _Pragma("unroll") for (int k = 0; k < 2; ++k) dst[m][k] = *(const LAS bf16x8*)(lds + PG8_SA(b, h) + aoff + m * 2048 + k * 1024); } while (0)
; #define PG8_LDB(dst, b, h) do { _Pragma("unroll") for (int n = 0; n < 2; ++n) _Pragma("unroll") for (int k = 0; k < 2; ++k) dst[n][k] = *(const LAS bf16x8*)(lds + PG8_SB(b, h) + boff + n * 2048 + k * 1024); } while (0)
; #define PG8_MMA(ai, bj, At, Bt) do { __builtin_amdgcn_s_setprio(1); _Pragma("unroll") for (int m = 0; m < 4; ++m) _Pragma("unroll") for (int n = 0; n < 2; ++n) _Pragma("unroll") for (int k = 0; k < 2; ++k) \
;         acc[ai][bj][m][n] = __builtin_amdgcn_mfma_f32_16x16x32_bf16(Bt[n][k], At[m][k], acc[ai][bj][m][n], 0, 0, 0); __builtin_amdgcn_s_setprio(0); } while (0)
; #define PG8_WAIT_V(n) asm volatile("s_waitcnt vmcnt(" #n ")" ::: "memory")
; #define PG8_WAIT_L(n) asm volatile("s_waitcnt lgkmcnt(" #n ")" ::: "memory")
; #define PG8_BAR __builtin_amdgcn_s_barrier()
; #define PG8_SCHED __builtin_amdgcn_sched_barrier(0)
; template <class Epi>
; __device__ __forceinline__ void gemm_phase(LAS unsigned char* lds, const Gemm g, const Sched& S, const Epi& E, const int tid) {
;     ...
;         const char* nA = cA; const char* nB = cB; if (has_next) S.ptrs(nxt, nA, nB);
;         for (int t = 0; t < nt; t += 2) {
;             const bool last = (t == nt - 2);
;             const char* a1 = cA + (size_t)(t + 1) * kstep;
;             const char* a2 = last ? nA : cA + (size_t)(t + 2) * kstep; const char* b2 = last ? nB : cB + (size_t)(t + 2) * kstep;
;             const char* a3 = a2 + kstep; const char* b3 = b2 + kstep;
;             PG8_LDB(B0, 0, 0); PG8_LDB(B1, 0, 1); PG8_SCHED; PG8_LDA(At, 0, 0); PG8_STAGE(PG8_SA(1, 1), a1 + hA, voffA);
;             PG8_WAIT_V(8); PG8_WAIT_L(0); PG8_BAR; PG8_MMA(0, 0, At, B0); PG8_MMA(0, 1, At, B1); PG8_BAR; PG8_SCHED;
;             PG8_LDA(At, 0, 1); PG8_STAGE(PG8_SB(0, 0), b2, voffB); PG8_STAGE(PG8_SB(0, 1), b2 + hB, voffB); PG8_STAGE(PG8_SA(0, 0), a2, voffA);
.LBB0_332:
	s_add_u32 s10, s10, 0x40080
	s_addc_u32 s11, s11, 0
	s_add_u32 s9, s74, 0x100
	s_addc_u32 s19, s75, 0
	s_mov_b32 s21, -2
	s_add_u32 s35, s10, 0xfffc0080
	s_addc_u32 s37, s11, -1
	s_add_i32 vcc_lo, 0, 0x10000
	s_cmp_eq_u32 s21, 12
	s_cselect_b32 s77, s23, s37
	s_cselect_b32 s76, s22, s35
	s_cselect_b32 s75, s73, s19
	s_cselect_b32 s74, s72, s9
	s_add_i32 s35, 0, 0x14000
	v_add_u32_e32 v156, vcc_lo, v145
	v_add_u32_e32 v172, s35, v145
	ds_read_b128 v[140:143], v156
	ds_read_b128 v[148:151], v156 offset:1024
	ds_read_b128 v[152:155], v156 offset:2048
	ds_read_b128 v[156:159], v156 offset:3072
	ds_read_b128 v[160:163], v172
	ds_read_b128 v[164:167], v172 offset:1024
	ds_read_b128 v[168:171], v172 offset:2048
	ds_read_b128 v[172:175], v172 offset:3072
	v_lshl_add_u64 v[190:191], s[10:11], 0, v[136:137]
	s_add_i32 m0, s13, 0xc000
	ds_read_b128 v[178:181], v147
	ds_read_b128 v[182:185], v147 offset:1024
	ds_read_b128 v[186:189], v147 offset:2048
	ds_read_b128 v[194:197], v147 offset:3072
	ds_read_b128 v[198:201], v147 offset:4096
	ds_read_b128 v[202:205], v147 offset:5120
	ds_read_b128 v[206:209], v147 offset:6144
	ds_read_b128 v[210:213], v147 offset:7168
	global_load_lds_dwordx4 v[190:191], off
	v_lshl_add_u64 v[190:191], s[10:11], 0, v[138:139]
	s_add_i32 m0, s13, 0xe000
	s_nop 0
	global_load_lds_dwordx4 v[190:191], off
	s_waitcnt vmcnt(8)
	s_waitcnt lgkmcnt(0)
	s_barrier
	s_setprio 1
	s_waitcnt lgkmcnt(0)
	v_mfma_f32_16x16x32_bf16 v[124:127], v[140:143], v[178:181], 0
	v_mfma_f32_16x16x32_bf16 v[120:123], v[152:155], v[178:181], 0
	v_mfma_f32_16x16x32_bf16 v[116:119], v[140:143], v[186:189], 0
	v_mfma_f32_16x16x32_bf16 v[108:111], v[152:155], v[186:189], 0
	v_mfma_f32_16x16x32_bf16 v[92:95], v[140:143], v[198:201], 0
	v_mfma_f32_16x16x32_bf16 v[88:91], v[152:155], v[198:201], 0
	v_mfma_f32_16x16x32_bf16 v[84:87], v[140:143], v[206:209], 0
	v_mfma_f32_16x16x32_bf16 v[76:79], v[152:155], v[206:209], 0
	v_mfma_f32_16x16x32_bf16 v[124:127], v[148:151], v[182:185], v[124:127]
	v_mfma_f32_16x16x32_bf16 v[120:123], v[156:159], v[182:185], v[120:123]
	v_mfma_f32_16x16x32_bf16 v[116:119], v[148:151], v[194:197], v[116:119]
	v_mfma_f32_16x16x32_bf16 v[108:111], v[156:159], v[194:197], v[108:111]
	v_mfma_f32_16x16x32_bf16 v[92:95], v[148:151], v[202:205], v[92:95]
	v_mfma_f32_16x16x32_bf16 v[88:91], v[156:159], v[202:205], v[88:91]
	v_mfma_f32_16x16x32_bf16 v[84:87], v[148:151], v[210:213], v[84:87]
	v_mfma_f32_16x16x32_bf16 v[76:79], v[156:159], v[210:213], v[76:79]
	v_mfma_f32_16x16x32_bf16 v[112:115], v[160:163], v[178:181], 0
	v_mfma_f32_16x16x32_bf16 v[104:107], v[168:171], v[178:181], 0
	v_mfma_f32_16x16x32_bf16 v[100:103], v[160:163], v[186:189], 0
	v_mfma_f32_16x16x32_bf16 v[96:99], v[168:171], v[186:189], 0
	v_mfma_f32_16x16x32_bf16 v[80:83], v[160:163], v[198:201], 0
	v_mfma_f32_16x16x32_bf16 v[72:75], v[168:171], v[198:201], 0
	v_mfma_f32_16x16x32_bf16 v[68:71], v[160:163], v[206:209], 0
	v_mfma_f32_16x16x32_bf16 v[64:67], v[168:171], v[206:209], 0
	v_mfma_f32_16x16x32_bf16 v[112:115], v[164:167], v[182:185], v[112:115]
	v_mfma_f32_16x16x32_bf16 v[104:107], v[172:175], v[182:185], v[104:107]
	v_mfma_f32_16x16x32_bf16 v[100:103], v[164:167], v[194:197], v[100:103]
	v_mfma_f32_16x16x32_bf16 v[96:99], v[172:175], v[194:197], v[96:99]
	v_mfma_f32_16x16x32_bf16 v[80:83], v[164:167], v[202:205], v[80:83]
	v_mfma_f32_16x16x32_bf16 v[72:75], v[172:175], v[202:205], v[72:75]
	v_mfma_f32_16x16x32_bf16 v[68:71], v[164:167], v[210:213], v[68:71]
	v_mfma_f32_16x16x32_bf16 v[64:67], v[172:175], v[210:213], v[64:67]
	s_setprio 0
	s_barrier
	s_add_i32 s37, vcc_lo, s39
	v_lshl_add_u64 v[190:191], s[74:75], 0, v[192:193]
	s_mov_b32 m0, s37
	ds_read_b128 v[178:181], v147 offset:16384
	ds_read_b128 v[182:185], v147 offset:17408
	ds_read_b128 v[186:189], v147 offset:18432
	ds_read_b128 v[194:197], v147 offset:19456
	ds_read_b128 v[198:201], v147 offset:20480
	ds_read_b128 v[202:205], v147 offset:21504
	ds_read_b128 v[206:209], v147 offset:22528
	ds_read_b128 v[210:213], v147 offset:23552
	global_load_lds_dwordx4 v[190:191], off
	s_add_i32 m0, s37, 0x2000
	s_add_u32 vcc_lo, s74, 0x40000
	v_lshl_add_u64 v[214:215], s[74:75], 0, v[132:133]
	s_addc_u32 vcc_hi, s75, 0
	s_add_i32 s35, s35, s39
	global_load_lds_dwordx4 v[214:215], off
	v_lshl_add_u64 v[216:217], vcc, 0, v[192:193]
	s_mov_b32 m0, s35
	v_lshl_add_u64 v[218:219], s[76:77], 0, v[130:131]
	global_load_lds_dwordx4 v[216:217], off
	v_lshl_add_u64 v[216:217], vcc, 0, v[132:133]
	s_add_i32 m0, s35, 0x2000
	s_nop 0
	global_load_lds_dwordx4 v[216:217], off
	v_lshl_add_u64 v[216:217], s[76:77], 0, v[128:129]
	s_mov_b32 m0, s13
	s_nop 0
	global_load_lds_dwordx4 v[216:217], off
	s_mov_b32 m0, s40
	s_nop 0
	global_load_lds_dwordx4 v[218:219], off
	s_waitcnt vmcnt(8)
	s_waitcnt lgkmcnt(0)
	s_barrier
; #define PG8_STAGE(bufoff, gbase, voff) do { _Pragma("unroll") for (int _i = 0; _i < 2; ++_i) \
;         __builtin_amdgcn_global_load_lds((const unsigned*)((const char*)(gbase) + (voff)[_i]), (LAS unsigned*)(lds + (bufoff) + ldsw + _i * 8192), 16, 0, 0); } while (0)
; #define PG8_LDA(dst, b, h) do { _Pragma("unroll") for (int m = 0; m < 4; ++m) _Pragma("unroll") for (int k = 0; k < 2; ++k) dst[m][k] = *(const LAS bf16x8*)(lds + PG8_SA(b, h) + aoff + m * 2048 + k * 1024); } while (0)
; #define PG8_LDB(dst, b, h) do { _Pragma("unroll") for (int n = 0; n < 2; ++n) _Pragma("unroll") for (int k = 0; k < 2; ++k) dst[n][k] = *(const LAS bf16x8*)(lds + PG8_SB(b, h) + boff + n * 2048 + k * 1024); } while (0)
; #define PG8_MMA(ai, bj, At, Bt) do { __builtin_amdgcn_s_setprio(1); _Pragma("unroll") for (int m = 0; m < 4; ++m) _Pragma("unroll") for (int n = 0; n < 2; ++n) _Pragma("unroll") for (int k = 0; k < 2; ++k) \
;         acc[ai][bj][m][n] = __builtin_amdgcn_mfma_f32_16x16x32_bf16(Bt[n][k], At[m][k], acc[ai][bj][m][n], 0, 0, 0); __builtin_amdgcn_s_setprio(0); } while (0)
; #define PG8_WAIT_V(n) asm volatile("s_waitcnt vmcnt(" #n ")" ::: "memory")
; #define PG8_WAIT_L(n) asm volatile("s_waitcnt lgkmcnt(" #n ")" ::: "memory")
; #define PG8_BAR __builtin_amdgcn_s_barrier()
; #define PG8_SCHED __builtin_amdgcn_sched_barrier(0)
; template <class Epi>
; __device__ __forceinline__ void gemm_phase(LAS unsigned char* lds, const Gemm g, const Sched& S, const Epi& E, const int tid) {
;     ...
;             PG8_WAIT_V(8); PG8_WAIT_L(0); PG8_BAR; PG8_MMA(1, 0, At, B0); PG8_MMA(1, 1, At, B1); PG8_BAR; PG8_SCHED;
;             PG8_LDB(B0, 1, 0); PG8_LDB(B1, 1, 1); PG8_SCHED; PG8_LDA(At, 1, 0); PG8_STAGE(PG8_SA(0, 1), a2 + hA, voffA);
;             PG8_WAIT_V(8); PG8_WAIT_L(0); PG8_BAR; PG8_MMA(0, 0, At, B0); PG8_MMA(0, 1, At, B1); PG8_BAR; PG8_SCHED;
	s_setprio 1
	s_waitcnt lgkmcnt(0)
	v_mfma_f32_16x16x32_bf16 v[60:63], v[140:143], v[178:181], 0
	v_mfma_f32_16x16x32_bf16 v[56:59], v[152:155], v[178:181], 0
	v_mfma_f32_16x16x32_bf16 v[52:55], v[140:143], v[186:189], 0
	v_mfma_f32_16x16x32_bf16 v[44:47], v[152:155], v[186:189], 0
	v_mfma_f32_16x16x32_bf16 v[28:31], v[140:143], v[198:201], 0
	v_mfma_f32_16x16x32_bf16 v[24:27], v[152:155], v[198:201], 0
	v_mfma_f32_16x16x32_bf16 v[20:23], v[140:143], v[206:209], 0
	v_mfma_f32_16x16x32_bf16 v[12:15], v[152:155], v[206:209], 0
	v_mfma_f32_16x16x32_bf16 v[60:63], v[148:151], v[182:185], v[60:63]
	v_mfma_f32_16x16x32_bf16 v[56:59], v[156:159], v[182:185], v[56:59]
	v_mfma_f32_16x16x32_bf16 v[52:55], v[148:151], v[194:197], v[52:55]
	v_mfma_f32_16x16x32_bf16 v[44:47], v[156:159], v[194:197], v[44:47]
	v_mfma_f32_16x16x32_bf16 v[28:31], v[148:151], v[202:205], v[28:31]
	v_mfma_f32_16x16x32_bf16 v[24:27], v[156:159], v[202:205], v[24:27]
	v_mfma_f32_16x16x32_bf16 v[20:23], v[148:151], v[210:213], v[20:23]
	v_mfma_f32_16x16x32_bf16 v[12:15], v[156:159], v[210:213], v[12:15]
	v_mfma_f32_16x16x32_bf16 v[48:51], v[160:163], v[178:181], 0
	v_mfma_f32_16x16x32_bf16 v[40:43], v[168:171], v[178:181], 0
	v_mfma_f32_16x16x32_bf16 v[36:39], v[160:163], v[186:189], 0
	v_mfma_f32_16x16x32_bf16 v[32:35], v[168:171], v[186:189], 0
	v_mfma_f32_16x16x32_bf16 v[16:19], v[160:163], v[198:201], 0
	v_mfma_f32_16x16x32_bf16 v[8:11], v[168:171], v[198:201], 0
	v_mfma_f32_16x16x32_bf16 v[4:7], v[160:163], v[206:209], 0
	v_mfma_f32_16x16x32_bf16 v[0:3], v[168:171], v[206:209], 0
	v_mfma_f32_16x16x32_bf16 v[48:51], v[164:167], v[182:185], v[48:51]
	v_mfma_f32_16x16x32_bf16 v[40:43], v[172:175], v[182:185], v[40:43]
	v_mfma_f32_16x16x32_bf16 v[36:39], v[164:167], v[194:197], v[36:39]
	v_mfma_f32_16x16x32_bf16 v[32:35], v[172:175], v[194:197], v[32:35]
	v_mfma_f32_16x16x32_bf16 v[16:19], v[164:167], v[202:205], v[16:19]
	v_mfma_f32_16x16x32_bf16 v[8:11], v[172:175], v[202:205], v[8:11]
	v_mfma_f32_16x16x32_bf16 v[4:7], v[164:167], v[210:213], v[4:7]
	v_mfma_f32_16x16x32_bf16 v[0:3], v[172:175], v[210:213], v[0:3]
	s_setprio 0
	s_barrier
	s_add_i32 s35, 0, 0x18000
	s_add_i32 s37, 0, 0x1c000
	v_add_u32_e32 v156, s35, v145
	v_add_u32_e32 v172, s37, v145
	ds_read_b128 v[140:143], v156
	ds_read_b128 v[148:151], v156 offset:1024
	ds_read_b128 v[152:155], v156 offset:2048
	ds_read_b128 v[156:159], v156 offset:3072
	ds_read_b128 v[160:163], v172
	ds_read_b128 v[164:167], v172 offset:1024
	ds_read_b128 v[168:171], v172 offset:2048
	ds_read_b128 v[172:175], v172 offset:3072
	s_add_u32 s76, s76, 0x40000
	s_addc_u32 s77, s77, 0
	s_mov_b32 m0, s45
	v_lshl_add_u64 v[224:225], s[76:77], 0, v[128:129]
	ds_read_b128 v[178:181], v147 offset:32768
	ds_read_b128 v[182:185], v147 offset:33792
	ds_read_b128 v[186:189], v147 offset:34816
	ds_read_b128 v[194:197], v147 offset:35840
	ds_read_b128 v[198:201], v147 offset:36864
	ds_read_b128 v[202:205], v147 offset:37888
	ds_read_b128 v[206:209], v147 offset:38912
	ds_read_b128 v[210:213], v147 offset:39936
	global_load_lds_dwordx4 v[224:225], off
	v_lshl_add_u64 v[224:225], s[76:77], 0, v[130:131]
	s_mov_b32 m0, s47
	s_nop 0
	global_load_lds_dwordx4 v[224:225], off
	s_waitcnt vmcnt(8)
	s_waitcnt lgkmcnt(0)
	s_barrier
	s_setprio 1
	s_waitcnt lgkmcnt(0)
	v_mfma_f32_16x16x32_bf16 v[124:127], v[140:143], v[178:181], v[124:127]
	v_mfma_f32_16x16x32_bf16 v[120:123], v[152:155], v[178:181], v[120:123]
	v_mfma_f32_16x16x32_bf16 v[116:119], v[140:143], v[186:189], v[116:119]
	v_mfma_f32_16x16x32_bf16 v[108:111], v[152:155], v[186:189], v[108:111]
	v_mfma_f32_16x16x32_bf16 v[92:95], v[140:143], v[198:201], v[92:95]
	v_mfma_f32_16x16x32_bf16 v[88:91], v[152:155], v[198:201], v[88:91]
	v_mfma_f32_16x16x32_bf16 v[84:87], v[140:143], v[206:209], v[84:87]
	v_mfma_f32_16x16x32_bf16 v[76:79], v[152:155], v[206:209], v[76:79]
	v_mfma_f32_16x16x32_bf16 v[124:127], v[148:151], v[182:185], v[124:127]
	v_mfma_f32_16x16x32_bf16 v[120:123], v[156:159], v[182:185], v[120:123]
	v_mfma_f32_16x16x32_bf16 v[116:119], v[148:151], v[194:197], v[116:119]
	v_mfma_f32_16x16x32_bf16 v[108:111], v[156:159], v[194:197], v[108:111]
	v_mfma_f32_16x16x32_bf16 v[92:95], v[148:151], v[202:205], v[92:95]
	v_mfma_f32_16x16x32_bf16 v[88:91], v[156:159], v[202:205], v[88:91]
	v_mfma_f32_16x16x32_bf16 v[84:87], v[148:151], v[210:213], v[84:87]
	v_mfma_f32_16x16x32_bf16 v[76:79], v[156:159], v[210:213], v[76:79]
	v_mfma_f32_16x16x32_bf16 v[112:115], v[160:163], v[178:181], v[112:115]
	v_mfma_f32_16x16x32_bf16 v[104:107], v[168:171], v[178:181], v[104:107]
	v_mfma_f32_16x16x32_bf16 v[100:103], v[160:163], v[186:189], v[100:103]
	v_mfma_f32_16x16x32_bf16 v[96:99], v[168:171], v[186:189], v[96:99]
	v_mfma_f32_16x16x32_bf16 v[80:83], v[160:163], v[198:201], v[80:83]
	v_mfma_f32_16x16x32_bf16 v[72:75], v[168:171], v[198:201], v[72:75]
	v_mfma_f32_16x16x32_bf16 v[68:71], v[160:163], v[206:209], v[68:71]
	v_mfma_f32_16x16x32_bf16 v[64:67], v[168:171], v[206:209], v[64:67]
	v_mfma_f32_16x16x32_bf16 v[112:115], v[164:167], v[182:185], v[112:115]
	v_mfma_f32_16x16x32_bf16 v[104:107], v[172:175], v[182:185], v[104:107]
	v_mfma_f32_16x16x32_bf16 v[100:103], v[164:167], v[194:197], v[100:103]
	v_mfma_f32_16x16x32_bf16 v[96:99], v[172:175], v[194:197], v[96:99]
	v_mfma_f32_16x16x32_bf16 v[80:83], v[164:167], v[202:205], v[80:83]
	v_mfma_f32_16x16x32_bf16 v[72:75], v[172:175], v[202:205], v[72:75]
	v_mfma_f32_16x16x32_bf16 v[68:71], v[164:167], v[210:213], v[68:71]
	v_mfma_f32_16x16x32_bf16 v[64:67], v[172:175], v[210:213], v[64:67]
	s_setprio 0
	s_barrier
; #define PG8_STAGE(bufoff, gbase, voff) do { _Pragma("unroll") for (int _i = 0; _i < 2; ++_i) \
;         __builtin_amdgcn_global_load_lds((const unsigned*)((const char*)(gbase) + (voff)[_i]), (LAS unsigned*)(lds + (bufoff) + ldsw + _i * 8192), 16, 0, 0); } while (0)
; #define PG8_LDA(dst, b, h) do { _Pragma("unroll") for (int m = 0; m < 4; ++m) _Pragma("unroll") for (int k = 0; k < 2; ++k) dst[m][k] = *(const LAS bf16x8*)(lds + PG8_SA(b, h) + aoff + m * 2048 + k * 1024); } while (0)
; #define PG8_LDB(dst, b, h) do { _Pragma("unroll") for (int n = 0; n < 2; ++n) _Pragma("unroll") for (int k = 0; k < 2; ++k) dst[n][k] = *(const LAS bf16x8*)(lds + PG8_SB(b, h) + boff + n * 2048 + k * 1024); } while (0)
; #define PG8_WAIT_V(n) asm volatile("s_waitcnt vmcnt(" #n ")" ::: "memory")
; #define PG8_WAIT_L(n) asm volatile("s_waitcnt lgkmcnt(" #n ")" ::: "memory")
; template <class Epi>
; __device__ __forceinline__ void gemm_phase(LAS unsigned char* lds, const Gemm g, const Sched& S, const Epi& E, const int tid) {
;     ...
;         for (int t = 0; t < nt; t += 2) {
;             const bool last = (t == nt - 2);
;             const char* a1 = cA + (size_t)(t + 1) * kstep;
;             const char* a2 = last ? nA : cA + (size_t)(t + 2) * kstep; const char* b2 = last ? nB : cB + (size_t)(t + 2) * kstep;
;             const char* a3 = a2 + kstep; const char* b3 = b2 + kstep;
;             PG8_LDB(B0, 0, 0); PG8_LDB(B1, 0, 1); PG8_SCHED; PG8_LDA(At, 0, 0); PG8_STAGE(PG8_SA(1, 1), a1 + hA, voffA);
;             PG8_WAIT_V(8); PG8_WAIT_L(0); PG8_BAR; PG8_MMA(0, 0, At, B0); PG8_MMA(0, 1, At, B1); PG8_BAR; PG8_SCHED;
;             PG8_LDA(At, 0, 1); PG8_STAGE(PG8_SB(0, 0), b2, voffB); PG8_STAGE(PG8_SB(0, 1), b2 + hB, voffB); PG8_STAGE(PG8_SA(0, 0), a2, voffA);
;             PG8_WAIT_V(8); PG8_WAIT_L(0); PG8_BAR; PG8_MMA(1, 0, At, B0); PG8_MMA(1, 1, At, B1); PG8_BAR; PG8_SCHED;
;             PG8_LDB(B0, 1, 0); PG8_LDB(B1, 1, 1); PG8_SCHED; PG8_LDA(At, 1, 0); PG8_STAGE(PG8_SA(0, 1), a2 + hA, voffA);
;             PG8_WAIT_V(8); PG8_WAIT_L(0); PG8_BAR; PG8_MMA(0, 0, At, B0); PG8_MMA(0, 1, At, B1); PG8_BAR; PG8_SCHED;
;             PG8_LDA(At, 1, 1); PG8_STAGE(PG8_SB(1, 0), b3, voffB); PG8_STAGE(PG8_SB(1, 1), b3 + hB, voffB); PG8_STAGE(PG8_SA(1, 0), a3, voffA);
;             PG8_WAIT_V(8); PG8_WAIT_L(0); PG8_BAR; PG8_MMA(1, 0, At, B0); PG8_MMA(1, 1, At, B1); PG8_BAR; PG8_SCHED;
	s_add_i32 s35, s35, s39
	v_lshl_add_u64 v[190:191], v[190:191], 0, s[94:95]
	s_mov_b32 m0, s35
	ds_read_b128 v[178:181], v147 offset:49152
	ds_read_b128 v[182:185], v147 offset:50176
	ds_read_b128 v[186:189], v147 offset:51200
	ds_read_b128 v[194:197], v147 offset:52224
	ds_read_b128 v[198:201], v147 offset:53248
	ds_read_b128 v[202:205], v147 offset:54272
	ds_read_b128 v[206:209], v147 offset:55296
	ds_read_b128 v[210:213], v147 offset:56320
	global_load_lds_dwordx4 v[190:191], off
	s_add_i32 m0, s35, 0x2000
	s_add_u32 s74, s74, 0x40080
	v_lshl_add_u64 v[190:191], v[214:215], 0, s[94:95]
	s_addc_u32 s75, s75, 0
	s_add_i32 s35, s37, s39
	global_load_lds_dwordx4 v[190:191], off
	v_lshl_add_u64 v[190:191], s[74:75], 0, v[192:193]
	s_mov_b32 m0, s35
	s_nop 0
	global_load_lds_dwordx4 v[190:191], off
	v_lshl_add_u64 v[190:191], s[74:75], 0, v[132:133]
	s_add_i32 m0, s35, 0x2000
	s_nop 0
	global_load_lds_dwordx4 v[190:191], off
	v_lshl_add_u64 v[190:191], v[216:217], 0, s[94:95]
	s_mov_b32 m0, s78
	s_nop 0
	global_load_lds_dwordx4 v[190:191], off
	v_lshl_add_u64 v[190:191], v[218:219], 0, s[94:95]
	s_mov_b32 m0, s80
	s_nop 0
	global_load_lds_dwordx4 v[190:191], off
	s_waitcnt vmcnt(8)
	s_waitcnt lgkmcnt(0)
	s_barrier
	s_setprio 1
	s_waitcnt lgkmcnt(0)
	v_mfma_f32_16x16x32_bf16 v[60:63], v[140:143], v[178:181], v[60:63]
	v_mfma_f32_16x16x32_bf16 v[56:59], v[152:155], v[178:181], v[56:59]
	v_mfma_f32_16x16x32_bf16 v[52:55], v[140:143], v[186:189], v[52:55]
	v_mfma_f32_16x16x32_bf16 v[44:47], v[152:155], v[186:189], v[44:47]
	v_mfma_f32_16x16x32_bf16 v[28:31], v[140:143], v[198:201], v[28:31]
	v_mfma_f32_16x16x32_bf16 v[24:27], v[152:155], v[198:201], v[24:27]
	v_mfma_f32_16x16x32_bf16 v[20:23], v[140:143], v[206:209], v[20:23]
	v_mfma_f32_16x16x32_bf16 v[12:15], v[152:155], v[206:209], v[12:15]
	v_mfma_f32_16x16x32_bf16 v[60:63], v[148:151], v[182:185], v[60:63]
	v_mfma_f32_16x16x32_bf16 v[56:59], v[156:159], v[182:185], v[56:59]
	v_mfma_f32_16x16x32_bf16 v[52:55], v[148:151], v[194:197], v[52:55]
	v_mfma_f32_16x16x32_bf16 v[44:47], v[156:159], v[194:197], v[44:47]
	v_mfma_f32_16x16x32_bf16 v[28:31], v[148:151], v[202:205], v[28:31]
	v_mfma_f32_16x16x32_bf16 v[24:27], v[156:159], v[202:205], v[24:27]
	v_mfma_f32_16x16x32_bf16 v[20:23], v[148:151], v[210:213], v[20:23]
	v_mfma_f32_16x16x32_bf16 v[12:15], v[156:159], v[210:213], v[12:15]
	v_mfma_f32_16x16x32_bf16 v[48:51], v[160:163], v[178:181], v[48:51]
	v_mfma_f32_16x16x32_bf16 v[40:43], v[168:171], v[178:181], v[40:43]
	v_mfma_f32_16x16x32_bf16 v[36:39], v[160:163], v[186:189], v[36:39]
	v_mfma_f32_16x16x32_bf16 v[32:35], v[168:171], v[186:189], v[32:35]
	v_mfma_f32_16x16x32_bf16 v[16:19], v[160:163], v[198:201], v[16:19]
	v_mfma_f32_16x16x32_bf16 v[8:11], v[168:171], v[198:201], v[8:11]
	v_mfma_f32_16x16x32_bf16 v[4:7], v[160:163], v[206:209], v[4:7]
	v_mfma_f32_16x16x32_bf16 v[0:3], v[168:171], v[206:209], v[0:3]
	v_mfma_f32_16x16x32_bf16 v[48:51], v[164:167], v[182:185], v[48:51]
	v_mfma_f32_16x16x32_bf16 v[40:43], v[172:175], v[182:185], v[40:43]
	v_mfma_f32_16x16x32_bf16 v[36:39], v[164:167], v[194:197], v[36:39]
	v_mfma_f32_16x16x32_bf16 v[32:35], v[172:175], v[194:197], v[32:35]
	v_mfma_f32_16x16x32_bf16 v[16:19], v[164:167], v[202:205], v[16:19]
	v_mfma_f32_16x16x32_bf16 v[8:11], v[172:175], v[202:205], v[8:11]
	v_mfma_f32_16x16x32_bf16 v[4:7], v[164:167], v[210:213], v[4:7]
	v_mfma_f32_16x16x32_bf16 v[0:3], v[172:175], v[210:213], v[0:3]
	s_add_i32 s21, s21, 2
	s_add_u32 s10, s10, 0x100
	s_addc_u32 s11, s11, 0
	s_add_u32 s9, s9, 0x100
	s_addc_u32 s19, s19, 0
	s_cmp_gt_u32 s21, 13
	s_setprio 0
	s_barrier
	s_cbranch_scc1 .Lgk_exit_0
.LBB0_333:
	s_add_u32 s35, s10, 0xfffc0080
	s_addc_u32 s37, s11, -1
	s_add_i32 vcc_lo, 0, 0x10000
	s_cmp_eq_u32 s21, 12
	s_cselect_b32 s77, s23, s37
	s_cselect_b32 s76, s22, s35
	s_cselect_b32 s75, s73, s19
	s_cselect_b32 s74, s72, s9
	s_add_i32 s35, 0, 0x14000
	v_add_u32_e32 v156, vcc_lo, v145
	v_add_u32_e32 v172, s35, v145
	ds_read_b128 v[140:143], v156
	ds_read_b128 v[148:151], v156 offset:1024
	ds_read_b128 v[152:155], v156 offset:2048
	ds_read_b128 v[156:159], v156 offset:3072
	ds_read_b128 v[160:163], v172
	ds_read_b128 v[164:167], v172 offset:1024
	ds_read_b128 v[168:171], v172 offset:2048
	ds_read_b128 v[172:175], v172 offset:3072
	v_lshl_add_u64 v[190:191], s[10:11], 0, v[136:137]
	s_add_i32 m0, s13, 0xc000
	ds_read_b128 v[178:181], v147
	ds_read_b128 v[182:185], v147 offset:1024
	ds_read_b128 v[186:189], v147 offset:2048
	ds_read_b128 v[194:197], v147 offset:3072
	ds_read_b128 v[198:201], v147 offset:4096
	ds_read_b128 v[202:205], v147 offset:5120
	ds_read_b128 v[206:209], v147 offset:6144
	ds_read_b128 v[210:213], v147 offset:7168
	global_load_lds_dwordx4 v[190:191], off
	v_lshl_add_u64 v[190:191], s[10:11], 0, v[138:139]
	s_add_i32 m0, s13, 0xe000
	s_nop 0
	global_load_lds_dwordx4 v[190:191], off
	s_waitcnt vmcnt(8)
	s_waitcnt lgkmcnt(0)
	s_barrier
; #define PG8_STAGE(bufoff, gbase, voff) do { _Pragma("unroll") for (int _i = 0; _i < 2; ++_i) \
;         __builtin_amdgcn_global_load_lds((const unsigned*)((const char*)(gbase) + (voff)[_i]), (LAS unsigned*)(lds + (bufoff) + ldsw + _i * 8192), 16, 0, 0); } while (0)
; #define PG8_LDA(dst, b, h) do { _Pragma("unroll") for (int m = 0; m < 4; ++m) _Pragma("unroll") for (int k = 0; k < 2; ++k) dst[m][k] = *(const LAS bf16x8*)(lds + PG8_SA(b, h) + aoff + m * 2048 + k * 1024); } while (0)
; #define PG8_MMA(ai, bj, At, Bt) do { __builtin_amdgcn_s_setprio(1); _Pragma("unroll") for (int m = 0; m < 4; ++m) _Pragma("unroll") for (int n = 0; n < 2; ++n) _Pragma("unroll") for (int k = 0; k < 2; ++k) \
;         acc[ai][bj][m][n] = __builtin_amdgcn_mfma_f32_16x16x32_bf16(Bt[n][k], At[m][k], acc[ai][bj][m][n], 0, 0, 0); __builtin_amdgcn_s_setprio(0); } while (0)
; #define PG8_WAIT_V(n) asm volatile("s_waitcnt vmcnt(" #n ")" ::: "memory")
; #define PG8_WAIT_L(n) asm volatile("s_waitcnt lgkmcnt(" #n ")" ::: "memory")
; #define PG8_BAR __builtin_amdgcn_s_barrier()
; #define PG8_SCHED __builtin_amdgcn_sched_barrier(0)
; template <class Epi>
; __device__ __forceinline__ void gemm_phase(LAS unsigned char* lds, const Gemm g, const Sched& S, const Epi& E, const int tid) {
;     ...
;             PG8_WAIT_V(8); PG8_WAIT_L(0); PG8_BAR; PG8_MMA(0, 0, At, B0); PG8_MMA(0, 1, At, B1); PG8_BAR; PG8_SCHED;
;             PG8_LDA(At, 0, 1); PG8_STAGE(PG8_SB(0, 0), b2, voffB); PG8_STAGE(PG8_SB(0, 1), b2 + hB, voffB); PG8_STAGE(PG8_SA(0, 0), a2, voffA);
;             PG8_WAIT_V(8); PG8_WAIT_L(0); PG8_BAR; PG8_MMA(1, 0, At, B0); PG8_MMA(1, 1, At, B1); PG8_BAR; PG8_SCHED;
	s_setprio 1
	s_waitcnt lgkmcnt(0)
	v_mfma_f32_16x16x32_bf16 v[124:127], v[140:143], v[178:181], v[124:127]
	v_mfma_f32_16x16x32_bf16 v[120:123], v[152:155], v[178:181], v[120:123]
	v_mfma_f32_16x16x32_bf16 v[116:119], v[140:143], v[186:189], v[116:119]
	v_mfma_f32_16x16x32_bf16 v[108:111], v[152:155], v[186:189], v[108:111]
	v_mfma_f32_16x16x32_bf16 v[92:95], v[140:143], v[198:201], v[92:95]
	v_mfma_f32_16x16x32_bf16 v[88:91], v[152:155], v[198:201], v[88:91]
	v_mfma_f32_16x16x32_bf16 v[84:87], v[140:143], v[206:209], v[84:87]
	v_mfma_f32_16x16x32_bf16 v[76:79], v[152:155], v[206:209], v[76:79]
	v_mfma_f32_16x16x32_bf16 v[124:127], v[148:151], v[182:185], v[124:127]
	v_mfma_f32_16x16x32_bf16 v[120:123], v[156:159], v[182:185], v[120:123]
	v_mfma_f32_16x16x32_bf16 v[116:119], v[148:151], v[194:197], v[116:119]
	v_mfma_f32_16x16x32_bf16 v[108:111], v[156:159], v[194:197], v[108:111]
	v_mfma_f32_16x16x32_bf16 v[92:95], v[148:151], v[202:205], v[92:95]
	v_mfma_f32_16x16x32_bf16 v[88:91], v[156:159], v[202:205], v[88:91]
	v_mfma_f32_16x16x32_bf16 v[84:87], v[148:151], v[210:213], v[84:87]
	v_mfma_f32_16x16x32_bf16 v[76:79], v[156:159], v[210:213], v[76:79]
	v_mfma_f32_16x16x32_bf16 v[112:115], v[160:163], v[178:181], v[112:115]
	v_mfma_f32_16x16x32_bf16 v[104:107], v[168:171], v[178:181], v[104:107]
	v_mfma_f32_16x16x32_bf16 v[100:103], v[160:163], v[186:189], v[100:103]
	v_mfma_f32_16x16x32_bf16 v[96:99], v[168:171], v[186:189], v[96:99]
	v_mfma_f32_16x16x32_bf16 v[80:83], v[160:163], v[198:201], v[80:83]
	v_mfma_f32_16x16x32_bf16 v[72:75], v[168:171], v[198:201], v[72:75]
	v_mfma_f32_16x16x32_bf16 v[68:71], v[160:163], v[206:209], v[68:71]
	v_mfma_f32_16x16x32_bf16 v[64:67], v[168:171], v[206:209], v[64:67]
	v_mfma_f32_16x16x32_bf16 v[112:115], v[164:167], v[182:185], v[112:115]
	v_mfma_f32_16x16x32_bf16 v[104:107], v[172:175], v[182:185], v[104:107]
	v_mfma_f32_16x16x32_bf16 v[100:103], v[164:167], v[194:197], v[100:103]
	v_mfma_f32_16x16x32_bf16 v[96:99], v[172:175], v[194:197], v[96:99]
	v_mfma_f32_16x16x32_bf16 v[80:83], v[164:167], v[202:205], v[80:83]
	v_mfma_f32_16x16x32_bf16 v[72:75], v[172:175], v[202:205], v[72:75]
	v_mfma_f32_16x16x32_bf16 v[68:71], v[164:167], v[210:213], v[68:71]
	v_mfma_f32_16x16x32_bf16 v[64:67], v[172:175], v[210:213], v[64:67]
	s_setprio 0
	s_barrier
	s_add_i32 s37, vcc_lo, s39
	v_lshl_add_u64 v[190:191], s[74:75], 0, v[192:193]
	s_mov_b32 m0, s37
	ds_read_b128 v[178:181], v147 offset:16384
	ds_read_b128 v[182:185], v147 offset:17408
	ds_read_b128 v[186:189], v147 offset:18432
	ds_read_b128 v[194:197], v147 offset:19456
	ds_read_b128 v[198:201], v147 offset:20480
	ds_read_b128 v[202:205], v147 offset:21504
	ds_read_b128 v[206:209], v147 offset:22528
	ds_read_b128 v[210:213], v147 offset:23552
	global_load_lds_dwordx4 v[190:191], off
	s_add_i32 m0, s37, 0x2000
	s_add_u32 vcc_lo, s74, 0x40000
	v_lshl_add_u64 v[214:215], s[74:75], 0, v[132:133]
	s_addc_u32 vcc_hi, s75, 0
	s_add_i32 s35, s35, s39
	global_load_lds_dwordx4 v[214:215], off
	v_lshl_add_u64 v[216:217], vcc, 0, v[192:193]
	s_mov_b32 m0, s35
	v_lshl_add_u64 v[218:219], s[76:77], 0, v[130:131]
	global_load_lds_dwordx4 v[216:217], off
	v_lshl_add_u64 v[216:217], vcc, 0, v[132:133]
	s_add_i32 m0, s35, 0x2000
	s_nop 0
	global_load_lds_dwordx4 v[216:217], off
	v_lshl_add_u64 v[216:217], s[76:77], 0, v[128:129]
	s_mov_b32 m0, s13
	s_nop 0
	global_load_lds_dwordx4 v[216:217], off
	s_mov_b32 m0, s40
	s_nop 0
	global_load_lds_dwordx4 v[218:219], off
	s_waitcnt vmcnt(8)
	s_waitcnt lgkmcnt(0)
	s_barrier
	s_setprio 1
	s_waitcnt lgkmcnt(0)
	v_mfma_f32_16x16x32_bf16 v[60:63], v[140:143], v[178:181], v[60:63]
	v_mfma_f32_16x16x32_bf16 v[56:59], v[152:155], v[178:181], v[56:59]
	v_mfma_f32_16x16x32_bf16 v[52:55], v[140:143], v[186:189], v[52:55]
	v_mfma_f32_16x16x32_bf16 v[44:47], v[152:155], v[186:189], v[44:47]
	v_mfma_f32_16x16x32_bf16 v[28:31], v[140:143], v[198:201], v[28:31]
	v_mfma_f32_16x16x32_bf16 v[24:27], v[152:155], v[198:201], v[24:27]
	v_mfma_f32_16x16x32_bf16 v[20:23], v[140:143], v[206:209], v[20:23]
	v_mfma_f32_16x16x32_bf16 v[12:15], v[152:155], v[206:209], v[12:15]
	v_mfma_f32_16x16x32_bf16 v[60:63], v[148:151], v[182:185], v[60:63]
	v_mfma_f32_16x16x32_bf16 v[56:59], v[156:159], v[182:185], v[56:59]
	v_mfma_f32_16x16x32_bf16 v[52:55], v[148:151], v[194:197], v[52:55]
	v_mfma_f32_16x16x32_bf16 v[44:47], v[156:159], v[194:197], v[44:47]
	v_mfma_f32_16x16x32_bf16 v[28:31], v[148:151], v[202:205], v[28:31]
	v_mfma_f32_16x16x32_bf16 v[24:27], v[156:159], v[202:205], v[24:27]
	v_mfma_f32_16x16x32_bf16 v[20:23], v[148:151], v[210:213], v[20:23]
	v_mfma_f32_16x16x32_bf16 v[12:15], v[156:159], v[210:213], v[12:15]
	v_mfma_f32_16x16x32_bf16 v[48:51], v[160:163], v[178:181], v[48:51]
	v_mfma_f32_16x16x32_bf16 v[40:43], v[168:171], v[178:181], v[40:43]
	v_mfma_f32_16x16x32_bf16 v[36:39], v[160:163], v[186:189], v[36:39]
	v_mfma_f32_16x16x32_bf16 v[32:35], v[168:171], v[186:189], v[32:35]
	v_mfma_f32_16x16x32_bf16 v[16:19], v[160:163], v[198:201], v[16:19]
	v_mfma_f32_16x16x32_bf16 v[8:11], v[168:171], v[198:201], v[8:11]
	v_mfma_f32_16x16x32_bf16 v[4:7], v[160:163], v[206:209], v[4:7]
	v_mfma_f32_16x16x32_bf16 v[0:3], v[168:171], v[206:209], v[0:3]
	v_mfma_f32_16x16x32_bf16 v[48:51], v[164:167], v[182:185], v[48:51]
	v_mfma_f32_16x16x32_bf16 v[40:43], v[172:175], v[182:185], v[40:43]
	v_mfma_f32_16x16x32_bf16 v[36:39], v[164:167], v[194:197], v[36:39]
	v_mfma_f32_16x16x32_bf16 v[32:35], v[172:175], v[194:197], v[32:35]
	v_mfma_f32_16x16x32_bf16 v[16:19], v[164:167], v[202:205], v[16:19]
	v_mfma_f32_16x16x32_bf16 v[8:11], v[172:175], v[202:205], v[8:11]
	v_mfma_f32_16x16x32_bf16 v[4:7], v[164:167], v[210:213], v[4:7]
	v_mfma_f32_16x16x32_bf16 v[0:3], v[172:175], v[210:213], v[0:3]
	s_setprio 0
	s_barrier
; #define PG8_STAGE(bufoff, gbase, voff) do { _Pragma("unroll") for (int _i = 0; _i < 2; ++_i) \
;         __builtin_amdgcn_global_load_lds((const unsigned*)((const char*)(gbase) + (voff)[_i]), (LAS unsigned*)(lds + (bufoff) + ldsw + _i * 8192), 16, 0, 0); } while (0)
; #define PG8_LDA(dst, b, h) do { _Pragma("unroll") for (int m = 0; m < 4; ++m) _Pragma("unroll") for (int k = 0; k < 2; ++k) dst[m][k] = *(const LAS bf16x8*)(lds + PG8_SA(b, h) + aoff + m * 2048 + k * 1024); } while (0)
; #define PG8_LDB(dst, b, h) do { _Pragma("unroll") for (int n = 0; n < 2; ++n) _Pragma("unroll") for (int k = 0; k < 2; ++k) dst[n][k] = *(const LAS bf16x8*)(lds + PG8_SB(b, h) + boff + n * 2048 + k * 1024); } while (0)
; #define PG8_MMA(ai, bj, At, Bt) do { __builtin_amdgcn_s_setprio(1); _Pragma("unroll") for (int m = 0; m < 4; ++m) _Pragma("unroll") for (int n = 0; n < 2; ++n) _Pragma("unroll") for (int k = 0; k < 2; ++k) \
;         acc[ai][bj][m][n] = __builtin_amdgcn_mfma_f32_16x16x32_bf16(Bt[n][k], At[m][k], acc[ai][bj][m][n], 0, 0, 0); __builtin_amdgcn_s_setprio(0); } while (0)
; #define PG8_WAIT_V(n) asm volatile("s_waitcnt vmcnt(" #n ")" ::: "memory")
; #define PG8_WAIT_L(n) asm volatile("s_waitcnt lgkmcnt(" #n ")" ::: "memory")
; #define PG8_BAR __builtin_amdgcn_s_barrier()
; #define PG8_SCHED __builtin_amdgcn_sched_barrier(0)
; template <class Epi>
; __device__ __forceinline__ void gemm_phase(LAS unsigned char* lds, const Gemm g, const Sched& S, const Epi& E, const int tid) {
;     ...
;             PG8_LDB(B0, 1, 0); PG8_LDB(B1, 1, 1); PG8_SCHED; PG8_LDA(At, 1, 0); PG8_STAGE(PG8_SA(0, 1), a2 + hA, voffA);
;             PG8_WAIT_V(8); PG8_WAIT_L(0); PG8_BAR; PG8_MMA(0, 0, At, B0); PG8_MMA(0, 1, At, B1); PG8_BAR; PG8_SCHED;
	s_add_i32 s35, 0, 0x18000
	s_add_i32 s37, 0, 0x1c000
	v_add_u32_e32 v156, s35, v145
	v_add_u32_e32 v172, s37, v145
	ds_read_b128 v[140:143], v156
	ds_read_b128 v[148:151], v156 offset:1024
	ds_read_b128 v[152:155], v156 offset:2048
	ds_read_b128 v[156:159], v156 offset:3072
	ds_read_b128 v[160:163], v172
	ds_read_b128 v[164:167], v172 offset:1024
	ds_read_b128 v[168:171], v172 offset:2048
	ds_read_b128 v[172:175], v172 offset:3072
	s_add_u32 s76, s76, 0x40000
	s_addc_u32 s77, s77, 0
	s_mov_b32 m0, s45
	v_lshl_add_u64 v[224:225], s[76:77], 0, v[128:129]
	ds_read_b128 v[178:181], v147 offset:32768
	ds_read_b128 v[182:185], v147 offset:33792
	ds_read_b128 v[186:189], v147 offset:34816
	ds_read_b128 v[194:197], v147 offset:35840
	ds_read_b128 v[198:201], v147 offset:36864
	ds_read_b128 v[202:205], v147 offset:37888
	ds_read_b128 v[206:209], v147 offset:38912
	ds_read_b128 v[210:213], v147 offset:39936
	global_load_lds_dwordx4 v[224:225], off
	v_lshl_add_u64 v[224:225], s[76:77], 0, v[130:131]
	s_mov_b32 m0, s47
	s_nop 0
	global_load_lds_dwordx4 v[224:225], off
	s_waitcnt vmcnt(8)
	s_waitcnt lgkmcnt(0)
	s_barrier
	s_setprio 1
	s_waitcnt lgkmcnt(0)
	v_mfma_f32_16x16x32_bf16 v[124:127], v[140:143], v[178:181], v[124:127]
	v_mfma_f32_16x16x32_bf16 v[120:123], v[152:155], v[178:181], v[120:123]
	v_mfma_f32_16x16x32_bf16 v[116:119], v[140:143], v[186:189], v[116:119]
	v_mfma_f32_16x16x32_bf16 v[108:111], v[152:155], v[186:189], v[108:111]
	v_mfma_f32_16x16x32_bf16 v[92:95], v[140:143], v[198:201], v[92:95]
	v_mfma_f32_16x16x32_bf16 v[88:91], v[152:155], v[198:201], v[88:91]
	v_mfma_f32_16x16x32_bf16 v[84:87], v[140:143], v[206:209], v[84:87]
	v_mfma_f32_16x16x32_bf16 v[76:79], v[152:155], v[206:209], v[76:79]
	v_mfma_f32_16x16x32_bf16 v[124:127], v[148:151], v[182:185], v[124:127]
	v_mfma_f32_16x16x32_bf16 v[120:123], v[156:159], v[182:185], v[120:123]
	v_mfma_f32_16x16x32_bf16 v[116:119], v[148:151], v[194:197], v[116:119]
	v_mfma_f32_16x16x32_bf16 v[108:111], v[156:159], v[194:197], v[108:111]
	v_mfma_f32_16x16x32_bf16 v[92:95], v[148:151], v[202:205], v[92:95]
	v_mfma_f32_16x16x32_bf16 v[88:91], v[156:159], v[202:205], v[88:91]
	v_mfma_f32_16x16x32_bf16 v[84:87], v[148:151], v[210:213], v[84:87]
	v_mfma_f32_16x16x32_bf16 v[76:79], v[156:159], v[210:213], v[76:79]
	v_mfma_f32_16x16x32_bf16 v[112:115], v[160:163], v[178:181], v[112:115]
	v_mfma_f32_16x16x32_bf16 v[104:107], v[168:171], v[178:181], v[104:107]
	v_mfma_f32_16x16x32_bf16 v[100:103], v[160:163], v[186:189], v[100:103]
	v_mfma_f32_16x16x32_bf16 v[96:99], v[168:171], v[186:189], v[96:99]
	v_mfma_f32_16x16x32_bf16 v[80:83], v[160:163], v[198:201], v[80:83]
	v_mfma_f32_16x16x32_bf16 v[72:75], v[168:171], v[198:201], v[72:75]
	v_mfma_f32_16x16x32_bf16 v[68:71], v[160:163], v[206:209], v[68:71]
	v_mfma_f32_16x16x32_bf16 v[64:67], v[168:171], v[206:209], v[64:67]
	v_mfma_f32_16x16x32_bf16 v[112:115], v[164:167], v[182:185], v[112:115]
	v_mfma_f32_16x16x32_bf16 v[104:107], v[172:175], v[182:185], v[104:107]
	v_mfma_f32_16x16x32_bf16 v[100:103], v[164:167], v[194:197], v[100:103]
	v_mfma_f32_16x16x32_bf16 v[96:99], v[172:175], v[194:197], v[96:99]
	v_mfma_f32_16x16x32_bf16 v[80:83], v[164:167], v[202:205], v[80:83]
	v_mfma_f32_16x16x32_bf16 v[72:75], v[172:175], v[202:205], v[72:75]
	v_mfma_f32_16x16x32_bf16 v[68:71], v[164:167], v[210:213], v[68:71]
	v_mfma_f32_16x16x32_bf16 v[64:67], v[172:175], v[210:213], v[64:67]
	s_setprio 0
	s_barrier
; #define PG8_STAGE(bufoff, gbase, voff) do { _Pragma("unroll") for (int _i = 0; _i < 2; ++_i) \
;         __builtin_amdgcn_global_load_lds((const unsigned*)((const char*)(gbase) + (voff)[_i]), (LAS unsigned*)(lds + (bufoff) + ldsw + _i * 8192), 16, 0, 0); } while (0)
; #define PG8_LDA(dst, b, h) do { _Pragma("unroll") for (int m = 0; m < 4; ++m) _Pragma("unroll") for (int k = 0; k < 2; ++k) dst[m][k] = *(const LAS bf16x8*)(lds + PG8_SA(b, h) + aoff + m * 2048 + k * 1024); } while (0)
; #define PG8_MMA(ai, bj, At, Bt) do { __builtin_amdgcn_s_setprio(1); _Pragma("unroll") for (int m = 0; m < 4; ++m) _Pragma("unroll") for (int n = 0; n < 2; ++n) _Pragma("unroll") for (int k = 0; k < 2; ++k) \
;         acc[ai][bj][m][n] = __builtin_amdgcn_mfma_f32_16x16x32_bf16(Bt[n][k], At[m][k], acc[ai][bj][m][n], 0, 0, 0); __builtin_amdgcn_s_setprio(0); } while (0)
; #define PG8_WAIT_V(n) asm volatile("s_waitcnt vmcnt(" #n ")" ::: "memory")
; #define PG8_WAIT_L(n) asm volatile("s_waitcnt lgkmcnt(" #n ")" ::: "memory")
; #define PG8_BAR __builtin_amdgcn_s_barrier()
; #define PG8_SCHED __builtin_amdgcn_sched_barrier(0)
; template <class Epi>
; __device__ __forceinline__ void gemm_phase(LAS unsigned char* lds, const Gemm g, const Sched& S, const Epi& E, const int tid) {
;     ...
;             PG8_LDA(At, 1, 1); PG8_STAGE(PG8_SB(1, 0), b3, voffB); PG8_STAGE(PG8_SB(1, 1), b3 + hB, voffB); PG8_STAGE(PG8_SA(1, 0), a3, voffA);
;             PG8_WAIT_V(8); PG8_WAIT_L(0); PG8_BAR; PG8_MMA(1, 0, At, B0); PG8_MMA(1, 1, At, B1); PG8_BAR; PG8_SCHED;
	s_add_i32 s35, s35, s39
	v_lshl_add_u64 v[190:191], v[190:191], 0, s[94:95]
	s_mov_b32 m0, s35
	ds_read_b128 v[178:181], v147 offset:49152
	ds_read_b128 v[182:185], v147 offset:50176
	ds_read_b128 v[186:189], v147 offset:51200
	ds_read_b128 v[194:197], v147 offset:52224
	ds_read_b128 v[198:201], v147 offset:53248
	ds_read_b128 v[202:205], v147 offset:54272
	ds_read_b128 v[206:209], v147 offset:55296
	ds_read_b128 v[210:213], v147 offset:56320
	global_load_lds_dwordx4 v[190:191], off
	s_add_i32 m0, s35, 0x2000
	s_add_u32 s74, s74, 0x40080
	v_lshl_add_u64 v[190:191], v[214:215], 0, s[94:95]
	s_addc_u32 s75, s75, 0
	s_add_i32 s35, s37, s39
	global_load_lds_dwordx4 v[190:191], off
	v_lshl_add_u64 v[190:191], s[74:75], 0, v[192:193]
	s_mov_b32 m0, s35
	s_nop 0
	global_load_lds_dwordx4 v[190:191], off
	v_lshl_add_u64 v[190:191], s[74:75], 0, v[132:133]
	s_add_i32 m0, s35, 0x2000
	s_nop 0
	global_load_lds_dwordx4 v[190:191], off
	v_lshl_add_u64 v[190:191], v[216:217], 0, s[94:95]
	s_mov_b32 m0, s78
	s_nop 0
	global_load_lds_dwordx4 v[190:191], off
	v_lshl_add_u64 v[190:191], v[218:219], 0, s[94:95]
	s_mov_b32 m0, s80
	s_nop 0
	global_load_lds_dwordx4 v[190:191], off
	s_waitcnt vmcnt(8)
	s_waitcnt lgkmcnt(0)
	s_barrier
	s_setprio 1
	s_waitcnt lgkmcnt(0)
	v_mfma_f32_16x16x32_bf16 v[60:63], v[140:143], v[178:181], v[60:63]
	v_mfma_f32_16x16x32_bf16 v[56:59], v[152:155], v[178:181], v[56:59]
	v_mfma_f32_16x16x32_bf16 v[52:55], v[140:143], v[186:189], v[52:55]
	v_mfma_f32_16x16x32_bf16 v[44:47], v[152:155], v[186:189], v[44:47]
	v_mfma_f32_16x16x32_bf16 v[28:31], v[140:143], v[198:201], v[28:31]
	v_mfma_f32_16x16x32_bf16 v[24:27], v[152:155], v[198:201], v[24:27]
	v_mfma_f32_16x16x32_bf16 v[20:23], v[140:143], v[206:209], v[20:23]
	v_mfma_f32_16x16x32_bf16 v[12:15], v[152:155], v[206:209], v[12:15]
	v_mfma_f32_16x16x32_bf16 v[60:63], v[148:151], v[182:185], v[60:63]
	v_mfma_f32_16x16x32_bf16 v[56:59], v[156:159], v[182:185], v[56:59]
	v_mfma_f32_16x16x32_bf16 v[52:55], v[148:151], v[194:197], v[52:55]
	v_mfma_f32_16x16x32_bf16 v[44:47], v[156:159], v[194:197], v[44:47]
	v_mfma_f32_16x16x32_bf16 v[28:31], v[148:151], v[202:205], v[28:31]
	v_mfma_f32_16x16x32_bf16 v[24:27], v[156:159], v[202:205], v[24:27]
	v_mfma_f32_16x16x32_bf16 v[20:23], v[148:151], v[210:213], v[20:23]
	v_mfma_f32_16x16x32_bf16 v[12:15], v[156:159], v[210:213], v[12:15]
	v_mfma_f32_16x16x32_bf16 v[48:51], v[160:163], v[178:181], v[48:51]
	v_mfma_f32_16x16x32_bf16 v[40:43], v[168:171], v[178:181], v[40:43]
	v_mfma_f32_16x16x32_bf16 v[36:39], v[160:163], v[186:189], v[36:39]
	v_mfma_f32_16x16x32_bf16 v[32:35], v[168:171], v[186:189], v[32:35]
	v_mfma_f32_16x16x32_bf16 v[16:19], v[160:163], v[198:201], v[16:19]
	v_mfma_f32_16x16x32_bf16 v[8:11], v[168:171], v[198:201], v[8:11]
	v_mfma_f32_16x16x32_bf16 v[4:7], v[160:163], v[206:209], v[4:7]
	v_mfma_f32_16x16x32_bf16 v[0:3], v[168:171], v[206:209], v[0:3]
	v_mfma_f32_16x16x32_bf16 v[48:51], v[164:167], v[182:185], v[48:51]
	v_mfma_f32_16x16x32_bf16 v[40:43], v[172:175], v[182:185], v[40:43]
	v_mfma_f32_16x16x32_bf16 v[36:39], v[164:167], v[194:197], v[36:39]
	v_mfma_f32_16x16x32_bf16 v[32:35], v[172:175], v[194:197], v[32:35]
	v_mfma_f32_16x16x32_bf16 v[16:19], v[164:167], v[202:205], v[16:19]
	v_mfma_f32_16x16x32_bf16 v[8:11], v[172:175], v[202:205], v[8:11]
	v_mfma_f32_16x16x32_bf16 v[4:7], v[164:167], v[210:213], v[4:7]
	v_mfma_f32_16x16x32_bf16 v[0:3], v[172:175], v[210:213], v[0:3]
	s_add_i32 s21, s21, 2
	s_add_u32 s10, s10, 0x100
	s_addc_u32 s11, s11, 0
	s_add_u32 s9, s9, 0x100
	s_addc_u32 s19, s19, 0
	s_cmp_gt_u32 s21, 13
	s_setprio 0
	s_barrier
	s_cbranch_scc0 .LBB0_333

; #define PG8_STAGE(bufoff, gbase, voff) do { _Pragma("unroll") for (int _i = 0; _i < 2; ++_i) \
;         __builtin_amdgcn_global_load_lds((const unsigned*)((const char*)(gbase) + (voff)[_i]), (LAS unsigned*)(lds + (bufoff) + ldsw + _i * 8192), 16, 0, 0); } while (0)
; #define PG8_LDA(dst, b, h) do { _Pragma("unroll") for (int m = 0; m < 4; ++m) _Pragma("unroll") for (int k = 0; k < 2; ++k) dst[m][k] = *(const LAS bf16x8*)(lds + PG8_SA(b, h) + aoff + m * 2048 + k * 1024); } while (0)
; #define PG8_LDB(dst, b, h) do { _Pragma("unroll") for (int n = 0; n < 2; ++n) _Pragma("unroll") for (int k = 0; k < 2; ++k) dst[n][k] = *(const LAS bf16x8*)(lds + PG8_SB(b, h) + boff + n * 2048 + k * 1024); } while (0)
; #define PG8_MMA(ai, bj, At, Bt) do { __builtin_amdgcn_s_setprio(1); _Pragma("unroll") for (int m = 0; m < 4; ++m) _Pragma("unroll") for (int n = 0; n < 2; ++n) _Pragma("unroll") for (int k = 0; k < 2; ++k) \
;         acc[ai][bj][m][n] = __builtin_amdgcn_mfma_f32_16x16x32_bf16(Bt[n][k], At[m][k], acc[ai][bj][m][n], 0, 0, 0); __builtin_amdgcn_s_setprio(0); } while (0)
; #define PG8_WAIT_V(n) asm volatile("s_waitcnt vmcnt(" #n ")" ::: "memory")
; #define PG8_WAIT_L(n) asm volatile("s_waitcnt lgkmcnt(" #n ")" ::: "memory")
; #define PG8_BAR __builtin_amdgcn_s_barrier()
; #define PG8_SCHED __builtin_amdgcn_sched_barrier(0)
; template <class Epi>
; __device__ __forceinline__ void gemm_phase(LAS unsigned char* lds, const Gemm g, const Sched& S, const Epi& E, const int tid) {
;     ...
;         const char* nA = cA; const char* nB = cB; if (has_next) S.ptrs(nxt, nA, nB);
;         for (int t = 0; t < nt; t += 2) {
;             const bool last = (t == nt - 2);
;             const char* a1 = cA + (size_t)(t + 1) * kstep;
;             const char* a2 = last ? nA : cA + (size_t)(t + 2) * kstep; const char* b2 = last ? nB : cB + (size_t)(t + 2) * kstep;
;             const char* a3 = a2 + kstep; const char* b3 = b2 + kstep;
;             PG8_LDB(B0, 0, 0); PG8_LDB(B1, 0, 1); PG8_SCHED; PG8_LDA(At, 0, 0); PG8_STAGE(PG8_SA(1, 1), a1 + hA, voffA);
;             PG8_WAIT_V(8); PG8_WAIT_L(0); PG8_BAR; PG8_MMA(0, 0, At, B0); PG8_MMA(0, 1, At, B1); PG8_BAR; PG8_SCHED;
;             PG8_LDA(At, 0, 1); PG8_STAGE(PG8_SB(0, 0), b2, voffB); PG8_STAGE(PG8_SB(0, 1), b2 + hB, voffB); PG8_STAGE(PG8_SA(0, 0), a2, voffA);
.LBB0_993:
	s_add_u32 s13, s18, 0x100
	s_addc_u32 s40, s19, 0
	s_mov_b32 s42, -2
	s_add_u32 s18, s16, 0x100
	s_addc_u32 s19, s17, 0
	s_add_i32 s45, 0, 0x10000
	s_cmp_eq_u32 s42, 4
	s_cselect_b32 s23, s7, s19
	s_cselect_b32 s22, s6, s18
	s_cselect_b32 s21, s15, s40
	s_cselect_b32 s20, s14, s13
	s_add_i32 s51, 0, 0x14000
	v_add_u32_e32 v128, s45, v183
	v_add_u32_e32 v156, s51, v183
	ds_read_b128 v[104:107], v128
	ds_read_b128 v[112:115], v128 offset:1024
	ds_read_b128 v[124:127], v128 offset:2048
	ds_read_b128 v[128:131], v128 offset:3072
	ds_read_b128 v[136:139], v156
	ds_read_b128 v[144:147], v156 offset:1024
	ds_read_b128 v[152:155], v156 offset:2048
	ds_read_b128 v[156:159], v156 offset:3072
	v_lshl_add_u64 v[190:191], s[16:17], 0, v[166:167]
	s_add_i32 m0, s73, 0xc000
	ds_read_b128 v[170:173], v185
	ds_read_b128 v[174:177], v185 offset:1024
	ds_read_b128 v[178:181], v185 offset:2048
	ds_read_b128 v[186:189], v185 offset:3072
	ds_read_b128 v[194:197], v185 offset:4096
	ds_read_b128 v[198:201], v185 offset:5120
	ds_read_b128 v[204:207], v185 offset:6144
	ds_read_b128 v[208:211], v185 offset:7168
	global_load_lds_dwordx4 v[190:191], off
	v_lshl_add_u64 v[190:191], s[16:17], 0, v[168:169]
	s_add_i32 m0, s73, 0xe000
	s_nop 0
	global_load_lds_dwordx4 v[190:191], off
	s_waitcnt vmcnt(8)
	s_waitcnt lgkmcnt(0)
	s_barrier
	s_setprio 1
	s_waitcnt lgkmcnt(0)
	v_mfma_f32_16x16x32_bf16 v[148:151], v[104:107], v[170:173], 0
	v_mfma_f32_16x16x32_bf16 v[140:143], v[124:127], v[170:173], 0
	v_mfma_f32_16x16x32_bf16 v[116:119], v[104:107], v[178:181], 0
	v_mfma_f32_16x16x32_bf16 v[108:111], v[124:127], v[178:181], 0
	v_mfma_f32_16x16x32_bf16 v[92:95], v[104:107], v[194:197], 0
	v_mfma_f32_16x16x32_bf16 v[88:91], v[124:127], v[194:197], 0
	v_mfma_f32_16x16x32_bf16 v[76:79], v[104:107], v[204:207], 0
	v_mfma_f32_16x16x32_bf16 v[72:75], v[124:127], v[204:207], 0
	v_mfma_f32_16x16x32_bf16 v[148:151], v[112:115], v[174:177], v[148:151]
	v_mfma_f32_16x16x32_bf16 v[140:143], v[128:131], v[174:177], v[140:143]
	v_mfma_f32_16x16x32_bf16 v[116:119], v[112:115], v[186:189], v[116:119]
	v_mfma_f32_16x16x32_bf16 v[108:111], v[128:131], v[186:189], v[108:111]
	v_mfma_f32_16x16x32_bf16 v[92:95], v[112:115], v[198:201], v[92:95]
	v_mfma_f32_16x16x32_bf16 v[88:91], v[128:131], v[198:201], v[88:91]
	v_mfma_f32_16x16x32_bf16 v[76:79], v[112:115], v[208:211], v[76:79]
	v_mfma_f32_16x16x32_bf16 v[72:75], v[128:131], v[208:211], v[72:75]
	v_mfma_f32_16x16x32_bf16 v[132:135], v[136:139], v[170:173], 0
	v_mfma_f32_16x16x32_bf16 v[120:123], v[152:155], v[170:173], 0
	v_mfma_f32_16x16x32_bf16 v[100:103], v[136:139], v[178:181], 0
	v_mfma_f32_16x16x32_bf16 v[96:99], v[152:155], v[178:181], 0
	v_mfma_f32_16x16x32_bf16 v[84:87], v[136:139], v[194:197], 0
	v_mfma_f32_16x16x32_bf16 v[80:83], v[152:155], v[194:197], 0
	v_mfma_f32_16x16x32_bf16 v[68:71], v[136:139], v[204:207], 0
	v_mfma_f32_16x16x32_bf16 v[64:67], v[152:155], v[204:207], 0
	v_mfma_f32_16x16x32_bf16 v[132:135], v[144:147], v[174:177], v[132:135]
	v_mfma_f32_16x16x32_bf16 v[120:123], v[156:159], v[174:177], v[120:123]
	v_mfma_f32_16x16x32_bf16 v[100:103], v[144:147], v[186:189], v[100:103]
	v_mfma_f32_16x16x32_bf16 v[96:99], v[156:159], v[186:189], v[96:99]
	v_mfma_f32_16x16x32_bf16 v[84:87], v[144:147], v[198:201], v[84:87]
	v_mfma_f32_16x16x32_bf16 v[80:83], v[156:159], v[198:201], v[80:83]
	v_mfma_f32_16x16x32_bf16 v[68:71], v[144:147], v[208:211], v[68:71]
	v_mfma_f32_16x16x32_bf16 v[64:67], v[156:159], v[208:211], v[64:67]
	s_setprio 0
	s_barrier
	s_add_i32 s16, s45, s47
	v_lshl_add_u64 v[190:191], s[20:21], 0, v[192:193]
	s_mov_b32 m0, s16
	ds_read_b128 v[170:173], v185 offset:16384
	ds_read_b128 v[174:177], v185 offset:17408
	ds_read_b128 v[178:181], v185 offset:18432
	ds_read_b128 v[186:189], v185 offset:19456
	ds_read_b128 v[194:197], v185 offset:20480
	ds_read_b128 v[198:201], v185 offset:21504
	ds_read_b128 v[204:207], v185 offset:22528
	ds_read_b128 v[208:211], v185 offset:23552
	global_load_lds_dwordx4 v[190:191], off
	s_add_i32 m0, s16, 0x2000
	s_add_u32 s16, s20, 0x20000
	v_lshl_add_u64 v[212:213], s[20:21], 0, v[164:165]
	s_addc_u32 s17, s21, 0
	s_add_i32 s45, s51, s47
	global_load_lds_dwordx4 v[212:213], off
	v_lshl_add_u64 v[214:215], s[16:17], 0, v[192:193]
	s_mov_b32 m0, s45
	v_lshl_add_u64 v[216:217], s[22:23], 0, v[162:163]
	global_load_lds_dwordx4 v[214:215], off
	v_lshl_add_u64 v[214:215], s[16:17], 0, v[164:165]
	s_add_i32 m0, s45, 0x2000
	s_nop 0
	global_load_lds_dwordx4 v[214:215], off
	v_lshl_add_u64 v[214:215], s[22:23], 0, v[160:161]
	s_mov_b32 m0, s73
	s_nop 0
	global_load_lds_dwordx4 v[214:215], off
	s_mov_b32 m0, s74
	s_nop 0
	global_load_lds_dwordx4 v[216:217], off
	s_waitcnt vmcnt(8)
	s_waitcnt lgkmcnt(0)
	s_barrier
; #define PG8_STAGE(bufoff, gbase, voff) do { _Pragma("unroll") for (int _i = 0; _i < 2; ++_i) \
;         __builtin_amdgcn_global_load_lds((const unsigned*)((const char*)(gbase) + (voff)[_i]), (LAS unsigned*)(lds + (bufoff) + ldsw + _i * 8192), 16, 0, 0); } while (0)
; #define PG8_LDA(dst, b, h) do { _Pragma("unroll") for (int m = 0; m < 4; ++m) _Pragma("unroll") for (int k = 0; k < 2; ++k) dst[m][k] = *(const LAS bf16x8*)(lds + PG8_SA(b, h) + aoff + m * 2048 + k * 1024); } while (0)
; #define PG8_LDB(dst, b, h) do { _Pragma("unroll") for (int n = 0; n < 2; ++n) _Pragma("unroll") for (int k = 0; k < 2; ++k) dst[n][k] = *(const LAS bf16x8*)(lds + PG8_SB(b, h) + boff + n * 2048 + k * 1024); } while (0)
; #define PG8_MMA(ai, bj, At, Bt) do { __builtin_amdgcn_s_setprio(1); _Pragma("unroll") for (int m = 0; m < 4; ++m) _Pragma("unroll") for (int n = 0; n < 2; ++n) _Pragma("unroll") for (int k = 0; k < 2; ++k) \
;         acc[ai][bj][m][n] = __builtin_amdgcn_mfma_f32_16x16x32_bf16(Bt[n][k], At[m][k], acc[ai][bj][m][n], 0, 0, 0); __builtin_amdgcn_s_setprio(0); } while (0)
; #define PG8_WAIT_V(n) asm volatile("s_waitcnt vmcnt(" #n ")" ::: "memory")
; #define PG8_WAIT_L(n) asm volatile("s_waitcnt lgkmcnt(" #n ")" ::: "memory")
; #define PG8_BAR __builtin_amdgcn_s_barrier()
; #define PG8_SCHED __builtin_amdgcn_sched_barrier(0)
; template <class Epi>
; __device__ __forceinline__ void gemm_phase(LAS unsigned char* lds, const Gemm g, const Sched& S, const Epi& E, const int tid) {
;     ...
;             PG8_WAIT_V(8); PG8_WAIT_L(0); PG8_BAR; PG8_MMA(1, 0, At, B0); PG8_MMA(1, 1, At, B1); PG8_BAR; PG8_SCHED;
;             PG8_LDB(B0, 1, 0); PG8_LDB(B1, 1, 1); PG8_SCHED; PG8_LDA(At, 1, 0); PG8_STAGE(PG8_SA(0, 1), a2 + hA, voffA);
;             PG8_WAIT_V(8); PG8_WAIT_L(0); PG8_BAR; PG8_MMA(0, 0, At, B0); PG8_MMA(0, 1, At, B1); PG8_BAR; PG8_SCHED;
	s_setprio 1
	s_waitcnt lgkmcnt(0)
	v_mfma_f32_16x16x32_bf16 v[60:63], v[104:107], v[170:173], 0
	v_mfma_f32_16x16x32_bf16 v[56:59], v[124:127], v[170:173], 0
	v_mfma_f32_16x16x32_bf16 v[44:47], v[104:107], v[178:181], 0
	v_mfma_f32_16x16x32_bf16 v[40:43], v[124:127], v[178:181], 0
	v_mfma_f32_16x16x32_bf16 v[28:31], v[104:107], v[194:197], 0
	v_mfma_f32_16x16x32_bf16 v[24:27], v[124:127], v[194:197], 0
	v_mfma_f32_16x16x32_bf16 v[12:15], v[104:107], v[204:207], 0
	v_mfma_f32_16x16x32_bf16 v[8:11], v[124:127], v[204:207], 0
	v_mfma_f32_16x16x32_bf16 v[60:63], v[112:115], v[174:177], v[60:63]
	v_mfma_f32_16x16x32_bf16 v[56:59], v[128:131], v[174:177], v[56:59]
	v_mfma_f32_16x16x32_bf16 v[44:47], v[112:115], v[186:189], v[44:47]
	v_mfma_f32_16x16x32_bf16 v[40:43], v[128:131], v[186:189], v[40:43]
	v_mfma_f32_16x16x32_bf16 v[28:31], v[112:115], v[198:201], v[28:31]
	v_mfma_f32_16x16x32_bf16 v[24:27], v[128:131], v[198:201], v[24:27]
	v_mfma_f32_16x16x32_bf16 v[12:15], v[112:115], v[208:211], v[12:15]
	v_mfma_f32_16x16x32_bf16 v[8:11], v[128:131], v[208:211], v[8:11]
	v_mfma_f32_16x16x32_bf16 v[52:55], v[136:139], v[170:173], 0
	v_mfma_f32_16x16x32_bf16 v[48:51], v[152:155], v[170:173], 0
	v_mfma_f32_16x16x32_bf16 v[36:39], v[136:139], v[178:181], 0
	v_mfma_f32_16x16x32_bf16 v[32:35], v[152:155], v[178:181], 0
	v_mfma_f32_16x16x32_bf16 v[20:23], v[136:139], v[194:197], 0
	v_mfma_f32_16x16x32_bf16 v[16:19], v[152:155], v[194:197], 0
	v_mfma_f32_16x16x32_bf16 v[4:7], v[136:139], v[204:207], 0
	v_mfma_f32_16x16x32_bf16 v[0:3], v[152:155], v[204:207], 0
	v_mfma_f32_16x16x32_bf16 v[52:55], v[144:147], v[174:177], v[52:55]
	v_mfma_f32_16x16x32_bf16 v[48:51], v[156:159], v[174:177], v[48:51]
	v_mfma_f32_16x16x32_bf16 v[36:39], v[144:147], v[186:189], v[36:39]
	v_mfma_f32_16x16x32_bf16 v[32:35], v[156:159], v[186:189], v[32:35]
	v_mfma_f32_16x16x32_bf16 v[20:23], v[144:147], v[198:201], v[20:23]
	v_mfma_f32_16x16x32_bf16 v[16:19], v[156:159], v[198:201], v[16:19]
	v_mfma_f32_16x16x32_bf16 v[4:7], v[144:147], v[208:211], v[4:7]
	v_mfma_f32_16x16x32_bf16 v[0:3], v[156:159], v[208:211], v[0:3]
	s_setprio 0
	s_barrier
	s_add_i32 s45, 0, 0x18000
	s_add_i32 s51, 0, 0x1c000
	v_add_u32_e32 v128, s45, v183
	v_add_u32_e32 v156, s51, v183
	ds_read_b128 v[104:107], v128
	ds_read_b128 v[112:115], v128 offset:1024
	ds_read_b128 v[124:127], v128 offset:2048
	ds_read_b128 v[128:131], v128 offset:3072
	ds_read_b128 v[136:139], v156
	ds_read_b128 v[144:147], v156 offset:1024
	ds_read_b128 v[152:155], v156 offset:2048
	ds_read_b128 v[156:159], v156 offset:3072
	s_add_u32 s16, s22, 0x120000
	s_addc_u32 s17, s23, 0
	s_mov_b32 m0, s75
	v_lshl_add_u64 v[218:219], s[16:17], 0, v[160:161]
	ds_read_b128 v[170:173], v185 offset:32768
	ds_read_b128 v[174:177], v185 offset:33792
	ds_read_b128 v[178:181], v185 offset:34816
	ds_read_b128 v[186:189], v185 offset:35840
	ds_read_b128 v[194:197], v185 offset:36864
	ds_read_b128 v[198:201], v185 offset:37888
	ds_read_b128 v[204:207], v185 offset:38912
	ds_read_b128 v[208:211], v185 offset:39936
	global_load_lds_dwordx4 v[218:219], off
	v_lshl_add_u64 v[218:219], s[16:17], 0, v[162:163]
	s_mov_b32 m0, s76
	s_nop 0
	global_load_lds_dwordx4 v[218:219], off
	s_waitcnt vmcnt(8)
	s_waitcnt lgkmcnt(0)
	s_barrier
	s_setprio 1
	s_waitcnt lgkmcnt(0)
	v_mfma_f32_16x16x32_bf16 v[148:151], v[104:107], v[170:173], v[148:151]
	v_mfma_f32_16x16x32_bf16 v[140:143], v[124:127], v[170:173], v[140:143]
	v_mfma_f32_16x16x32_bf16 v[116:119], v[104:107], v[178:181], v[116:119]
	v_mfma_f32_16x16x32_bf16 v[108:111], v[124:127], v[178:181], v[108:111]
	v_mfma_f32_16x16x32_bf16 v[92:95], v[104:107], v[194:197], v[92:95]
	v_mfma_f32_16x16x32_bf16 v[88:91], v[124:127], v[194:197], v[88:91]
	v_mfma_f32_16x16x32_bf16 v[76:79], v[104:107], v[204:207], v[76:79]
	v_mfma_f32_16x16x32_bf16 v[72:75], v[124:127], v[204:207], v[72:75]
	v_mfma_f32_16x16x32_bf16 v[148:151], v[112:115], v[174:177], v[148:151]
	v_mfma_f32_16x16x32_bf16 v[140:143], v[128:131], v[174:177], v[140:143]
	v_mfma_f32_16x16x32_bf16 v[116:119], v[112:115], v[186:189], v[116:119]
	v_mfma_f32_16x16x32_bf16 v[108:111], v[128:131], v[186:189], v[108:111]
	v_mfma_f32_16x16x32_bf16 v[92:95], v[112:115], v[198:201], v[92:95]
	v_mfma_f32_16x16x32_bf16 v[88:91], v[128:131], v[198:201], v[88:91]
	v_mfma_f32_16x16x32_bf16 v[76:79], v[112:115], v[208:211], v[76:79]
	v_mfma_f32_16x16x32_bf16 v[72:75], v[128:131], v[208:211], v[72:75]
	v_mfma_f32_16x16x32_bf16 v[132:135], v[136:139], v[170:173], v[132:135]
	v_mfma_f32_16x16x32_bf16 v[120:123], v[152:155], v[170:173], v[120:123]
	v_mfma_f32_16x16x32_bf16 v[100:103], v[136:139], v[178:181], v[100:103]
	v_mfma_f32_16x16x32_bf16 v[96:99], v[152:155], v[178:181], v[96:99]
	v_mfma_f32_16x16x32_bf16 v[84:87], v[136:139], v[194:197], v[84:87]
	v_mfma_f32_16x16x32_bf16 v[80:83], v[152:155], v[194:197], v[80:83]
	v_mfma_f32_16x16x32_bf16 v[68:71], v[136:139], v[204:207], v[68:71]
	v_mfma_f32_16x16x32_bf16 v[64:67], v[152:155], v[204:207], v[64:67]
	v_mfma_f32_16x16x32_bf16 v[132:135], v[144:147], v[174:177], v[132:135]
	v_mfma_f32_16x16x32_bf16 v[120:123], v[156:159], v[174:177], v[120:123]
	v_mfma_f32_16x16x32_bf16 v[100:103], v[144:147], v[186:189], v[100:103]
	v_mfma_f32_16x16x32_bf16 v[96:99], v[156:159], v[186:189], v[96:99]
	v_mfma_f32_16x16x32_bf16 v[84:87], v[144:147], v[198:201], v[84:87]
	v_mfma_f32_16x16x32_bf16 v[80:83], v[156:159], v[198:201], v[80:83]
	v_mfma_f32_16x16x32_bf16 v[68:71], v[144:147], v[208:211], v[68:71]
	v_mfma_f32_16x16x32_bf16 v[64:67], v[156:159], v[208:211], v[64:67]
	s_setprio 0
	s_barrier
; #define PG8_STAGE(bufoff, gbase, voff) do { _Pragma("unroll") for (int _i = 0; _i < 2; ++_i) \
;         __builtin_amdgcn_global_load_lds((const unsigned*)((const char*)(gbase) + (voff)[_i]), (LAS unsigned*)(lds + (bufoff) + ldsw + _i * 8192), 16, 0, 0); } while (0)
; #define PG8_LDA(dst, b, h) do { _Pragma("unroll") for (int m = 0; m < 4; ++m) _Pragma("unroll") for (int k = 0; k < 2; ++k) dst[m][k] = *(const LAS bf16x8*)(lds + PG8_SA(b, h) + aoff + m * 2048 + k * 1024); } while (0)
; #define PG8_LDB(dst, b, h) do { _Pragma("unroll") for (int n = 0; n < 2; ++n) _Pragma("unroll") for (int k = 0; k < 2; ++k) dst[n][k] = *(const LAS bf16x8*)(lds + PG8_SB(b, h) + boff + n * 2048 + k * 1024); } while (0)
; #define PG8_WAIT_V(n) asm volatile("s_waitcnt vmcnt(" #n ")" ::: "memory")
; #define PG8_WAIT_L(n) asm volatile("s_waitcnt lgkmcnt(" #n ")" ::: "memory")
; template <class Epi>
; __device__ __forceinline__ void gemm_phase(LAS unsigned char* lds, const Gemm g, const Sched& S, const Epi& E, const int tid) {
;     ...
;         for (int t = 0; t < nt; t += 2) {
;             const bool last = (t == nt - 2);
;             const char* a1 = cA + (size_t)(t + 1) * kstep;
;             const char* a2 = last ? nA : cA + (size_t)(t + 2) * kstep; const char* b2 = last ? nB : cB + (size_t)(t + 2) * kstep;
;             const char* a3 = a2 + kstep; const char* b3 = b2 + kstep;
;             PG8_LDB(B0, 0, 0); PG8_LDB(B1, 0, 1); PG8_SCHED; PG8_LDA(At, 0, 0); PG8_STAGE(PG8_SA(1, 1), a1 + hA, voffA);
;             PG8_WAIT_V(8); PG8_WAIT_L(0); PG8_BAR; PG8_MMA(0, 0, At, B0); PG8_MMA(0, 1, At, B1); PG8_BAR; PG8_SCHED;
;             PG8_LDA(At, 0, 1); PG8_STAGE(PG8_SB(0, 0), b2, voffB); PG8_STAGE(PG8_SB(0, 1), b2 + hB, voffB); PG8_STAGE(PG8_SA(0, 0), a2, voffA);
;             PG8_WAIT_V(8); PG8_WAIT_L(0); PG8_BAR; PG8_MMA(1, 0, At, B0); PG8_MMA(1, 1, At, B1); PG8_BAR; PG8_SCHED;
;             PG8_LDB(B0, 1, 0); PG8_LDB(B1, 1, 1); PG8_SCHED; PG8_LDA(At, 1, 0); PG8_STAGE(PG8_SA(0, 1), a2 + hA, voffA);
;             PG8_WAIT_V(8); PG8_WAIT_L(0); PG8_BAR; PG8_MMA(0, 0, At, B0); PG8_MMA(0, 1, At, B1); PG8_BAR; PG8_SCHED;
;             PG8_LDA(At, 1, 1); PG8_STAGE(PG8_SB(1, 0), b3, voffB); PG8_STAGE(PG8_SB(1, 1), b3 + hB, voffB); PG8_STAGE(PG8_SA(1, 0), a3, voffA);
;             PG8_WAIT_V(8); PG8_WAIT_L(0); PG8_BAR; PG8_MMA(1, 0, At, B0); PG8_MMA(1, 1, At, B1); PG8_BAR; PG8_SCHED;
	s_add_i32 s16, s45, s47
	v_lshl_add_u64 v[190:191], v[190:191], 0, s[94:95]
	s_mov_b32 m0, s16
	ds_read_b128 v[170:173], v185 offset:49152
	ds_read_b128 v[174:177], v185 offset:50176
	ds_read_b128 v[178:181], v185 offset:51200
	ds_read_b128 v[186:189], v185 offset:52224
	ds_read_b128 v[194:197], v185 offset:53248
	ds_read_b128 v[198:201], v185 offset:54272
	ds_read_b128 v[204:207], v185 offset:55296
	ds_read_b128 v[208:211], v185 offset:56320
	global_load_lds_dwordx4 v[190:191], off
	s_add_i32 m0, s16, 0x2000
	s_add_u32 s16, s20, 0x20080
	v_lshl_add_u64 v[190:191], v[212:213], 0, s[94:95]
	s_addc_u32 s17, s21, 0
	s_add_i32 s20, s51, s47
	global_load_lds_dwordx4 v[190:191], off
	v_lshl_add_u64 v[190:191], s[16:17], 0, v[192:193]
	s_mov_b32 m0, s20
	s_nop 0
	global_load_lds_dwordx4 v[190:191], off
	v_lshl_add_u64 v[190:191], s[16:17], 0, v[164:165]
	s_add_i32 m0, s20, 0x2000
	s_nop 0
	global_load_lds_dwordx4 v[190:191], off
	v_lshl_add_u64 v[190:191], v[214:215], 0, s[94:95]
	s_mov_b32 m0, s77
	s_nop 0
	global_load_lds_dwordx4 v[190:191], off
	v_lshl_add_u64 v[190:191], v[216:217], 0, s[94:95]
	s_mov_b32 m0, s78
	s_nop 0
	global_load_lds_dwordx4 v[190:191], off
	s_waitcnt vmcnt(8)
	s_waitcnt lgkmcnt(0)
	s_barrier
	s_setprio 1
	s_waitcnt lgkmcnt(0)
	v_mfma_f32_16x16x32_bf16 v[60:63], v[104:107], v[170:173], v[60:63]
	v_mfma_f32_16x16x32_bf16 v[56:59], v[124:127], v[170:173], v[56:59]
	v_mfma_f32_16x16x32_bf16 v[44:47], v[104:107], v[178:181], v[44:47]
	v_mfma_f32_16x16x32_bf16 v[40:43], v[124:127], v[178:181], v[40:43]
	v_mfma_f32_16x16x32_bf16 v[28:31], v[104:107], v[194:197], v[28:31]
	v_mfma_f32_16x16x32_bf16 v[24:27], v[124:127], v[194:197], v[24:27]
	v_mfma_f32_16x16x32_bf16 v[12:15], v[104:107], v[204:207], v[12:15]
	v_mfma_f32_16x16x32_bf16 v[8:11], v[124:127], v[204:207], v[8:11]
	v_mfma_f32_16x16x32_bf16 v[60:63], v[112:115], v[174:177], v[60:63]
	v_mfma_f32_16x16x32_bf16 v[56:59], v[128:131], v[174:177], v[56:59]
	v_mfma_f32_16x16x32_bf16 v[44:47], v[112:115], v[186:189], v[44:47]
	v_mfma_f32_16x16x32_bf16 v[40:43], v[128:131], v[186:189], v[40:43]
	v_mfma_f32_16x16x32_bf16 v[28:31], v[112:115], v[198:201], v[28:31]
	v_mfma_f32_16x16x32_bf16 v[24:27], v[128:131], v[198:201], v[24:27]
	v_mfma_f32_16x16x32_bf16 v[12:15], v[112:115], v[208:211], v[12:15]
	v_mfma_f32_16x16x32_bf16 v[8:11], v[128:131], v[208:211], v[8:11]
	v_mfma_f32_16x16x32_bf16 v[52:55], v[136:139], v[170:173], v[52:55]
	v_mfma_f32_16x16x32_bf16 v[48:51], v[152:155], v[170:173], v[48:51]
	v_mfma_f32_16x16x32_bf16 v[36:39], v[136:139], v[178:181], v[36:39]
	v_mfma_f32_16x16x32_bf16 v[32:35], v[152:155], v[178:181], v[32:35]
	v_mfma_f32_16x16x32_bf16 v[20:23], v[136:139], v[194:197], v[20:23]
	v_mfma_f32_16x16x32_bf16 v[16:19], v[152:155], v[194:197], v[16:19]
	v_mfma_f32_16x16x32_bf16 v[4:7], v[136:139], v[204:207], v[4:7]
	v_mfma_f32_16x16x32_bf16 v[0:3], v[152:155], v[204:207], v[0:3]
	v_mfma_f32_16x16x32_bf16 v[52:55], v[144:147], v[174:177], v[52:55]
	v_mfma_f32_16x16x32_bf16 v[48:51], v[156:159], v[174:177], v[48:51]
	v_mfma_f32_16x16x32_bf16 v[36:39], v[144:147], v[186:189], v[36:39]
	v_mfma_f32_16x16x32_bf16 v[32:35], v[156:159], v[186:189], v[32:35]
	v_mfma_f32_16x16x32_bf16 v[20:23], v[144:147], v[198:201], v[20:23]
	v_mfma_f32_16x16x32_bf16 v[16:19], v[156:159], v[198:201], v[16:19]
	v_mfma_f32_16x16x32_bf16 v[4:7], v[144:147], v[208:211], v[4:7]
	v_mfma_f32_16x16x32_bf16 v[0:3], v[156:159], v[208:211], v[0:3]
	s_add_i32 s42, s42, 2
	s_add_u32 s13, s13, 0x100
	s_addc_u32 s40, s40, 0
	s_cmp_gt_u32 s42, 5
	s_mov_b64 s[16:17], s[18:19]
	s_setprio 0
	s_barrier
	s_cbranch_scc1 .Lgk_exit_1
.LBB0_994:
	s_add_u32 s18, s16, 0x100
	s_addc_u32 s19, s17, 0
	s_add_i32 s45, 0, 0x10000
	s_cmp_eq_u32 s42, 4
	s_cselect_b32 s23, s7, s19
	s_cselect_b32 s22, s6, s18
	s_cselect_b32 s21, s15, s40
	s_cselect_b32 s20, s14, s13
	s_add_i32 s51, 0, 0x14000
	v_add_u32_e32 v128, s45, v183
	v_add_u32_e32 v156, s51, v183
	ds_read_b128 v[104:107], v128
	ds_read_b128 v[112:115], v128 offset:1024
	ds_read_b128 v[124:127], v128 offset:2048
	ds_read_b128 v[128:131], v128 offset:3072
	ds_read_b128 v[136:139], v156
	ds_read_b128 v[144:147], v156 offset:1024
	ds_read_b128 v[152:155], v156 offset:2048
	ds_read_b128 v[156:159], v156 offset:3072
	v_lshl_add_u64 v[190:191], s[16:17], 0, v[166:167]
	s_add_i32 m0, s73, 0xc000
	ds_read_b128 v[170:173], v185
	ds_read_b128 v[174:177], v185 offset:1024
	ds_read_b128 v[178:181], v185 offset:2048
	ds_read_b128 v[186:189], v185 offset:3072
	ds_read_b128 v[194:197], v185 offset:4096
	ds_read_b128 v[198:201], v185 offset:5120
	ds_read_b128 v[204:207], v185 offset:6144
	ds_read_b128 v[208:211], v185 offset:7168
	global_load_lds_dwordx4 v[190:191], off
	v_lshl_add_u64 v[190:191], s[16:17], 0, v[168:169]
	s_add_i32 m0, s73, 0xe000
	s_nop 0
	global_load_lds_dwordx4 v[190:191], off
	s_waitcnt vmcnt(8)
	s_waitcnt lgkmcnt(0)
	s_barrier
; #define PG8_STAGE(bufoff, gbase, voff) do { _Pragma("unroll") for (int _i = 0; _i < 2; ++_i) \
;         __builtin_amdgcn_global_load_lds((const unsigned*)((const char*)(gbase) + (voff)[_i]), (LAS unsigned*)(lds + (bufoff) + ldsw + _i * 8192), 16, 0, 0); } while (0)
; #define PG8_LDA(dst, b, h) do { _Pragma("unroll") for (int m = 0; m < 4; ++m) _Pragma("unroll") for (int k = 0; k < 2; ++k) dst[m][k] = *(const LAS bf16x8*)(lds + PG8_SA(b, h) + aoff + m * 2048 + k * 1024); } while (0)
; #define PG8_LDB(dst, b, h) do { _Pragma("unroll") for (int n = 0; n < 2; ++n) _Pragma("unroll") for (int k = 0; k < 2; ++k) dst[n][k] = *(const LAS bf16x8*)(lds + PG8_SB(b, h) + boff + n * 2048 + k * 1024); } while (0)
; #define PG8_MMA(ai, bj, At, Bt) do { __builtin_amdgcn_s_setprio(1); _Pragma("unroll") for (int m = 0; m < 4; ++m) _Pragma("unroll") for (int n = 0; n < 2; ++n) _Pragma("unroll") for (int k = 0; k < 2; ++k) \
;         acc[ai][bj][m][n] = __builtin_amdgcn_mfma_f32_16x16x32_bf16(Bt[n][k], At[m][k], acc[ai][bj][m][n], 0, 0, 0); __builtin_amdgcn_s_setprio(0); } while (0)
; #define PG8_WAIT_V(n) asm volatile("s_waitcnt vmcnt(" #n ")" ::: "memory")
; #define PG8_WAIT_L(n) asm volatile("s_waitcnt lgkmcnt(" #n ")" ::: "memory")
; #define PG8_BAR __builtin_amdgcn_s_barrier()
; #define PG8_SCHED __builtin_amdgcn_sched_barrier(0)
; template <class Epi>
; __device__ __forceinline__ void gemm_phase(LAS unsigned char* lds, const Gemm g, const Sched& S, const Epi& E, const int tid) {
;     ...
;             PG8_LDB(B0, 0, 0); PG8_LDB(B1, 0, 1); PG8_SCHED; PG8_LDA(At, 0, 0); PG8_STAGE(PG8_SA(1, 1), a1 + hA, voffA);
;             PG8_WAIT_V(8); PG8_WAIT_L(0); PG8_BAR; PG8_MMA(0, 0, At, B0); PG8_MMA(0, 1, At, B1); PG8_BAR; PG8_SCHED;
;             PG8_LDA(At, 0, 1); PG8_STAGE(PG8_SB(0, 0), b2, voffB); PG8_STAGE(PG8_SB(0, 1), b2 + hB, voffB); PG8_STAGE(PG8_SA(0, 0), a2, voffA);
;             PG8_WAIT_V(8); PG8_WAIT_L(0); PG8_BAR; PG8_MMA(1, 0, At, B0); PG8_MMA(1, 1, At, B1); PG8_BAR; PG8_SCHED;
	s_setprio 1
	s_waitcnt lgkmcnt(0)
	v_mfma_f32_16x16x32_bf16 v[148:151], v[104:107], v[170:173], v[148:151]
	v_mfma_f32_16x16x32_bf16 v[140:143], v[124:127], v[170:173], v[140:143]
	v_mfma_f32_16x16x32_bf16 v[116:119], v[104:107], v[178:181], v[116:119]
	v_mfma_f32_16x16x32_bf16 v[108:111], v[124:127], v[178:181], v[108:111]
	v_mfma_f32_16x16x32_bf16 v[92:95], v[104:107], v[194:197], v[92:95]
	v_mfma_f32_16x16x32_bf16 v[88:91], v[124:127], v[194:197], v[88:91]
	v_mfma_f32_16x16x32_bf16 v[76:79], v[104:107], v[204:207], v[76:79]
	v_mfma_f32_16x16x32_bf16 v[72:75], v[124:127], v[204:207], v[72:75]
	v_mfma_f32_16x16x32_bf16 v[148:151], v[112:115], v[174:177], v[148:151]
	v_mfma_f32_16x16x32_bf16 v[140:143], v[128:131], v[174:177], v[140:143]
	v_mfma_f32_16x16x32_bf16 v[116:119], v[112:115], v[186:189], v[116:119]
	v_mfma_f32_16x16x32_bf16 v[108:111], v[128:131], v[186:189], v[108:111]
	v_mfma_f32_16x16x32_bf16 v[92:95], v[112:115], v[198:201], v[92:95]
	v_mfma_f32_16x16x32_bf16 v[88:91], v[128:131], v[198:201], v[88:91]
	v_mfma_f32_16x16x32_bf16 v[76:79], v[112:115], v[208:211], v[76:79]
	v_mfma_f32_16x16x32_bf16 v[72:75], v[128:131], v[208:211], v[72:75]
	v_mfma_f32_16x16x32_bf16 v[132:135], v[136:139], v[170:173], v[132:135]
	v_mfma_f32_16x16x32_bf16 v[120:123], v[152:155], v[170:173], v[120:123]
	v_mfma_f32_16x16x32_bf16 v[100:103], v[136:139], v[178:181], v[100:103]
	v_mfma_f32_16x16x32_bf16 v[96:99], v[152:155], v[178:181], v[96:99]
	v_mfma_f32_16x16x32_bf16 v[84:87], v[136:139], v[194:197], v[84:87]
	v_mfma_f32_16x16x32_bf16 v[80:83], v[152:155], v[194:197], v[80:83]
	v_mfma_f32_16x16x32_bf16 v[68:71], v[136:139], v[204:207], v[68:71]
	v_mfma_f32_16x16x32_bf16 v[64:67], v[152:155], v[204:207], v[64:67]
	v_mfma_f32_16x16x32_bf16 v[132:135], v[144:147], v[174:177], v[132:135]
	v_mfma_f32_16x16x32_bf16 v[120:123], v[156:159], v[174:177], v[120:123]
	v_mfma_f32_16x16x32_bf16 v[100:103], v[144:147], v[186:189], v[100:103]
	v_mfma_f32_16x16x32_bf16 v[96:99], v[156:159], v[186:189], v[96:99]
	v_mfma_f32_16x16x32_bf16 v[84:87], v[144:147], v[198:201], v[84:87]
	v_mfma_f32_16x16x32_bf16 v[80:83], v[156:159], v[198:201], v[80:83]
	v_mfma_f32_16x16x32_bf16 v[68:71], v[144:147], v[208:211], v[68:71]
	v_mfma_f32_16x16x32_bf16 v[64:67], v[156:159], v[208:211], v[64:67]
	s_setprio 0
	s_barrier
	s_add_i32 s16, s45, s47
	v_lshl_add_u64 v[190:191], s[20:21], 0, v[192:193]
	s_mov_b32 m0, s16
	ds_read_b128 v[170:173], v185 offset:16384
	ds_read_b128 v[174:177], v185 offset:17408
	ds_read_b128 v[178:181], v185 offset:18432
	ds_read_b128 v[186:189], v185 offset:19456
	ds_read_b128 v[194:197], v185 offset:20480
	ds_read_b128 v[198:201], v185 offset:21504
	ds_read_b128 v[204:207], v185 offset:22528
	ds_read_b128 v[208:211], v185 offset:23552
	global_load_lds_dwordx4 v[190:191], off
	s_add_i32 m0, s16, 0x2000
	s_add_u32 s16, s20, 0x20000
	v_lshl_add_u64 v[212:213], s[20:21], 0, v[164:165]
	s_addc_u32 s17, s21, 0
	s_add_i32 s45, s51, s47
	global_load_lds_dwordx4 v[212:213], off
	v_lshl_add_u64 v[214:215], s[16:17], 0, v[192:193]
	s_mov_b32 m0, s45
	v_lshl_add_u64 v[216:217], s[22:23], 0, v[162:163]
	global_load_lds_dwordx4 v[214:215], off
	v_lshl_add_u64 v[214:215], s[16:17], 0, v[164:165]
	s_add_i32 m0, s45, 0x2000
	s_nop 0
	global_load_lds_dwordx4 v[214:215], off
	v_lshl_add_u64 v[214:215], s[22:23], 0, v[160:161]
	s_mov_b32 m0, s73
	s_nop 0
	global_load_lds_dwordx4 v[214:215], off
	s_mov_b32 m0, s74
	s_nop 0
	global_load_lds_dwordx4 v[216:217], off
	s_waitcnt vmcnt(8)
	s_waitcnt lgkmcnt(0)
	s_barrier
	s_setprio 1
	s_waitcnt lgkmcnt(0)
	v_mfma_f32_16x16x32_bf16 v[60:63], v[104:107], v[170:173], v[60:63]
	v_mfma_f32_16x16x32_bf16 v[56:59], v[124:127], v[170:173], v[56:59]
	v_mfma_f32_16x16x32_bf16 v[44:47], v[104:107], v[178:181], v[44:47]
	v_mfma_f32_16x16x32_bf16 v[40:43], v[124:127], v[178:181], v[40:43]
	v_mfma_f32_16x16x32_bf16 v[28:31], v[104:107], v[194:197], v[28:31]
	v_mfma_f32_16x16x32_bf16 v[24:27], v[124:127], v[194:197], v[24:27]
	v_mfma_f32_16x16x32_bf16 v[12:15], v[104:107], v[204:207], v[12:15]
	v_mfma_f32_16x16x32_bf16 v[8:11], v[124:127], v[204:207], v[8:11]
	v_mfma_f32_16x16x32_bf16 v[60:63], v[112:115], v[174:177], v[60:63]
	v_mfma_f32_16x16x32_bf16 v[56:59], v[128:131], v[174:177], v[56:59]
	v_mfma_f32_16x16x32_bf16 v[44:47], v[112:115], v[186:189], v[44:47]
	v_mfma_f32_16x16x32_bf16 v[40:43], v[128:131], v[186:189], v[40:43]
	v_mfma_f32_16x16x32_bf16 v[28:31], v[112:115], v[198:201], v[28:31]
	v_mfma_f32_16x16x32_bf16 v[24:27], v[128:131], v[198:201], v[24:27]
	v_mfma_f32_16x16x32_bf16 v[12:15], v[112:115], v[208:211], v[12:15]
	v_mfma_f32_16x16x32_bf16 v[8:11], v[128:131], v[208:211], v[8:11]
	v_mfma_f32_16x16x32_bf16 v[52:55], v[136:139], v[170:173], v[52:55]
	v_mfma_f32_16x16x32_bf16 v[48:51], v[152:155], v[170:173], v[48:51]
	v_mfma_f32_16x16x32_bf16 v[36:39], v[136:139], v[178:181], v[36:39]
	v_mfma_f32_16x16x32_bf16 v[32:35], v[152:155], v[178:181], v[32:35]
	v_mfma_f32_16x16x32_bf16 v[20:23], v[136:139], v[194:197], v[20:23]
	v_mfma_f32_16x16x32_bf16 v[16:19], v[152:155], v[194:197], v[16:19]
	v_mfma_f32_16x16x32_bf16 v[4:7], v[136:139], v[204:207], v[4:7]
	v_mfma_f32_16x16x32_bf16 v[0:3], v[152:155], v[204:207], v[0:3]
	v_mfma_f32_16x16x32_bf16 v[52:55], v[144:147], v[174:177], v[52:55]
	v_mfma_f32_16x16x32_bf16 v[48:51], v[156:159], v[174:177], v[48:51]
	v_mfma_f32_16x16x32_bf16 v[36:39], v[144:147], v[186:189], v[36:39]
	v_mfma_f32_16x16x32_bf16 v[32:35], v[156:159], v[186:189], v[32:35]
	v_mfma_f32_16x16x32_bf16 v[20:23], v[144:147], v[198:201], v[20:23]
	v_mfma_f32_16x16x32_bf16 v[16:19], v[156:159], v[198:201], v[16:19]
	v_mfma_f32_16x16x32_bf16 v[4:7], v[144:147], v[208:211], v[4:7]
	v_mfma_f32_16x16x32_bf16 v[0:3], v[156:159], v[208:211], v[0:3]
	s_setprio 0
	s_barrier
; #define PG8_STAGE(bufoff, gbase, voff) do { _Pragma("unroll") for (int _i = 0; _i < 2; ++_i) \
;         __builtin_amdgcn_global_load_lds((const unsigned*)((const char*)(gbase) + (voff)[_i]), (LAS unsigned*)(lds + (bufoff) + ldsw + _i * 8192), 16, 0, 0); } while (0)
; #define PG8_LDA(dst, b, h) do { _Pragma("unroll") for (int m = 0; m < 4; ++m) _Pragma("unroll") for (int k = 0; k < 2; ++k) dst[m][k] = *(const LAS bf16x8*)(lds + PG8_SA(b, h) + aoff + m * 2048 + k * 1024); } while (0)
; #define PG8_LDB(dst, b, h) do { _Pragma("unroll") for (int n = 0; n < 2; ++n) _Pragma("unroll") for (int k = 0; k < 2; ++k) dst[n][k] = *(const LAS bf16x8*)(lds + PG8_SB(b, h) + boff + n * 2048 + k * 1024); } while (0)
; #define PG8_MMA(ai, bj, At, Bt) do { __builtin_amdgcn_s_setprio(1); _Pragma("unroll") for (int m = 0; m < 4; ++m) _Pragma("unroll") for (int n = 0; n < 2; ++n) _Pragma("unroll") for (int k = 0; k < 2; ++k) \
;         acc[ai][bj][m][n] = __builtin_amdgcn_mfma_f32_16x16x32_bf16(Bt[n][k], At[m][k], acc[ai][bj][m][n], 0, 0, 0); __builtin_amdgcn_s_setprio(0); } while (0)
; #define PG8_WAIT_V(n) asm volatile("s_waitcnt vmcnt(" #n ")" ::: "memory")
; #define PG8_WAIT_L(n) asm volatile("s_waitcnt lgkmcnt(" #n ")" ::: "memory")
; #define PG8_BAR __builtin_amdgcn_s_barrier()
; #define PG8_SCHED __builtin_amdgcn_sched_barrier(0)
; template <class Epi>
; __device__ __forceinline__ void gemm_phase(LAS unsigned char* lds, const Gemm g, const Sched& S, const Epi& E, const int tid) {
;     ...
;             PG8_LDB(B0, 1, 0); PG8_LDB(B1, 1, 1); PG8_SCHED; PG8_LDA(At, 1, 0); PG8_STAGE(PG8_SA(0, 1), a2 + hA, voffA);
;             PG8_WAIT_V(8); PG8_WAIT_L(0); PG8_BAR; PG8_MMA(0, 0, At, B0); PG8_MMA(0, 1, At, B1); PG8_BAR; PG8_SCHED;
	s_add_i32 s45, 0, 0x18000
	s_add_i32 s51, 0, 0x1c000
	v_add_u32_e32 v128, s45, v183
	v_add_u32_e32 v156, s51, v183
	ds_read_b128 v[104:107], v128
	ds_read_b128 v[112:115], v128 offset:1024
	ds_read_b128 v[124:127], v128 offset:2048
	ds_read_b128 v[128:131], v128 offset:3072
	ds_read_b128 v[136:139], v156
	ds_read_b128 v[144:147], v156 offset:1024
	ds_read_b128 v[152:155], v156 offset:2048
	ds_read_b128 v[156:159], v156 offset:3072
	s_add_u32 s16, s22, 0x120000
	s_addc_u32 s17, s23, 0
	s_mov_b32 m0, s75
	v_lshl_add_u64 v[218:219], s[16:17], 0, v[160:161]
	ds_read_b128 v[170:173], v185 offset:32768
	ds_read_b128 v[174:177], v185 offset:33792
	ds_read_b128 v[178:181], v185 offset:34816
	ds_read_b128 v[186:189], v185 offset:35840
	ds_read_b128 v[194:197], v185 offset:36864
	ds_read_b128 v[198:201], v185 offset:37888
	ds_read_b128 v[204:207], v185 offset:38912
	ds_read_b128 v[208:211], v185 offset:39936
	global_load_lds_dwordx4 v[218:219], off
	v_lshl_add_u64 v[218:219], s[16:17], 0, v[162:163]
	s_mov_b32 m0, s76
	s_nop 0
	global_load_lds_dwordx4 v[218:219], off
	s_waitcnt vmcnt(8)
	s_waitcnt lgkmcnt(0)
	s_barrier
	s_setprio 1
	s_waitcnt lgkmcnt(0)
	v_mfma_f32_16x16x32_bf16 v[148:151], v[104:107], v[170:173], v[148:151]
	v_mfma_f32_16x16x32_bf16 v[140:143], v[124:127], v[170:173], v[140:143]
	v_mfma_f32_16x16x32_bf16 v[116:119], v[104:107], v[178:181], v[116:119]
	v_mfma_f32_16x16x32_bf16 v[108:111], v[124:127], v[178:181], v[108:111]
	v_mfma_f32_16x16x32_bf16 v[92:95], v[104:107], v[194:197], v[92:95]
	v_mfma_f32_16x16x32_bf16 v[88:91], v[124:127], v[194:197], v[88:91]
	v_mfma_f32_16x16x32_bf16 v[76:79], v[104:107], v[204:207], v[76:79]
	v_mfma_f32_16x16x32_bf16 v[72:75], v[124:127], v[204:207], v[72:75]
	v_mfma_f32_16x16x32_bf16 v[148:151], v[112:115], v[174:177], v[148:151]
	v_mfma_f32_16x16x32_bf16 v[140:143], v[128:131], v[174:177], v[140:143]
	v_mfma_f32_16x16x32_bf16 v[116:119], v[112:115], v[186:189], v[116:119]
	v_mfma_f32_16x16x32_bf16 v[108:111], v[128:131], v[186:189], v[108:111]
	v_mfma_f32_16x16x32_bf16 v[92:95], v[112:115], v[198:201], v[92:95]
	v_mfma_f32_16x16x32_bf16 v[88:91], v[128:131], v[198:201], v[88:91]
	v_mfma_f32_16x16x32_bf16 v[76:79], v[112:115], v[208:211], v[76:79]
	v_mfma_f32_16x16x32_bf16 v[72:75], v[128:131], v[208:211], v[72:75]
	v_mfma_f32_16x16x32_bf16 v[132:135], v[136:139], v[170:173], v[132:135]
	v_mfma_f32_16x16x32_bf16 v[120:123], v[152:155], v[170:173], v[120:123]
	v_mfma_f32_16x16x32_bf16 v[100:103], v[136:139], v[178:181], v[100:103]
	v_mfma_f32_16x16x32_bf16 v[96:99], v[152:155], v[178:181], v[96:99]
	v_mfma_f32_16x16x32_bf16 v[84:87], v[136:139], v[194:197], v[84:87]
	v_mfma_f32_16x16x32_bf16 v[80:83], v[152:155], v[194:197], v[80:83]
	v_mfma_f32_16x16x32_bf16 v[68:71], v[136:139], v[204:207], v[68:71]
	v_mfma_f32_16x16x32_bf16 v[64:67], v[152:155], v[204:207], v[64:67]
	v_mfma_f32_16x16x32_bf16 v[132:135], v[144:147], v[174:177], v[132:135]
	v_mfma_f32_16x16x32_bf16 v[120:123], v[156:159], v[174:177], v[120:123]
	v_mfma_f32_16x16x32_bf16 v[100:103], v[144:147], v[186:189], v[100:103]
	v_mfma_f32_16x16x32_bf16 v[96:99], v[156:159], v[186:189], v[96:99]
	v_mfma_f32_16x16x32_bf16 v[84:87], v[144:147], v[198:201], v[84:87]
	v_mfma_f32_16x16x32_bf16 v[80:83], v[156:159], v[198:201], v[80:83]
	v_mfma_f32_16x16x32_bf16 v[68:71], v[144:147], v[208:211], v[68:71]
	v_mfma_f32_16x16x32_bf16 v[64:67], v[156:159], v[208:211], v[64:67]
	s_setprio 0
	s_barrier
; #define PG8_STAGE(bufoff, gbase, voff) do { _Pragma("unroll") for (int _i = 0; _i < 2; ++_i) \
;         __builtin_amdgcn_global_load_lds((const unsigned*)((const char*)(gbase) + (voff)[_i]), (LAS unsigned*)(lds + (bufoff) + ldsw + _i * 8192), 16, 0, 0); } while (0)
; #define PG8_LDA(dst, b, h) do { _Pragma("unroll") for (int m = 0; m < 4; ++m) _Pragma("unroll") for (int k = 0; k < 2; ++k) dst[m][k] = *(const LAS bf16x8*)(lds + PG8_SA(b, h) + aoff + m * 2048 + k * 1024); } while (0)
; #define PG8_MMA(ai, bj, At, Bt) do { __builtin_amdgcn_s_setprio(1); _Pragma("unroll") for (int m = 0; m < 4; ++m) _Pragma("unroll") for (int n = 0; n < 2; ++n) _Pragma("unroll") for (int k = 0; k < 2; ++k) \
;         acc[ai][bj][m][n] = __builtin_amdgcn_mfma_f32_16x16x32_bf16(Bt[n][k], At[m][k], acc[ai][bj][m][n], 0, 0, 0); __builtin_amdgcn_s_setprio(0); } while (0)
; #define PG8_WAIT_V(n) asm volatile("s_waitcnt vmcnt(" #n ")" ::: "memory")
; #define PG8_WAIT_L(n) asm volatile("s_waitcnt lgkmcnt(" #n ")" ::: "memory")
; #define PG8_BAR __builtin_amdgcn_s_barrier()
; #define PG8_SCHED __builtin_amdgcn_sched_barrier(0)
; template <class Epi>
; __device__ __forceinline__ void gemm_phase(LAS unsigned char* lds, const Gemm g, const Sched& S, const Epi& E, const int tid) {
;     ...
;         for (int t = 0; t < nt; t += 2) {
;     ...
;             PG8_LDA(At, 1, 1); PG8_STAGE(PG8_SB(1, 0), b3, voffB); PG8_STAGE(PG8_SB(1, 1), b3 + hB, voffB); PG8_STAGE(PG8_SA(1, 0), a3, voffA);
;             PG8_WAIT_V(8); PG8_WAIT_L(0); PG8_BAR; PG8_MMA(1, 0, At, B0); PG8_MMA(1, 1, At, B1); PG8_BAR; PG8_SCHED;
;         }
	s_add_i32 s16, s45, s47
	v_lshl_add_u64 v[190:191], v[190:191], 0, s[94:95]
	s_mov_b32 m0, s16
	ds_read_b128 v[170:173], v185 offset:49152
	ds_read_b128 v[174:177], v185 offset:50176
	ds_read_b128 v[178:181], v185 offset:51200
	ds_read_b128 v[186:189], v185 offset:52224
	ds_read_b128 v[194:197], v185 offset:53248
	ds_read_b128 v[198:201], v185 offset:54272
	ds_read_b128 v[204:207], v185 offset:55296
	ds_read_b128 v[208:211], v185 offset:56320
	global_load_lds_dwordx4 v[190:191], off
	s_add_i32 m0, s16, 0x2000
	s_add_u32 s16, s20, 0x20080
	v_lshl_add_u64 v[190:191], v[212:213], 0, s[94:95]
	s_addc_u32 s17, s21, 0
	s_add_i32 s20, s51, s47
	global_load_lds_dwordx4 v[190:191], off
	v_lshl_add_u64 v[190:191], s[16:17], 0, v[192:193]
	s_mov_b32 m0, s20
	s_nop 0
	global_load_lds_dwordx4 v[190:191], off
	v_lshl_add_u64 v[190:191], s[16:17], 0, v[164:165]
	s_add_i32 m0, s20, 0x2000
	s_nop 0
	global_load_lds_dwordx4 v[190:191], off
	v_lshl_add_u64 v[190:191], v[214:215], 0, s[94:95]
	s_mov_b32 m0, s77
	s_nop 0
	global_load_lds_dwordx4 v[190:191], off
	v_lshl_add_u64 v[190:191], v[216:217], 0, s[94:95]
	s_mov_b32 m0, s78
	s_nop 0
	global_load_lds_dwordx4 v[190:191], off
	s_waitcnt vmcnt(8)
	s_waitcnt lgkmcnt(0)
	s_barrier
	s_setprio 1
	s_waitcnt lgkmcnt(0)
	v_mfma_f32_16x16x32_bf16 v[60:63], v[104:107], v[170:173], v[60:63]
	v_mfma_f32_16x16x32_bf16 v[56:59], v[124:127], v[170:173], v[56:59]
	v_mfma_f32_16x16x32_bf16 v[44:47], v[104:107], v[178:181], v[44:47]
	v_mfma_f32_16x16x32_bf16 v[40:43], v[124:127], v[178:181], v[40:43]
	v_mfma_f32_16x16x32_bf16 v[28:31], v[104:107], v[194:197], v[28:31]
	v_mfma_f32_16x16x32_bf16 v[24:27], v[124:127], v[194:197], v[24:27]
	v_mfma_f32_16x16x32_bf16 v[12:15], v[104:107], v[204:207], v[12:15]
	v_mfma_f32_16x16x32_bf16 v[8:11], v[124:127], v[204:207], v[8:11]
	v_mfma_f32_16x16x32_bf16 v[60:63], v[112:115], v[174:177], v[60:63]
	v_mfma_f32_16x16x32_bf16 v[56:59], v[128:131], v[174:177], v[56:59]
	v_mfma_f32_16x16x32_bf16 v[44:47], v[112:115], v[186:189], v[44:47]
	v_mfma_f32_16x16x32_bf16 v[40:43], v[128:131], v[186:189], v[40:43]
	v_mfma_f32_16x16x32_bf16 v[28:31], v[112:115], v[198:201], v[28:31]
	v_mfma_f32_16x16x32_bf16 v[24:27], v[128:131], v[198:201], v[24:27]
	v_mfma_f32_16x16x32_bf16 v[12:15], v[112:115], v[208:211], v[12:15]
	v_mfma_f32_16x16x32_bf16 v[8:11], v[128:131], v[208:211], v[8:11]
	v_mfma_f32_16x16x32_bf16 v[52:55], v[136:139], v[170:173], v[52:55]
	v_mfma_f32_16x16x32_bf16 v[48:51], v[152:155], v[170:173], v[48:51]
	v_mfma_f32_16x16x32_bf16 v[36:39], v[136:139], v[178:181], v[36:39]
	v_mfma_f32_16x16x32_bf16 v[32:35], v[152:155], v[178:181], v[32:35]
	v_mfma_f32_16x16x32_bf16 v[20:23], v[136:139], v[194:197], v[20:23]
	v_mfma_f32_16x16x32_bf16 v[16:19], v[152:155], v[194:197], v[16:19]
	v_mfma_f32_16x16x32_bf16 v[4:7], v[136:139], v[204:207], v[4:7]
	v_mfma_f32_16x16x32_bf16 v[0:3], v[152:155], v[204:207], v[0:3]
	v_mfma_f32_16x16x32_bf16 v[52:55], v[144:147], v[174:177], v[52:55]
	v_mfma_f32_16x16x32_bf16 v[48:51], v[156:159], v[174:177], v[48:51]
	v_mfma_f32_16x16x32_bf16 v[36:39], v[144:147], v[186:189], v[36:39]
	v_mfma_f32_16x16x32_bf16 v[32:35], v[156:159], v[186:189], v[32:35]
	v_mfma_f32_16x16x32_bf16 v[20:23], v[144:147], v[198:201], v[20:23]
	v_mfma_f32_16x16x32_bf16 v[16:19], v[156:159], v[198:201], v[16:19]
	v_mfma_f32_16x16x32_bf16 v[4:7], v[144:147], v[208:211], v[4:7]
	v_mfma_f32_16x16x32_bf16 v[0:3], v[156:159], v[208:211], v[0:3]
	s_add_i32 s42, s42, 2
	s_add_u32 s13, s13, 0x100
	s_addc_u32 s40, s40, 0
	s_cmp_gt_u32 s42, 5
	s_mov_b64 s[16:17], s[18:19]
	s_setprio 0
	s_barrier
	s_cbranch_scc0 .LBB0_994

; #define PG8_STAGE(bufoff, gbase, voff) do { _Pragma("unroll") for (int _i = 0; _i < 2; ++_i) \
;         __builtin_amdgcn_global_load_lds((const unsigned*)((const char*)(gbase) + (voff)[_i]), (LAS unsigned*)(lds + (bufoff) + ldsw + _i * 8192), 16, 0, 0); } while (0)
; #define PG8_LDA(dst, b, h) do { _Pragma("unroll") for (int m = 0; m < 4; ++m) _Pragma("unroll") for (int k = 0; k < 2; ++k) dst[m][k] = *(const LAS bf16x8*)(lds + PG8_SA(b, h) + aoff + m * 2048 + k * 1024); } while (0)
; #define PG8_LDB(dst, b, h) do { _Pragma("unroll") for (int n = 0; n < 2; ++n) _Pragma("unroll") for (int k = 0; k < 2; ++k) dst[n][k] = *(const LAS bf16x8*)(lds + PG8_SB(b, h) + boff + n * 2048 + k * 1024); } while (0)
; #define PG8_WAIT_V(n) asm volatile("s_waitcnt vmcnt(" #n ")" ::: "memory")
; #define PG8_BAR __builtin_amdgcn_s_barrier()
; template <class Epi>
; __device__ __forceinline__ void gemm_phase(LAS unsigned char* lds, const Gemm g, const Sched& S, const Epi& E, const int tid) {
;     ...
;     PG8_STAGE(PG8_SB(0, 0), cB, voffB); PG8_STAGE(PG8_SB(0, 1), cB + hB, voffB); PG8_STAGE(PG8_SA(0, 0), cA, voffA); PG8_STAGE(PG8_SA(0, 1), cA + hA, voffA);
;     if (wr == 1) PG8_BAR;
;     PG8_WAIT_V(2); PG8_BAR;
;     PG8_STAGE(PG8_SB(1, 0), cB + kstep, voffB); PG8_STAGE(PG8_SA(1, 0), cA + kstep, voffA); PG8_STAGE(PG8_SB(1, 1), cB + hB + kstep, voffB);
;     PG8_WAIT_V(6); PG8_BAR;
;     for (;;) {
;         const bool has_next = S.next(ui + 1, nxt);
;         const char* nA = cA; const char* nB = cB; if (has_next) S.ptrs(nxt, nA, nB);
;         for (int t = 0; t < nt; t += 2) {
;             const bool last = (t == nt - 2);
;             const char* a1 = cA + (size_t)(t + 1) * kstep;
;             const char* a2 = last ? nA : cA + (size_t)(t + 2) * kstep; const char* b2 = last ? nB : cB + (size_t)(t + 2) * kstep;
;             const char* a3 = a2 + kstep; const char* b3 = b2 + kstep;
;             PG8_LDB(B0, 0, 0); PG8_LDB(B1, 0, 1); PG8_SCHED; PG8_LDA(At, 0, 0); PG8_STAGE(PG8_SA(1, 1), a1 + hA, voffA);
;             PG8_WAIT_V(8); PG8_WAIT_L(0); PG8_BAR; PG8_MMA(0, 0, At, B0); PG8_MMA(0, 1, At, B1); PG8_BAR; PG8_SCHED;
;             PG8_LDA(At, 0, 1); PG8_STAGE(PG8_SB(0, 0), b2, voffB); PG8_STAGE(PG8_SB(0, 1), b2 + hB, voffB); PG8_STAGE(PG8_SA(0, 0), a2, voffA);
;             PG8_WAIT_V(8); PG8_WAIT_L(0); PG8_BAR; PG8_MMA(1, 0, At, B0); PG8_MMA(1, 1, At, B1); PG8_BAR; PG8_SCHED;
.LBB0_1028:
	s_add_u32 s13, s22, 0x100
	s_addc_u32 s37, s23, 0
	s_mov_b32 s40, -2
	s_add_u32 s6, s20, 0x100
	s_addc_u32 s7, s21, 0
	s_add_i32 s42, 0, 0x10000
	s_cmp_eq_u32 s40, 4
	s_cselect_b32 s73, s15, s7
	s_cselect_b32 s72, s14, s6
	s_cselect_b32 s23, s17, s37
	s_cselect_b32 s22, s16, s13
	s_add_i32 s45, 0, 0x14000
	v_add_u32_e32 v128, s42, v241
	v_add_u32_e32 v156, s45, v241
	ds_read_b128 v[104:107], v128
	ds_read_b128 v[112:115], v128 offset:1024
	ds_read_b128 v[120:123], v128 offset:2048
	ds_read_b128 v[128:131], v128 offset:3072
	ds_read_b128 v[136:139], v156
	ds_read_b128 v[140:143], v156 offset:1024
	ds_read_b128 v[148:151], v156 offset:2048
	ds_read_b128 v[156:159], v156 offset:3072
	v_lshl_add_u64 v[194:195], s[20:21], 0, v[210:211]
	s_add_i32 m0, s19, 0xc000
	ds_read_b128 v[160:163], v243
	ds_read_b128 v[164:167], v243 offset:1024
	ds_read_b128 v[168:171], v243 offset:2048
	ds_read_b128 v[172:175], v243 offset:3072
	ds_read_b128 v[176:179], v243 offset:4096
	ds_read_b128 v[180:183], v243 offset:5120
	ds_read_b128 v[184:187], v243 offset:6144
	ds_read_b128 v[188:191], v243 offset:7168
	global_load_lds_dwordx4 v[194:195], off
	v_lshl_add_u64 v[194:195], s[20:21], 0, v[212:213]
	s_add_i32 m0, s19, 0xe000
	s_nop 0
	global_load_lds_dwordx4 v[194:195], off
	s_waitcnt vmcnt(8)
	s_waitcnt lgkmcnt(0)
	s_barrier
	s_setprio 1
	s_waitcnt lgkmcnt(0)
	v_mfma_f32_16x16x32_bf16 v[152:155], v[104:107], v[160:163], 0
	v_mfma_f32_16x16x32_bf16 v[144:147], v[120:123], v[160:163], 0
	v_mfma_f32_16x16x32_bf16 v[116:119], v[104:107], v[168:171], 0
	v_mfma_f32_16x16x32_bf16 v[108:111], v[120:123], v[168:171], 0
	v_mfma_f32_16x16x32_bf16 v[92:95], v[104:107], v[176:179], 0
	v_mfma_f32_16x16x32_bf16 v[88:91], v[120:123], v[176:179], 0
	v_mfma_f32_16x16x32_bf16 v[76:79], v[104:107], v[184:187], 0
	v_mfma_f32_16x16x32_bf16 v[72:75], v[120:123], v[184:187], 0
	v_mfma_f32_16x16x32_bf16 v[152:155], v[112:115], v[164:167], v[152:155]
	v_mfma_f32_16x16x32_bf16 v[144:147], v[128:131], v[164:167], v[144:147]
	v_mfma_f32_16x16x32_bf16 v[116:119], v[112:115], v[172:175], v[116:119]
	v_mfma_f32_16x16x32_bf16 v[108:111], v[128:131], v[172:175], v[108:111]
	v_mfma_f32_16x16x32_bf16 v[92:95], v[112:115], v[180:183], v[92:95]
	v_mfma_f32_16x16x32_bf16 v[88:91], v[128:131], v[180:183], v[88:91]
	v_mfma_f32_16x16x32_bf16 v[76:79], v[112:115], v[188:191], v[76:79]
	v_mfma_f32_16x16x32_bf16 v[72:75], v[128:131], v[188:191], v[72:75]
	v_mfma_f32_16x16x32_bf16 v[132:135], v[136:139], v[160:163], 0
	v_mfma_f32_16x16x32_bf16 v[124:127], v[148:151], v[160:163], 0
	v_mfma_f32_16x16x32_bf16 v[100:103], v[136:139], v[168:171], 0
	v_mfma_f32_16x16x32_bf16 v[96:99], v[148:151], v[168:171], 0
	v_mfma_f32_16x16x32_bf16 v[84:87], v[136:139], v[176:179], 0
	v_mfma_f32_16x16x32_bf16 v[80:83], v[148:151], v[176:179], 0
	v_mfma_f32_16x16x32_bf16 v[68:71], v[136:139], v[184:187], 0
	v_mfma_f32_16x16x32_bf16 v[64:67], v[148:151], v[184:187], 0
	v_mfma_f32_16x16x32_bf16 v[132:135], v[140:143], v[164:167], v[132:135]
	v_mfma_f32_16x16x32_bf16 v[124:127], v[156:159], v[164:167], v[124:127]
	v_mfma_f32_16x16x32_bf16 v[100:103], v[140:143], v[172:175], v[100:103]
	v_mfma_f32_16x16x32_bf16 v[96:99], v[156:159], v[172:175], v[96:99]
	v_mfma_f32_16x16x32_bf16 v[84:87], v[140:143], v[180:183], v[84:87]
	v_mfma_f32_16x16x32_bf16 v[80:83], v[156:159], v[180:183], v[80:83]
	v_mfma_f32_16x16x32_bf16 v[68:71], v[140:143], v[188:191], v[68:71]
	v_mfma_f32_16x16x32_bf16 v[64:67], v[156:159], v[188:191], v[64:67]
	s_setprio 0
	s_barrier
	s_add_i32 s20, s42, s35
	v_lshl_add_u64 v[194:195], s[22:23], 0, v[192:193]
	s_mov_b32 m0, s20
	ds_read_b128 v[160:163], v243 offset:16384
	ds_read_b128 v[164:167], v243 offset:17408
	ds_read_b128 v[168:171], v243 offset:18432
	ds_read_b128 v[172:175], v243 offset:19456
	ds_read_b128 v[176:179], v243 offset:20480
	ds_read_b128 v[180:183], v243 offset:21504
	ds_read_b128 v[184:187], v243 offset:22528
	ds_read_b128 v[188:191], v243 offset:23552
	global_load_lds_dwordx4 v[194:195], off
	s_add_i32 m0, s20, 0x2000
	s_add_u32 s20, s22, 0x20000
	v_lshl_add_u64 v[196:197], s[22:23], 0, v[208:209]
	s_addc_u32 s21, s23, 0
	s_add_i32 s42, s45, s35
	global_load_lds_dwordx4 v[196:197], off
	v_lshl_add_u64 v[198:199], s[20:21], 0, v[192:193]
	s_mov_b32 m0, s42
	v_lshl_add_u64 v[200:201], s[72:73], 0, v[206:207]
	global_load_lds_dwordx4 v[198:199], off
	v_lshl_add_u64 v[198:199], s[20:21], 0, v[208:209]
	s_add_i32 m0, s42, 0x2000
	s_nop 0
	global_load_lds_dwordx4 v[198:199], off
	v_lshl_add_u64 v[198:199], s[72:73], 0, v[204:205]
	s_mov_b32 m0, s19
	s_nop 0
	global_load_lds_dwordx4 v[198:199], off
	s_mov_b32 m0, s74
	s_nop 0
	global_load_lds_dwordx4 v[200:201], off
	s_waitcnt vmcnt(8)
	s_waitcnt lgkmcnt(0)
	s_barrier
; #define PG8_STAGE(bufoff, gbase, voff) do { _Pragma("unroll") for (int _i = 0; _i < 2; ++_i) \
;         __builtin_amdgcn_global_load_lds((const unsigned*)((const char*)(gbase) + (voff)[_i]), (LAS unsigned*)(lds + (bufoff) + ldsw + _i * 8192), 16, 0, 0); } while (0)
; #define PG8_LDA(dst, b, h) do { _Pragma("unroll") for (int m = 0; m < 4; ++m) _Pragma("unroll") for (int k = 0; k < 2; ++k) dst[m][k] = *(const LAS bf16x8*)(lds + PG8_SA(b, h) + aoff + m * 2048 + k * 1024); } while (0)
; #define PG8_LDB(dst, b, h) do { _Pragma("unroll") for (int n = 0; n < 2; ++n) _Pragma("unroll") for (int k = 0; k < 2; ++k) dst[n][k] = *(const LAS bf16x8*)(lds + PG8_SB(b, h) + boff + n * 2048 + k * 1024); } while (0)
; #define PG8_MMA(ai, bj, At, Bt) do { __builtin_amdgcn_s_setprio(1); _Pragma("unroll") for (int m = 0; m < 4; ++m) _Pragma("unroll") for (int n = 0; n < 2; ++n) _Pragma("unroll") for (int k = 0; k < 2; ++k) \
;         acc[ai][bj][m][n] = __builtin_amdgcn_mfma_f32_16x16x32_bf16(Bt[n][k], At[m][k], acc[ai][bj][m][n], 0, 0, 0); __builtin_amdgcn_s_setprio(0); } while (0)
; #define PG8_WAIT_V(n) asm volatile("s_waitcnt vmcnt(" #n ")" ::: "memory")
; #define PG8_WAIT_L(n) asm volatile("s_waitcnt lgkmcnt(" #n ")" ::: "memory")
; #define PG8_BAR __builtin_amdgcn_s_barrier()
; #define PG8_SCHED __builtin_amdgcn_sched_barrier(0)
; template <class Epi>
; __device__ __forceinline__ void gemm_phase(LAS unsigned char* lds, const Gemm g, const Sched& S, const Epi& E, const int tid) {
;     ...
;             PG8_WAIT_V(8); PG8_WAIT_L(0); PG8_BAR; PG8_MMA(1, 0, At, B0); PG8_MMA(1, 1, At, B1); PG8_BAR; PG8_SCHED;
;             PG8_LDB(B0, 1, 0); PG8_LDB(B1, 1, 1); PG8_SCHED; PG8_LDA(At, 1, 0); PG8_STAGE(PG8_SA(0, 1), a2 + hA, voffA);
;             PG8_WAIT_V(8); PG8_WAIT_L(0); PG8_BAR; PG8_MMA(0, 0, At, B0); PG8_MMA(0, 1, At, B1); PG8_BAR; PG8_SCHED;
	s_setprio 1
	s_waitcnt lgkmcnt(0)
	v_mfma_f32_16x16x32_bf16 v[60:63], v[104:107], v[160:163], 0
	v_mfma_f32_16x16x32_bf16 v[56:59], v[120:123], v[160:163], 0
	v_mfma_f32_16x16x32_bf16 v[44:47], v[104:107], v[168:171], 0
	v_mfma_f32_16x16x32_bf16 v[40:43], v[120:123], v[168:171], 0
	v_mfma_f32_16x16x32_bf16 v[28:31], v[104:107], v[176:179], 0
	v_mfma_f32_16x16x32_bf16 v[24:27], v[120:123], v[176:179], 0
	v_mfma_f32_16x16x32_bf16 v[12:15], v[104:107], v[184:187], 0
	v_mfma_f32_16x16x32_bf16 v[8:11], v[120:123], v[184:187], 0
	v_mfma_f32_16x16x32_bf16 v[60:63], v[112:115], v[164:167], v[60:63]
	v_mfma_f32_16x16x32_bf16 v[56:59], v[128:131], v[164:167], v[56:59]
	v_mfma_f32_16x16x32_bf16 v[44:47], v[112:115], v[172:175], v[44:47]
	v_mfma_f32_16x16x32_bf16 v[40:43], v[128:131], v[172:175], v[40:43]
	v_mfma_f32_16x16x32_bf16 v[28:31], v[112:115], v[180:183], v[28:31]
	v_mfma_f32_16x16x32_bf16 v[24:27], v[128:131], v[180:183], v[24:27]
	v_mfma_f32_16x16x32_bf16 v[12:15], v[112:115], v[188:191], v[12:15]
	v_mfma_f32_16x16x32_bf16 v[8:11], v[128:131], v[188:191], v[8:11]
	v_mfma_f32_16x16x32_bf16 v[52:55], v[136:139], v[160:163], 0
	v_mfma_f32_16x16x32_bf16 v[48:51], v[148:151], v[160:163], 0
	v_mfma_f32_16x16x32_bf16 v[36:39], v[136:139], v[168:171], 0
	v_mfma_f32_16x16x32_bf16 v[32:35], v[148:151], v[168:171], 0
	v_mfma_f32_16x16x32_bf16 v[20:23], v[136:139], v[176:179], 0
	v_mfma_f32_16x16x32_bf16 v[16:19], v[148:151], v[176:179], 0
	v_mfma_f32_16x16x32_bf16 v[4:7], v[136:139], v[184:187], 0
	v_mfma_f32_16x16x32_bf16 v[0:3], v[148:151], v[184:187], 0
	v_mfma_f32_16x16x32_bf16 v[52:55], v[140:143], v[164:167], v[52:55]
	v_mfma_f32_16x16x32_bf16 v[48:51], v[156:159], v[164:167], v[48:51]
	v_mfma_f32_16x16x32_bf16 v[36:39], v[140:143], v[172:175], v[36:39]
	v_mfma_f32_16x16x32_bf16 v[32:35], v[156:159], v[172:175], v[32:35]
	v_mfma_f32_16x16x32_bf16 v[20:23], v[140:143], v[180:183], v[20:23]
	v_mfma_f32_16x16x32_bf16 v[16:19], v[156:159], v[180:183], v[16:19]
	v_mfma_f32_16x16x32_bf16 v[4:7], v[140:143], v[188:191], v[4:7]
	v_mfma_f32_16x16x32_bf16 v[0:3], v[156:159], v[188:191], v[0:3]
	s_setprio 0
	s_barrier
	s_add_i32 s42, 0, 0x18000
	s_add_i32 s45, 0, 0x1c000
	v_add_u32_e32 v128, s42, v241
	v_add_u32_e32 v156, s45, v241
	ds_read_b128 v[104:107], v128
	ds_read_b128 v[112:115], v128 offset:1024
	ds_read_b128 v[120:123], v128 offset:2048
	ds_read_b128 v[128:131], v128 offset:3072
	ds_read_b128 v[136:139], v156
	ds_read_b128 v[140:143], v156 offset:1024
	ds_read_b128 v[148:151], v156 offset:2048
	ds_read_b128 v[156:159], v156 offset:3072
	s_add_u32 s20, s72, 0x120000
	s_addc_u32 s21, s73, 0
	s_mov_b32 m0, s75
	v_lshl_add_u64 v[214:215], s[20:21], 0, v[204:205]
	ds_read_b128 v[160:163], v243 offset:32768
	ds_read_b128 v[164:167], v243 offset:33792
	ds_read_b128 v[168:171], v243 offset:34816
	ds_read_b128 v[172:175], v243 offset:35840
	ds_read_b128 v[176:179], v243 offset:36864
	ds_read_b128 v[180:183], v243 offset:37888
	ds_read_b128 v[184:187], v243 offset:38912
	ds_read_b128 v[188:191], v243 offset:39936
	global_load_lds_dwordx4 v[214:215], off
	v_lshl_add_u64 v[214:215], s[20:21], 0, v[206:207]
	s_mov_b32 m0, s76
	s_nop 0
	global_load_lds_dwordx4 v[214:215], off
	s_waitcnt vmcnt(8)
	s_waitcnt lgkmcnt(0)
	s_barrier
	s_setprio 1
	s_waitcnt lgkmcnt(0)
	v_mfma_f32_16x16x32_bf16 v[152:155], v[104:107], v[160:163], v[152:155]
	v_mfma_f32_16x16x32_bf16 v[144:147], v[120:123], v[160:163], v[144:147]
	v_mfma_f32_16x16x32_bf16 v[116:119], v[104:107], v[168:171], v[116:119]
	v_mfma_f32_16x16x32_bf16 v[108:111], v[120:123], v[168:171], v[108:111]
	v_mfma_f32_16x16x32_bf16 v[92:95], v[104:107], v[176:179], v[92:95]
	v_mfma_f32_16x16x32_bf16 v[88:91], v[120:123], v[176:179], v[88:91]
	v_mfma_f32_16x16x32_bf16 v[76:79], v[104:107], v[184:187], v[76:79]
	v_mfma_f32_16x16x32_bf16 v[72:75], v[120:123], v[184:187], v[72:75]
	v_mfma_f32_16x16x32_bf16 v[152:155], v[112:115], v[164:167], v[152:155]
	v_mfma_f32_16x16x32_bf16 v[144:147], v[128:131], v[164:167], v[144:147]
	v_mfma_f32_16x16x32_bf16 v[116:119], v[112:115], v[172:175], v[116:119]
	v_mfma_f32_16x16x32_bf16 v[108:111], v[128:131], v[172:175], v[108:111]
	v_mfma_f32_16x16x32_bf16 v[92:95], v[112:115], v[180:183], v[92:95]
	v_mfma_f32_16x16x32_bf16 v[88:91], v[128:131], v[180:183], v[88:91]
	v_mfma_f32_16x16x32_bf16 v[76:79], v[112:115], v[188:191], v[76:79]
	v_mfma_f32_16x16x32_bf16 v[72:75], v[128:131], v[188:191], v[72:75]
	v_mfma_f32_16x16x32_bf16 v[132:135], v[136:139], v[160:163], v[132:135]
	v_mfma_f32_16x16x32_bf16 v[124:127], v[148:151], v[160:163], v[124:127]
	v_mfma_f32_16x16x32_bf16 v[100:103], v[136:139], v[168:171], v[100:103]
	v_mfma_f32_16x16x32_bf16 v[96:99], v[148:151], v[168:171], v[96:99]
	v_mfma_f32_16x16x32_bf16 v[84:87], v[136:139], v[176:179], v[84:87]
	v_mfma_f32_16x16x32_bf16 v[80:83], v[148:151], v[176:179], v[80:83]
	v_mfma_f32_16x16x32_bf16 v[68:71], v[136:139], v[184:187], v[68:71]
	v_mfma_f32_16x16x32_bf16 v[64:67], v[148:151], v[184:187], v[64:67]
	v_mfma_f32_16x16x32_bf16 v[132:135], v[140:143], v[164:167], v[132:135]
	v_mfma_f32_16x16x32_bf16 v[124:127], v[156:159], v[164:167], v[124:127]
	v_mfma_f32_16x16x32_bf16 v[100:103], v[140:143], v[172:175], v[100:103]
	v_mfma_f32_16x16x32_bf16 v[96:99], v[156:159], v[172:175], v[96:99]
	v_mfma_f32_16x16x32_bf16 v[84:87], v[140:143], v[180:183], v[84:87]
	v_mfma_f32_16x16x32_bf16 v[80:83], v[156:159], v[180:183], v[80:83]
	v_mfma_f32_16x16x32_bf16 v[68:71], v[140:143], v[188:191], v[68:71]
	v_mfma_f32_16x16x32_bf16 v[64:67], v[156:159], v[188:191], v[64:67]
	s_setprio 0
	s_barrier
; #define PG8_STAGE(bufoff, gbase, voff) do { _Pragma("unroll") for (int _i = 0; _i < 2; ++_i) \
;         __builtin_amdgcn_global_load_lds((const unsigned*)((const char*)(gbase) + (voff)[_i]), (LAS unsigned*)(lds + (bufoff) + ldsw + _i * 8192), 16, 0, 0); } while (0)
; #define PG8_LDA(dst, b, h) do { _Pragma("unroll") for (int m = 0; m < 4; ++m) _Pragma("unroll") for (int k = 0; k < 2; ++k) dst[m][k] = *(const LAS bf16x8*)(lds + PG8_SA(b, h) + aoff + m * 2048 + k * 1024); } while (0)
; #define PG8_LDB(dst, b, h) do { _Pragma("unroll") for (int n = 0; n < 2; ++n) _Pragma("unroll") for (int k = 0; k < 2; ++k) dst[n][k] = *(const LAS bf16x8*)(lds + PG8_SB(b, h) + boff + n * 2048 + k * 1024); } while (0)
; #define PG8_MMA(ai, bj, At, Bt) do { __builtin_amdgcn_s_setprio(1); _Pragma("unroll") for (int m = 0; m < 4; ++m) _Pragma("unroll") for (int n = 0; n < 2; ++n) _Pragma("unroll") for (int k = 0; k < 2; ++k) \
;         acc[ai][bj][m][n] = __builtin_amdgcn_mfma_f32_16x16x32_bf16(Bt[n][k], At[m][k], acc[ai][bj][m][n], 0, 0, 0); __builtin_amdgcn_s_setprio(0); } while (0)
; #define PG8_WAIT_V(n) asm volatile("s_waitcnt vmcnt(" #n ")" ::: "memory")
; #define PG8_WAIT_L(n) asm volatile("s_waitcnt lgkmcnt(" #n ")" ::: "memory")
; #define PG8_BAR __builtin_amdgcn_s_barrier()
; #define PG8_SCHED __builtin_amdgcn_sched_barrier(0)
; template <class Epi>
; __device__ __forceinline__ void gemm_phase(LAS unsigned char* lds, const Gemm g, const Sched& S, const Epi& E, const int tid) {
;     ...
;         for (int t = 0; t < nt; t += 2) {
;             const bool last = (t == nt - 2);
;             const char* a1 = cA + (size_t)(t + 1) * kstep;
;             const char* a2 = last ? nA : cA + (size_t)(t + 2) * kstep; const char* b2 = last ? nB : cB + (size_t)(t + 2) * kstep;
;             const char* a3 = a2 + kstep; const char* b3 = b2 + kstep;
;             PG8_LDB(B0, 0, 0); PG8_LDB(B1, 0, 1); PG8_SCHED; PG8_LDA(At, 0, 0); PG8_STAGE(PG8_SA(1, 1), a1 + hA, voffA);
;             PG8_WAIT_V(8); PG8_WAIT_L(0); PG8_BAR; PG8_MMA(0, 0, At, B0); PG8_MMA(0, 1, At, B1); PG8_BAR; PG8_SCHED;
;     ...
;             PG8_LDA(At, 1, 1); PG8_STAGE(PG8_SB(1, 0), b3, voffB); PG8_STAGE(PG8_SB(1, 1), b3 + hB, voffB); PG8_STAGE(PG8_SA(1, 0), a3, voffA);
;             PG8_WAIT_V(8); PG8_WAIT_L(0); PG8_BAR; PG8_MMA(1, 0, At, B0); PG8_MMA(1, 1, At, B1); PG8_BAR; PG8_SCHED;
;         }
	s_add_i32 s20, s42, s35
	v_lshl_add_u64 v[194:195], v[194:195], 0, s[94:95]
	s_mov_b32 m0, s20
	ds_read_b128 v[160:163], v243 offset:49152
	ds_read_b128 v[164:167], v243 offset:50176
	ds_read_b128 v[168:171], v243 offset:51200
	ds_read_b128 v[172:175], v243 offset:52224
	ds_read_b128 v[176:179], v243 offset:53248
	ds_read_b128 v[180:183], v243 offset:54272
	ds_read_b128 v[184:187], v243 offset:55296
	ds_read_b128 v[188:191], v243 offset:56320
	global_load_lds_dwordx4 v[194:195], off
	s_add_i32 m0, s20, 0x2000
	s_add_u32 s20, s22, 0x20080
	v_lshl_add_u64 v[194:195], v[196:197], 0, s[94:95]
	s_addc_u32 s21, s23, 0
	s_add_i32 s22, s45, s35
	global_load_lds_dwordx4 v[194:195], off
	v_lshl_add_u64 v[194:195], s[20:21], 0, v[192:193]
	s_mov_b32 m0, s22
	s_nop 0
	global_load_lds_dwordx4 v[194:195], off
	v_lshl_add_u64 v[194:195], s[20:21], 0, v[208:209]
	s_add_i32 m0, s22, 0x2000
	s_nop 0
	global_load_lds_dwordx4 v[194:195], off
	v_lshl_add_u64 v[194:195], v[198:199], 0, s[94:95]
	s_mov_b32 m0, s77
	s_nop 0
	global_load_lds_dwordx4 v[194:195], off
	v_lshl_add_u64 v[194:195], v[200:201], 0, s[94:95]
	s_mov_b32 m0, s78
	s_nop 0
	global_load_lds_dwordx4 v[194:195], off
	s_waitcnt vmcnt(8)
	s_waitcnt lgkmcnt(0)
	s_barrier
	s_setprio 1
	s_waitcnt lgkmcnt(0)
	v_mfma_f32_16x16x32_bf16 v[60:63], v[104:107], v[160:163], v[60:63]
	v_mfma_f32_16x16x32_bf16 v[56:59], v[120:123], v[160:163], v[56:59]
	v_mfma_f32_16x16x32_bf16 v[44:47], v[104:107], v[168:171], v[44:47]
	v_mfma_f32_16x16x32_bf16 v[40:43], v[120:123], v[168:171], v[40:43]
	v_mfma_f32_16x16x32_bf16 v[28:31], v[104:107], v[176:179], v[28:31]
	v_mfma_f32_16x16x32_bf16 v[24:27], v[120:123], v[176:179], v[24:27]
	v_mfma_f32_16x16x32_bf16 v[12:15], v[104:107], v[184:187], v[12:15]
	v_mfma_f32_16x16x32_bf16 v[8:11], v[120:123], v[184:187], v[8:11]
	v_mfma_f32_16x16x32_bf16 v[60:63], v[112:115], v[164:167], v[60:63]
	v_mfma_f32_16x16x32_bf16 v[56:59], v[128:131], v[164:167], v[56:59]
	v_mfma_f32_16x16x32_bf16 v[44:47], v[112:115], v[172:175], v[44:47]
	v_mfma_f32_16x16x32_bf16 v[40:43], v[128:131], v[172:175], v[40:43]
	v_mfma_f32_16x16x32_bf16 v[28:31], v[112:115], v[180:183], v[28:31]
	v_mfma_f32_16x16x32_bf16 v[24:27], v[128:131], v[180:183], v[24:27]
	v_mfma_f32_16x16x32_bf16 v[12:15], v[112:115], v[188:191], v[12:15]
	v_mfma_f32_16x16x32_bf16 v[8:11], v[128:131], v[188:191], v[8:11]
	v_mfma_f32_16x16x32_bf16 v[52:55], v[136:139], v[160:163], v[52:55]
	v_mfma_f32_16x16x32_bf16 v[48:51], v[148:151], v[160:163], v[48:51]
	v_mfma_f32_16x16x32_bf16 v[36:39], v[136:139], v[168:171], v[36:39]
	v_mfma_f32_16x16x32_bf16 v[32:35], v[148:151], v[168:171], v[32:35]
	v_mfma_f32_16x16x32_bf16 v[20:23], v[136:139], v[176:179], v[20:23]
	v_mfma_f32_16x16x32_bf16 v[16:19], v[148:151], v[176:179], v[16:19]
	v_mfma_f32_16x16x32_bf16 v[4:7], v[136:139], v[184:187], v[4:7]
	v_mfma_f32_16x16x32_bf16 v[0:3], v[148:151], v[184:187], v[0:3]
	v_mfma_f32_16x16x32_bf16 v[52:55], v[140:143], v[164:167], v[52:55]
	v_mfma_f32_16x16x32_bf16 v[48:51], v[156:159], v[164:167], v[48:51]
	v_mfma_f32_16x16x32_bf16 v[36:39], v[140:143], v[172:175], v[36:39]
	v_mfma_f32_16x16x32_bf16 v[32:35], v[156:159], v[172:175], v[32:35]
	v_mfma_f32_16x16x32_bf16 v[20:23], v[140:143], v[180:183], v[20:23]
	v_mfma_f32_16x16x32_bf16 v[16:19], v[156:159], v[180:183], v[16:19]
	v_mfma_f32_16x16x32_bf16 v[4:7], v[140:143], v[188:191], v[4:7]
	v_mfma_f32_16x16x32_bf16 v[0:3], v[156:159], v[188:191], v[0:3]
	s_add_i32 s40, s40, 2
	s_add_u32 s13, s13, 0x100
	s_addc_u32 s37, s37, 0
	s_cmp_gt_u32 s40, 5
	s_mov_b64 s[20:21], s[6:7]
	s_setprio 0
	s_barrier
	s_cbranch_scc1 .Lgk_exit_2
.LBB0_1029:
	s_add_u32 s6, s20, 0x100
	s_addc_u32 s7, s21, 0
	s_add_i32 s42, 0, 0x10000
	s_cmp_eq_u32 s40, 4
	s_cselect_b32 s73, s15, s7
	s_cselect_b32 s72, s14, s6
	s_cselect_b32 s23, s17, s37
	s_cselect_b32 s22, s16, s13
	s_add_i32 s45, 0, 0x14000
	v_add_u32_e32 v128, s42, v241
	v_add_u32_e32 v156, s45, v241
	ds_read_b128 v[104:107], v128
	ds_read_b128 v[112:115], v128 offset:1024
	ds_read_b128 v[120:123], v128 offset:2048
	ds_read_b128 v[128:131], v128 offset:3072
	ds_read_b128 v[136:139], v156
	ds_read_b128 v[140:143], v156 offset:1024
	ds_read_b128 v[148:151], v156 offset:2048
	ds_read_b128 v[156:159], v156 offset:3072
	v_lshl_add_u64 v[194:195], s[20:21], 0, v[210:211]
	s_add_i32 m0, s19, 0xc000
	ds_read_b128 v[160:163], v243
	ds_read_b128 v[164:167], v243 offset:1024
	ds_read_b128 v[168:171], v243 offset:2048
	ds_read_b128 v[172:175], v243 offset:3072
	ds_read_b128 v[176:179], v243 offset:4096
	ds_read_b128 v[180:183], v243 offset:5120
	ds_read_b128 v[184:187], v243 offset:6144
	ds_read_b128 v[188:191], v243 offset:7168
	global_load_lds_dwordx4 v[194:195], off
	v_lshl_add_u64 v[194:195], s[20:21], 0, v[212:213]
	s_add_i32 m0, s19, 0xe000
	s_nop 0
	global_load_lds_dwordx4 v[194:195], off
	s_waitcnt vmcnt(8)
	s_waitcnt lgkmcnt(0)
	s_barrier
; #define PG8_STAGE(bufoff, gbase, voff) do { _Pragma("unroll") for (int _i = 0; _i < 2; ++_i) \
;         __builtin_amdgcn_global_load_lds((const unsigned*)((const char*)(gbase) + (voff)[_i]), (LAS unsigned*)(lds + (bufoff) + ldsw + _i * 8192), 16, 0, 0); } while (0)
; #define PG8_LDA(dst, b, h) do { _Pragma("unroll") for (int m = 0; m < 4; ++m) _Pragma("unroll") for (int k = 0; k < 2; ++k) dst[m][k] = *(const LAS bf16x8*)(lds + PG8_SA(b, h) + aoff + m * 2048 + k * 1024); } while (0)
; #define PG8_MMA(ai, bj, At, Bt) do { __builtin_amdgcn_s_setprio(1); _Pragma("unroll") for (int m = 0; m < 4; ++m) _Pragma("unroll") for (int n = 0; n < 2; ++n) _Pragma("unroll") for (int k = 0; k < 2; ++k) \
;         acc[ai][bj][m][n] = __builtin_amdgcn_mfma_f32_16x16x32_bf16(Bt[n][k], At[m][k], acc[ai][bj][m][n], 0, 0, 0); __builtin_amdgcn_s_setprio(0); } while (0)
; #define PG8_WAIT_V(n) asm volatile("s_waitcnt vmcnt(" #n ")" ::: "memory")
; #define PG8_WAIT_L(n) asm volatile("s_waitcnt lgkmcnt(" #n ")" ::: "memory")
; #define PG8_BAR __builtin_amdgcn_s_barrier()
; #define PG8_SCHED __builtin_amdgcn_sched_barrier(0)
; template <class Epi>
; __device__ __forceinline__ void gemm_phase(LAS unsigned char* lds, const Gemm g, const Sched& S, const Epi& E, const int tid) {
;     ...
;             PG8_WAIT_V(8); PG8_WAIT_L(0); PG8_BAR; PG8_MMA(0, 0, At, B0); PG8_MMA(0, 1, At, B1); PG8_BAR; PG8_SCHED;
;             PG8_LDA(At, 0, 1); PG8_STAGE(PG8_SB(0, 0), b2, voffB); PG8_STAGE(PG8_SB(0, 1), b2 + hB, voffB); PG8_STAGE(PG8_SA(0, 0), a2, voffA);
;             PG8_WAIT_V(8); PG8_WAIT_L(0); PG8_BAR; PG8_MMA(1, 0, At, B0); PG8_MMA(1, 1, At, B1); PG8_BAR; PG8_SCHED;
	s_setprio 1
	s_waitcnt lgkmcnt(0)
	v_mfma_f32_16x16x32_bf16 v[152:155], v[104:107], v[160:163], v[152:155]
	v_mfma_f32_16x16x32_bf16 v[144:147], v[120:123], v[160:163], v[144:147]
	v_mfma_f32_16x16x32_bf16 v[116:119], v[104:107], v[168:171], v[116:119]
	v_mfma_f32_16x16x32_bf16 v[108:111], v[120:123], v[168:171], v[108:111]
	v_mfma_f32_16x16x32_bf16 v[92:95], v[104:107], v[176:179], v[92:95]
	v_mfma_f32_16x16x32_bf16 v[88:91], v[120:123], v[176:179], v[88:91]
	v_mfma_f32_16x16x32_bf16 v[76:79], v[104:107], v[184:187], v[76:79]
	v_mfma_f32_16x16x32_bf16 v[72:75], v[120:123], v[184:187], v[72:75]
	v_mfma_f32_16x16x32_bf16 v[152:155], v[112:115], v[164:167], v[152:155]
	v_mfma_f32_16x16x32_bf16 v[144:147], v[128:131], v[164:167], v[144:147]
	v_mfma_f32_16x16x32_bf16 v[116:119], v[112:115], v[172:175], v[116:119]
	v_mfma_f32_16x16x32_bf16 v[108:111], v[128:131], v[172:175], v[108:111]
	v_mfma_f32_16x16x32_bf16 v[92:95], v[112:115], v[180:183], v[92:95]
	v_mfma_f32_16x16x32_bf16 v[88:91], v[128:131], v[180:183], v[88:91]
	v_mfma_f32_16x16x32_bf16 v[76:79], v[112:115], v[188:191], v[76:79]
	v_mfma_f32_16x16x32_bf16 v[72:75], v[128:131], v[188:191], v[72:75]
	v_mfma_f32_16x16x32_bf16 v[132:135], v[136:139], v[160:163], v[132:135]
	v_mfma_f32_16x16x32_bf16 v[124:127], v[148:151], v[160:163], v[124:127]
	v_mfma_f32_16x16x32_bf16 v[100:103], v[136:139], v[168:171], v[100:103]
	v_mfma_f32_16x16x32_bf16 v[96:99], v[148:151], v[168:171], v[96:99]
	v_mfma_f32_16x16x32_bf16 v[84:87], v[136:139], v[176:179], v[84:87]
	v_mfma_f32_16x16x32_bf16 v[80:83], v[148:151], v[176:179], v[80:83]
	v_mfma_f32_16x16x32_bf16 v[68:71], v[136:139], v[184:187], v[68:71]
	v_mfma_f32_16x16x32_bf16 v[64:67], v[148:151], v[184:187], v[64:67]
	v_mfma_f32_16x16x32_bf16 v[132:135], v[140:143], v[164:167], v[132:135]
	v_mfma_f32_16x16x32_bf16 v[124:127], v[156:159], v[164:167], v[124:127]
	v_mfma_f32_16x16x32_bf16 v[100:103], v[140:143], v[172:175], v[100:103]
	v_mfma_f32_16x16x32_bf16 v[96:99], v[156:159], v[172:175], v[96:99]
	v_mfma_f32_16x16x32_bf16 v[84:87], v[140:143], v[180:183], v[84:87]
	v_mfma_f32_16x16x32_bf16 v[80:83], v[156:159], v[180:183], v[80:83]
	v_mfma_f32_16x16x32_bf16 v[68:71], v[140:143], v[188:191], v[68:71]
	v_mfma_f32_16x16x32_bf16 v[64:67], v[156:159], v[188:191], v[64:67]
	s_setprio 0
	s_barrier
	s_add_i32 s20, s42, s35
	v_lshl_add_u64 v[194:195], s[22:23], 0, v[192:193]
	s_mov_b32 m0, s20
	ds_read_b128 v[160:163], v243 offset:16384
	ds_read_b128 v[164:167], v243 offset:17408
	ds_read_b128 v[168:171], v243 offset:18432
	ds_read_b128 v[172:175], v243 offset:19456
	ds_read_b128 v[176:179], v243 offset:20480
	ds_read_b128 v[180:183], v243 offset:21504
	ds_read_b128 v[184:187], v243 offset:22528
	ds_read_b128 v[188:191], v243 offset:23552
	global_load_lds_dwordx4 v[194:195], off
	s_add_i32 m0, s20, 0x2000
	s_add_u32 s20, s22, 0x20000
	v_lshl_add_u64 v[196:197], s[22:23], 0, v[208:209]
	s_addc_u32 s21, s23, 0
	s_add_i32 s42, s45, s35
	global_load_lds_dwordx4 v[196:197], off
	v_lshl_add_u64 v[198:199], s[20:21], 0, v[192:193]
	s_mov_b32 m0, s42
	v_lshl_add_u64 v[200:201], s[72:73], 0, v[206:207]
	global_load_lds_dwordx4 v[198:199], off
	v_lshl_add_u64 v[198:199], s[20:21], 0, v[208:209]
	s_add_i32 m0, s42, 0x2000
	s_nop 0
	global_load_lds_dwordx4 v[198:199], off
	v_lshl_add_u64 v[198:199], s[72:73], 0, v[204:205]
	s_mov_b32 m0, s19
	s_nop 0
	global_load_lds_dwordx4 v[198:199], off
	s_mov_b32 m0, s74
	s_nop 0
	global_load_lds_dwordx4 v[200:201], off
	s_waitcnt vmcnt(8)
	s_waitcnt lgkmcnt(0)
	s_barrier
	s_setprio 1
	s_waitcnt lgkmcnt(0)
	v_mfma_f32_16x16x32_bf16 v[60:63], v[104:107], v[160:163], v[60:63]
	v_mfma_f32_16x16x32_bf16 v[56:59], v[120:123], v[160:163], v[56:59]
	v_mfma_f32_16x16x32_bf16 v[44:47], v[104:107], v[168:171], v[44:47]
	v_mfma_f32_16x16x32_bf16 v[40:43], v[120:123], v[168:171], v[40:43]
	v_mfma_f32_16x16x32_bf16 v[28:31], v[104:107], v[176:179], v[28:31]
	v_mfma_f32_16x16x32_bf16 v[24:27], v[120:123], v[176:179], v[24:27]
	v_mfma_f32_16x16x32_bf16 v[12:15], v[104:107], v[184:187], v[12:15]
	v_mfma_f32_16x16x32_bf16 v[8:11], v[120:123], v[184:187], v[8:11]
	v_mfma_f32_16x16x32_bf16 v[60:63], v[112:115], v[164:167], v[60:63]
	v_mfma_f32_16x16x32_bf16 v[56:59], v[128:131], v[164:167], v[56:59]
	v_mfma_f32_16x16x32_bf16 v[44:47], v[112:115], v[172:175], v[44:47]
	v_mfma_f32_16x16x32_bf16 v[40:43], v[128:131], v[172:175], v[40:43]
	v_mfma_f32_16x16x32_bf16 v[28:31], v[112:115], v[180:183], v[28:31]
	v_mfma_f32_16x16x32_bf16 v[24:27], v[128:131], v[180:183], v[24:27]
	v_mfma_f32_16x16x32_bf16 v[12:15], v[112:115], v[188:191], v[12:15]
	v_mfma_f32_16x16x32_bf16 v[8:11], v[128:131], v[188:191], v[8:11]
	v_mfma_f32_16x16x32_bf16 v[52:55], v[136:139], v[160:163], v[52:55]
	v_mfma_f32_16x16x32_bf16 v[48:51], v[148:151], v[160:163], v[48:51]
	v_mfma_f32_16x16x32_bf16 v[36:39], v[136:139], v[168:171], v[36:39]
	v_mfma_f32_16x16x32_bf16 v[32:35], v[148:151], v[168:171], v[32:35]
	v_mfma_f32_16x16x32_bf16 v[20:23], v[136:139], v[176:179], v[20:23]
	v_mfma_f32_16x16x32_bf16 v[16:19], v[148:151], v[176:179], v[16:19]
	v_mfma_f32_16x16x32_bf16 v[4:7], v[136:139], v[184:187], v[4:7]
	v_mfma_f32_16x16x32_bf16 v[0:3], v[148:151], v[184:187], v[0:3]
	v_mfma_f32_16x16x32_bf16 v[52:55], v[140:143], v[164:167], v[52:55]
	v_mfma_f32_16x16x32_bf16 v[48:51], v[156:159], v[164:167], v[48:51]
	v_mfma_f32_16x16x32_bf16 v[36:39], v[140:143], v[172:175], v[36:39]
	v_mfma_f32_16x16x32_bf16 v[32:35], v[156:159], v[172:175], v[32:35]
	v_mfma_f32_16x16x32_bf16 v[20:23], v[140:143], v[180:183], v[20:23]
	v_mfma_f32_16x16x32_bf16 v[16:19], v[156:159], v[180:183], v[16:19]
	v_mfma_f32_16x16x32_bf16 v[4:7], v[140:143], v[188:191], v[4:7]
	v_mfma_f32_16x16x32_bf16 v[0:3], v[156:159], v[188:191], v[0:3]
	s_setprio 0
	s_barrier
; #define PG8_STAGE(bufoff, gbase, voff) do { _Pragma("unroll") for (int _i = 0; _i < 2; ++_i) \
;         __builtin_amdgcn_global_load_lds((const unsigned*)((const char*)(gbase) + (voff)[_i]), (LAS unsigned*)(lds + (bufoff) + ldsw + _i * 8192), 16, 0, 0); } while (0)
; #define PG8_LDA(dst, b, h) do { _Pragma("unroll") for (int m = 0; m < 4; ++m) _Pragma("unroll") for (int k = 0; k < 2; ++k) dst[m][k] = *(const LAS bf16x8*)(lds + PG8_SA(b, h) + aoff + m * 2048 + k * 1024); } while (0)
; #define PG8_LDB(dst, b, h) do { _Pragma("unroll") for (int n = 0; n < 2; ++n) _Pragma("unroll") for (int k = 0; k < 2; ++k) dst[n][k] = *(const LAS bf16x8*)(lds + PG8_SB(b, h) + boff + n * 2048 + k * 1024); } while (0)
; #define PG8_MMA(ai, bj, At, Bt) do { __builtin_amdgcn_s_setprio(1); _Pragma("unroll") for (int m = 0; m < 4; ++m) _Pragma("unroll") for (int n = 0; n < 2; ++n) _Pragma("unroll") for (int k = 0; k < 2; ++k) \
;         acc[ai][bj][m][n] = __builtin_amdgcn_mfma_f32_16x16x32_bf16(Bt[n][k], At[m][k], acc[ai][bj][m][n], 0, 0, 0); __builtin_amdgcn_s_setprio(0); } while (0)
; #define PG8_WAIT_V(n) asm volatile("s_waitcnt vmcnt(" #n ")" ::: "memory")
; #define PG8_WAIT_L(n) asm volatile("s_waitcnt lgkmcnt(" #n ")" ::: "memory")
; #define PG8_BAR __builtin_amdgcn_s_barrier()
; #define PG8_SCHED __builtin_amdgcn_sched_barrier(0)
; template <class Epi>
; __device__ __forceinline__ void gemm_phase(LAS unsigned char* lds, const Gemm g, const Sched& S, const Epi& E, const int tid) {
;     ...
;             PG8_LDB(B0, 1, 0); PG8_LDB(B1, 1, 1); PG8_SCHED; PG8_LDA(At, 1, 0); PG8_STAGE(PG8_SA(0, 1), a2 + hA, voffA);
;             PG8_WAIT_V(8); PG8_WAIT_L(0); PG8_BAR; PG8_MMA(0, 0, At, B0); PG8_MMA(0, 1, At, B1); PG8_BAR; PG8_SCHED;
	s_add_i32 s42, 0, 0x18000
	s_add_i32 s45, 0, 0x1c000
	v_add_u32_e32 v128, s42, v241
	v_add_u32_e32 v156, s45, v241
	ds_read_b128 v[104:107], v128
	ds_read_b128 v[112:115], v128 offset:1024
	ds_read_b128 v[120:123], v128 offset:2048
	ds_read_b128 v[128:131], v128 offset:3072
	ds_read_b128 v[136:139], v156
	ds_read_b128 v[140:143], v156 offset:1024
	ds_read_b128 v[148:151], v156 offset:2048
	ds_read_b128 v[156:159], v156 offset:3072
	s_add_u32 s20, s72, 0x120000
	s_addc_u32 s21, s73, 0
	s_mov_b32 m0, s75
	v_lshl_add_u64 v[214:215], s[20:21], 0, v[204:205]
	ds_read_b128 v[160:163], v243 offset:32768
	ds_read_b128 v[164:167], v243 offset:33792
	ds_read_b128 v[168:171], v243 offset:34816
	ds_read_b128 v[172:175], v243 offset:35840
	ds_read_b128 v[176:179], v243 offset:36864
	ds_read_b128 v[180:183], v243 offset:37888
	ds_read_b128 v[184:187], v243 offset:38912
	ds_read_b128 v[188:191], v243 offset:39936
	global_load_lds_dwordx4 v[214:215], off
	v_lshl_add_u64 v[214:215], s[20:21], 0, v[206:207]
	s_mov_b32 m0, s76
	s_nop 0
	global_load_lds_dwordx4 v[214:215], off
	s_waitcnt vmcnt(8)
	s_waitcnt lgkmcnt(0)
	s_barrier
	s_setprio 1
	s_waitcnt lgkmcnt(0)
	v_mfma_f32_16x16x32_bf16 v[152:155], v[104:107], v[160:163], v[152:155]
	v_mfma_f32_16x16x32_bf16 v[144:147], v[120:123], v[160:163], v[144:147]
	v_mfma_f32_16x16x32_bf16 v[116:119], v[104:107], v[168:171], v[116:119]
	v_mfma_f32_16x16x32_bf16 v[108:111], v[120:123], v[168:171], v[108:111]
	v_mfma_f32_16x16x32_bf16 v[92:95], v[104:107], v[176:179], v[92:95]
	v_mfma_f32_16x16x32_bf16 v[88:91], v[120:123], v[176:179], v[88:91]
	v_mfma_f32_16x16x32_bf16 v[76:79], v[104:107], v[184:187], v[76:79]
	v_mfma_f32_16x16x32_bf16 v[72:75], v[120:123], v[184:187], v[72:75]
	v_mfma_f32_16x16x32_bf16 v[152:155], v[112:115], v[164:167], v[152:155]
	v_mfma_f32_16x16x32_bf16 v[144:147], v[128:131], v[164:167], v[144:147]
	v_mfma_f32_16x16x32_bf16 v[116:119], v[112:115], v[172:175], v[116:119]
	v_mfma_f32_16x16x32_bf16 v[108:111], v[128:131], v[172:175], v[108:111]
	v_mfma_f32_16x16x32_bf16 v[92:95], v[112:115], v[180:183], v[92:95]
	v_mfma_f32_16x16x32_bf16 v[88:91], v[128:131], v[180:183], v[88:91]
	v_mfma_f32_16x16x32_bf16 v[76:79], v[112:115], v[188:191], v[76:79]
	v_mfma_f32_16x16x32_bf16 v[72:75], v[128:131], v[188:191], v[72:75]
	v_mfma_f32_16x16x32_bf16 v[132:135], v[136:139], v[160:163], v[132:135]
	v_mfma_f32_16x16x32_bf16 v[124:127], v[148:151], v[160:163], v[124:127]
	v_mfma_f32_16x16x32_bf16 v[100:103], v[136:139], v[168:171], v[100:103]
	v_mfma_f32_16x16x32_bf16 v[96:99], v[148:151], v[168:171], v[96:99]
	v_mfma_f32_16x16x32_bf16 v[84:87], v[136:139], v[176:179], v[84:87]
	v_mfma_f32_16x16x32_bf16 v[80:83], v[148:151], v[176:179], v[80:83]
	v_mfma_f32_16x16x32_bf16 v[68:71], v[136:139], v[184:187], v[68:71]
	v_mfma_f32_16x16x32_bf16 v[64:67], v[148:151], v[184:187], v[64:67]
	v_mfma_f32_16x16x32_bf16 v[132:135], v[140:143], v[164:167], v[132:135]
	v_mfma_f32_16x16x32_bf16 v[124:127], v[156:159], v[164:167], v[124:127]
	v_mfma_f32_16x16x32_bf16 v[100:103], v[140:143], v[172:175], v[100:103]
	v_mfma_f32_16x16x32_bf16 v[96:99], v[156:159], v[172:175], v[96:99]
	v_mfma_f32_16x16x32_bf16 v[84:87], v[140:143], v[180:183], v[84:87]
	v_mfma_f32_16x16x32_bf16 v[80:83], v[156:159], v[180:183], v[80:83]
	v_mfma_f32_16x16x32_bf16 v[68:71], v[140:143], v[188:191], v[68:71]
	v_mfma_f32_16x16x32_bf16 v[64:67], v[156:159], v[188:191], v[64:67]
	s_setprio 0
	s_barrier
; #define PG8_STAGE(bufoff, gbase, voff) do { _Pragma("unroll") for (int _i = 0; _i < 2; ++_i) \
;         __builtin_amdgcn_global_load_lds((const unsigned*)((const char*)(gbase) + (voff)[_i]), (LAS unsigned*)(lds + (bufoff) + ldsw + _i * 8192), 16, 0, 0); } while (0)
; #define PG8_LDA(dst, b, h) do { _Pragma("unroll") for (int m = 0; m < 4; ++m) _Pragma("unroll") for (int k = 0; k < 2; ++k) dst[m][k] = *(const LAS bf16x8*)(lds + PG8_SA(b, h) + aoff + m * 2048 + k * 1024); } while (0)
; #define PG8_MMA(ai, bj, At, Bt) do { __builtin_amdgcn_s_setprio(1); _Pragma("unroll") for (int m = 0; m < 4; ++m) _Pragma("unroll") for (int n = 0; n < 2; ++n) _Pragma("unroll") for (int k = 0; k < 2; ++k) \
;         acc[ai][bj][m][n] = __builtin_amdgcn_mfma_f32_16x16x32_bf16(Bt[n][k], At[m][k], acc[ai][bj][m][n], 0, 0, 0); __builtin_amdgcn_s_setprio(0); } while (0)
; #define PG8_WAIT_V(n) asm volatile("s_waitcnt vmcnt(" #n ")" ::: "memory")
; #define PG8_WAIT_L(n) asm volatile("s_waitcnt lgkmcnt(" #n ")" ::: "memory")
; #define PG8_BAR __builtin_amdgcn_s_barrier()
; #define PG8_SCHED __builtin_amdgcn_sched_barrier(0)
; template <class Epi>
; __device__ __forceinline__ void gemm_phase(LAS unsigned char* lds, const Gemm g, const Sched& S, const Epi& E, const int tid) {
;     ...
;         for (int t = 0; t < nt; t += 2) {
;     ...
;             PG8_LDA(At, 1, 1); PG8_STAGE(PG8_SB(1, 0), b3, voffB); PG8_STAGE(PG8_SB(1, 1), b3 + hB, voffB); PG8_STAGE(PG8_SA(1, 0), a3, voffA);
;             PG8_WAIT_V(8); PG8_WAIT_L(0); PG8_BAR; PG8_MMA(1, 0, At, B0); PG8_MMA(1, 1, At, B1); PG8_BAR; PG8_SCHED;
;         }
	s_add_i32 s20, s42, s35
	v_lshl_add_u64 v[194:195], v[194:195], 0, s[94:95]
	s_mov_b32 m0, s20
	ds_read_b128 v[160:163], v243 offset:49152
	ds_read_b128 v[164:167], v243 offset:50176
	ds_read_b128 v[168:171], v243 offset:51200
	ds_read_b128 v[172:175], v243 offset:52224
	ds_read_b128 v[176:179], v243 offset:53248
	ds_read_b128 v[180:183], v243 offset:54272
	ds_read_b128 v[184:187], v243 offset:55296
	ds_read_b128 v[188:191], v243 offset:56320
	global_load_lds_dwordx4 v[194:195], off
	s_add_i32 m0, s20, 0x2000
	s_add_u32 s20, s22, 0x20080
	v_lshl_add_u64 v[194:195], v[196:197], 0, s[94:95]
	s_addc_u32 s21, s23, 0
	s_add_i32 s22, s45, s35
	global_load_lds_dwordx4 v[194:195], off
	v_lshl_add_u64 v[194:195], s[20:21], 0, v[192:193]
	s_mov_b32 m0, s22
	s_nop 0
	global_load_lds_dwordx4 v[194:195], off
	v_lshl_add_u64 v[194:195], s[20:21], 0, v[208:209]
	s_add_i32 m0, s22, 0x2000
	s_nop 0
	global_load_lds_dwordx4 v[194:195], off
	v_lshl_add_u64 v[194:195], v[198:199], 0, s[94:95]
	s_mov_b32 m0, s77
	s_nop 0
	global_load_lds_dwordx4 v[194:195], off
	v_lshl_add_u64 v[194:195], v[200:201], 0, s[94:95]
	s_mov_b32 m0, s78
	s_nop 0
	global_load_lds_dwordx4 v[194:195], off
	s_waitcnt vmcnt(8)
	s_waitcnt lgkmcnt(0)
	s_barrier
	s_setprio 1
	s_waitcnt lgkmcnt(0)
	v_mfma_f32_16x16x32_bf16 v[60:63], v[104:107], v[160:163], v[60:63]
	v_mfma_f32_16x16x32_bf16 v[56:59], v[120:123], v[160:163], v[56:59]
	v_mfma_f32_16x16x32_bf16 v[44:47], v[104:107], v[168:171], v[44:47]
	v_mfma_f32_16x16x32_bf16 v[40:43], v[120:123], v[168:171], v[40:43]
	v_mfma_f32_16x16x32_bf16 v[28:31], v[104:107], v[176:179], v[28:31]
	v_mfma_f32_16x16x32_bf16 v[24:27], v[120:123], v[176:179], v[24:27]
	v_mfma_f32_16x16x32_bf16 v[12:15], v[104:107], v[184:187], v[12:15]
	v_mfma_f32_16x16x32_bf16 v[8:11], v[120:123], v[184:187], v[8:11]
	v_mfma_f32_16x16x32_bf16 v[60:63], v[112:115], v[164:167], v[60:63]
	v_mfma_f32_16x16x32_bf16 v[56:59], v[128:131], v[164:167], v[56:59]
	v_mfma_f32_16x16x32_bf16 v[44:47], v[112:115], v[172:175], v[44:47]
	v_mfma_f32_16x16x32_bf16 v[40:43], v[128:131], v[172:175], v[40:43]
	v_mfma_f32_16x16x32_bf16 v[28:31], v[112:115], v[180:183], v[28:31]
	v_mfma_f32_16x16x32_bf16 v[24:27], v[128:131], v[180:183], v[24:27]
	v_mfma_f32_16x16x32_bf16 v[12:15], v[112:115], v[188:191], v[12:15]
	v_mfma_f32_16x16x32_bf16 v[8:11], v[128:131], v[188:191], v[8:11]
	v_mfma_f32_16x16x32_bf16 v[52:55], v[136:139], v[160:163], v[52:55]
	v_mfma_f32_16x16x32_bf16 v[48:51], v[148:151], v[160:163], v[48:51]
	v_mfma_f32_16x16x32_bf16 v[36:39], v[136:139], v[168:171], v[36:39]
	v_mfma_f32_16x16x32_bf16 v[32:35], v[148:151], v[168:171], v[32:35]
	v_mfma_f32_16x16x32_bf16 v[20:23], v[136:139], v[176:179], v[20:23]
	v_mfma_f32_16x16x32_bf16 v[16:19], v[148:151], v[176:179], v[16:19]
	v_mfma_f32_16x16x32_bf16 v[4:7], v[136:139], v[184:187], v[4:7]
	v_mfma_f32_16x16x32_bf16 v[0:3], v[148:151], v[184:187], v[0:3]
	v_mfma_f32_16x16x32_bf16 v[52:55], v[140:143], v[164:167], v[52:55]
	v_mfma_f32_16x16x32_bf16 v[48:51], v[156:159], v[164:167], v[48:51]
	v_mfma_f32_16x16x32_bf16 v[36:39], v[140:143], v[172:175], v[36:39]
	v_mfma_f32_16x16x32_bf16 v[32:35], v[156:159], v[172:175], v[32:35]
	v_mfma_f32_16x16x32_bf16 v[20:23], v[140:143], v[180:183], v[20:23]
	v_mfma_f32_16x16x32_bf16 v[16:19], v[156:159], v[180:183], v[16:19]
	v_mfma_f32_16x16x32_bf16 v[4:7], v[140:143], v[188:191], v[4:7]
	v_mfma_f32_16x16x32_bf16 v[0:3], v[156:159], v[188:191], v[0:3]
	s_add_i32 s40, s40, 2
	s_add_u32 s13, s13, 0x100
	s_addc_u32 s37, s37, 0
	s_cmp_gt_u32 s40, 5
	s_mov_b64 s[20:21], s[6:7]
	s_setprio 0
	s_barrier
	s_cbranch_scc0 .LBB0_1029

; #define PG8_STAGE(bufoff, gbase, voff) do { _Pragma("unroll") for (int _i = 0; _i < 2; ++_i) \
;         __builtin_amdgcn_global_load_lds((const unsigned*)((const char*)(gbase) + (voff)[_i]), (LAS unsigned*)(lds + (bufoff) + ldsw + _i * 8192), 16, 0, 0); } while (0)
; #define PG8_LDA(dst, b, h) do { _Pragma("unroll") for (int m = 0; m < 4; ++m) _Pragma("unroll") for (int k = 0; k < 2; ++k) dst[m][k] = *(const LAS bf16x8*)(lds + PG8_SA(b, h) + aoff + m * 2048 + k * 1024); } while (0)
; #define PG8_LDB(dst, b, h) do { _Pragma("unroll") for (int n = 0; n < 2; ++n) _Pragma("unroll") for (int k = 0; k < 2; ++k) dst[n][k] = *(const LAS bf16x8*)(lds + PG8_SB(b, h) + boff + n * 2048 + k * 1024); } while (0)
; #define PG8_WAIT_V(n) asm volatile("s_waitcnt vmcnt(" #n ")" ::: "memory")
; #define PG8_BAR __builtin_amdgcn_s_barrier()
; template <class Epi>
; __device__ __forceinline__ void gemm_phase(LAS unsigned char* lds, const Gemm g, const Sched& S, const Epi& E, const int tid) {
;     ...
;     PG8_STAGE(PG8_SB(0, 0), cB, voffB); PG8_STAGE(PG8_SB(0, 1), cB + hB, voffB); PG8_STAGE(PG8_SA(0, 0), cA, voffA); PG8_STAGE(PG8_SA(0, 1), cA + hA, voffA);
;     if (wr == 1) PG8_BAR;
;     PG8_WAIT_V(2); PG8_BAR;
;     PG8_STAGE(PG8_SB(1, 0), cB + kstep, voffB); PG8_STAGE(PG8_SA(1, 0), cA + kstep, voffA); PG8_STAGE(PG8_SB(1, 1), cB + hB + kstep, voffB);
;     PG8_WAIT_V(6); PG8_BAR;
;     for (;;) {
;         const bool has_next = S.next(ui + 1, nxt);
;         const char* nA = cA; const char* nB = cB; if (has_next) S.ptrs(nxt, nA, nB);
;         for (int t = 0; t < nt; t += 2) {
;             const bool last = (t == nt - 2);
;             const char* a1 = cA + (size_t)(t + 1) * kstep;
;             const char* a2 = last ? nA : cA + (size_t)(t + 2) * kstep; const char* b2 = last ? nB : cB + (size_t)(t + 2) * kstep;
;             const char* a3 = a2 + kstep; const char* b3 = b2 + kstep;
;             PG8_LDB(B0, 0, 0); PG8_LDB(B1, 0, 1); PG8_SCHED; PG8_LDA(At, 0, 0); PG8_STAGE(PG8_SA(1, 1), a1 + hA, voffA);
;             PG8_WAIT_V(8); PG8_WAIT_L(0); PG8_BAR; PG8_MMA(0, 0, At, B0); PG8_MMA(0, 1, At, B1); PG8_BAR; PG8_SCHED;
;             PG8_LDA(At, 0, 1); PG8_STAGE(PG8_SB(0, 0), b2, voffB); PG8_STAGE(PG8_SB(0, 1), b2 + hB, voffB); PG8_STAGE(PG8_SA(0, 0), a2, voffA);
;             PG8_WAIT_V(8); PG8_WAIT_L(0); PG8_BAR; PG8_MMA(1, 0, At, B0); PG8_MMA(1, 1, At, B1); PG8_BAR; PG8_SCHED;
.LBB0_1142:
	s_add_u32 s17, s22, 0x100
	s_addc_u32 vcc_lo, s23, 0
	s_mov_b32 vcc_hi, -2
	s_add_u32 s22, s20, 0x100
	s_addc_u32 s23, s21, 0
	s_add_i32 s43, 0, 0x10000
	s_cmp_eq_u32 vcc_hi, 12
	s_cselect_b32 s75, s7, s23
	s_cselect_b32 s74, s6, s22
	s_cselect_b32 s73, s19, vcc_lo
	s_cselect_b32 s72, s18, s17
	s_add_i32 s44, 0, 0x14000
	v_add_u32_e32 v100, s43, v159
	v_add_u32_e32 v170, s44, v159
	ds_read_b128 v[64:67], v100
	ds_read_b128 v[68:71], v100 offset:1024
	ds_read_b128 v[72:75], v100 offset:2048
	ds_read_b128 v[100:103], v100 offset:3072
	ds_read_b128 v[154:157], v170
	ds_read_b128 v[162:165], v170 offset:1024
	ds_read_b128 v[166:169], v170 offset:2048
	ds_read_b128 v[170:173], v170 offset:3072
	v_lshl_add_u64 v[190:191], s[20:21], 0, v[150:151]
	s_add_i32 m0, s80, 0xc000
	ds_read_b128 v[174:177], v161
	ds_read_b128 v[178:181], v161 offset:1024
	ds_read_b128 v[182:185], v161 offset:2048
	ds_read_b128 v[186:189], v161 offset:3072
	ds_read_b128 v[194:197], v161 offset:4096
	ds_read_b128 v[198:201], v161 offset:5120
	ds_read_b128 v[204:207], v161 offset:6144
	ds_read_b128 v[208:211], v161 offset:7168
	global_load_lds_dwordx4 v[190:191], off
	v_lshl_add_u64 v[190:191], s[20:21], 0, v[152:153]
	s_add_i32 m0, s80, 0xe000
	s_nop 0
	global_load_lds_dwordx4 v[190:191], off
	s_waitcnt vmcnt(8)
	s_waitcnt lgkmcnt(0)
	s_barrier
	s_setprio 1
	s_waitcnt lgkmcnt(0)
	v_mfma_f32_16x16x32_bf16 v[140:143], v[64:67], v[174:177], 0
	v_mfma_f32_16x16x32_bf16 v[136:139], v[72:75], v[174:177], 0
	v_mfma_f32_16x16x32_bf16 v[132:135], v[64:67], v[182:185], 0
	v_mfma_f32_16x16x32_bf16 v[120:123], v[72:75], v[182:185], 0
	v_mfma_f32_16x16x32_bf16 v[108:111], v[64:67], v[194:197], 0
	v_mfma_f32_16x16x32_bf16 v[104:107], v[72:75], v[194:197], 0
	v_mfma_f32_16x16x32_bf16 v[96:99], v[64:67], v[204:207], 0
	v_mfma_f32_16x16x32_bf16 v[84:87], v[72:75], v[204:207], 0
	v_mfma_f32_16x16x32_bf16 v[140:143], v[68:71], v[178:181], v[140:143]
	v_mfma_f32_16x16x32_bf16 v[136:139], v[100:103], v[178:181], v[136:139]
	v_mfma_f32_16x16x32_bf16 v[132:135], v[68:71], v[186:189], v[132:135]
	v_mfma_f32_16x16x32_bf16 v[120:123], v[100:103], v[186:189], v[120:123]
	v_mfma_f32_16x16x32_bf16 v[108:111], v[68:71], v[198:201], v[108:111]
	v_mfma_f32_16x16x32_bf16 v[104:107], v[100:103], v[198:201], v[104:107]
	v_mfma_f32_16x16x32_bf16 v[96:99], v[68:71], v[208:211], v[96:99]
	v_mfma_f32_16x16x32_bf16 v[84:87], v[100:103], v[208:211], v[84:87]
	v_mfma_f32_16x16x32_bf16 v[128:131], v[154:157], v[174:177], 0
	v_mfma_f32_16x16x32_bf16 v[124:127], v[166:169], v[174:177], 0
	v_mfma_f32_16x16x32_bf16 v[116:119], v[154:157], v[182:185], 0
	v_mfma_f32_16x16x32_bf16 v[112:115], v[166:169], v[182:185], 0
	v_mfma_f32_16x16x32_bf16 v[92:95], v[154:157], v[194:197], 0
	v_mfma_f32_16x16x32_bf16 v[88:91], v[166:169], v[194:197], 0
	v_mfma_f32_16x16x32_bf16 v[80:83], v[154:157], v[204:207], 0
	v_mfma_f32_16x16x32_bf16 v[76:79], v[166:169], v[204:207], 0
	v_mfma_f32_16x16x32_bf16 v[128:131], v[162:165], v[178:181], v[128:131]
	v_mfma_f32_16x16x32_bf16 v[124:127], v[170:173], v[178:181], v[124:127]
	v_mfma_f32_16x16x32_bf16 v[116:119], v[162:165], v[186:189], v[116:119]
	v_mfma_f32_16x16x32_bf16 v[112:115], v[170:173], v[186:189], v[112:115]
	v_mfma_f32_16x16x32_bf16 v[92:95], v[162:165], v[198:201], v[92:95]
	v_mfma_f32_16x16x32_bf16 v[88:91], v[170:173], v[198:201], v[88:91]
	v_mfma_f32_16x16x32_bf16 v[80:83], v[162:165], v[208:211], v[80:83]
	v_mfma_f32_16x16x32_bf16 v[76:79], v[170:173], v[208:211], v[76:79]
	s_setprio 0
	s_barrier
	s_add_i32 s20, s43, s76
	v_lshl_add_u64 v[190:191], s[72:73], 0, v[192:193]
	s_mov_b32 m0, s20
	ds_read_b128 v[174:177], v161 offset:16384
	ds_read_b128 v[178:181], v161 offset:17408
	ds_read_b128 v[182:185], v161 offset:18432
	ds_read_b128 v[186:189], v161 offset:19456
	ds_read_b128 v[194:197], v161 offset:20480
	ds_read_b128 v[198:201], v161 offset:21504
	ds_read_b128 v[204:207], v161 offset:22528
	ds_read_b128 v[208:211], v161 offset:23552
	global_load_lds_dwordx4 v[190:191], off
	s_add_i32 m0, s20, 0x2000
	s_add_u32 s20, s72, 0x40000
	v_lshl_add_u64 v[212:213], s[72:73], 0, v[144:145]
	s_addc_u32 s21, s73, 0
	s_add_i32 s43, s44, s76
	global_load_lds_dwordx4 v[212:213], off
	v_lshl_add_u64 v[214:215], s[20:21], 0, v[192:193]
	s_mov_b32 m0, s43
	v_lshl_add_u64 v[216:217], s[74:75], 0, v[146:147]
	global_load_lds_dwordx4 v[214:215], off
	v_lshl_add_u64 v[214:215], s[20:21], 0, v[144:145]
	s_add_i32 m0, s43, 0x2000
	s_nop 0
	global_load_lds_dwordx4 v[214:215], off
	v_lshl_add_u64 v[214:215], s[74:75], 0, v[148:149]
	s_mov_b32 m0, s80
	s_nop 0
	global_load_lds_dwordx4 v[214:215], off
	s_mov_b32 m0, s81
	s_nop 0
	global_load_lds_dwordx4 v[216:217], off
	s_waitcnt vmcnt(8)
	s_waitcnt lgkmcnt(0)
	s_barrier
; #define PG8_STAGE(bufoff, gbase, voff) do { _Pragma("unroll") for (int _i = 0; _i < 2; ++_i) \
;         __builtin_amdgcn_global_load_lds((const unsigned*)((const char*)(gbase) + (voff)[_i]), (LAS unsigned*)(lds + (bufoff) + ldsw + _i * 8192), 16, 0, 0); } while (0)
; #define PG8_LDA(dst, b, h) do { _Pragma("unroll") for (int m = 0; m < 4; ++m) _Pragma("unroll") for (int k = 0; k < 2; ++k) dst[m][k] = *(const LAS bf16x8*)(lds + PG8_SA(b, h) + aoff + m * 2048 + k * 1024); } while (0)
; #define PG8_LDB(dst, b, h) do { _Pragma("unroll") for (int n = 0; n < 2; ++n) _Pragma("unroll") for (int k = 0; k < 2; ++k) dst[n][k] = *(const LAS bf16x8*)(lds + PG8_SB(b, h) + boff + n * 2048 + k * 1024); } while (0)
; #define PG8_MMA(ai, bj, At, Bt) do { __builtin_amdgcn_s_setprio(1); _Pragma("unroll") for (int m = 0; m < 4; ++m) _Pragma("unroll") for (int n = 0; n < 2; ++n) _Pragma("unroll") for (int k = 0; k < 2; ++k) \
;         acc[ai][bj][m][n] = __builtin_amdgcn_mfma_f32_16x16x32_bf16(Bt[n][k], At[m][k], acc[ai][bj][m][n], 0, 0, 0); __builtin_amdgcn_s_setprio(0); } while (0)
; #define PG8_WAIT_V(n) asm volatile("s_waitcnt vmcnt(" #n ")" ::: "memory")
; #define PG8_WAIT_L(n) asm volatile("s_waitcnt lgkmcnt(" #n ")" ::: "memory")
; #define PG8_BAR __builtin_amdgcn_s_barrier()
; #define PG8_SCHED __builtin_amdgcn_sched_barrier(0)
; template <class Epi>
; __device__ __forceinline__ void gemm_phase(LAS unsigned char* lds, const Gemm g, const Sched& S, const Epi& E, const int tid) {
;     ...
;             PG8_WAIT_V(8); PG8_WAIT_L(0); PG8_BAR; PG8_MMA(1, 0, At, B0); PG8_MMA(1, 1, At, B1); PG8_BAR; PG8_SCHED;
;             PG8_LDB(B0, 1, 0); PG8_LDB(B1, 1, 1); PG8_SCHED; PG8_LDA(At, 1, 0); PG8_STAGE(PG8_SA(0, 1), a2 + hA, voffA);
;             PG8_WAIT_V(8); PG8_WAIT_L(0); PG8_BAR; PG8_MMA(0, 0, At, B0); PG8_MMA(0, 1, At, B1); PG8_BAR; PG8_SCHED;
	s_setprio 1
	s_waitcnt lgkmcnt(0)
	v_mfma_f32_16x16x32_bf16 v[60:63], v[64:67], v[174:177], 0
	v_mfma_f32_16x16x32_bf16 v[56:59], v[72:75], v[174:177], 0
	v_mfma_f32_16x16x32_bf16 v[52:55], v[64:67], v[182:185], 0
	v_mfma_f32_16x16x32_bf16 v[40:43], v[72:75], v[182:185], 0
	v_mfma_f32_16x16x32_bf16 v[28:31], v[64:67], v[194:197], 0
	v_mfma_f32_16x16x32_bf16 v[24:27], v[72:75], v[194:197], 0
	v_mfma_f32_16x16x32_bf16 v[20:23], v[64:67], v[204:207], 0
	v_mfma_f32_16x16x32_bf16 v[8:11], v[72:75], v[204:207], 0
	v_mfma_f32_16x16x32_bf16 v[60:63], v[68:71], v[178:181], v[60:63]
	v_mfma_f32_16x16x32_bf16 v[56:59], v[100:103], v[178:181], v[56:59]
	v_mfma_f32_16x16x32_bf16 v[52:55], v[68:71], v[186:189], v[52:55]
	v_mfma_f32_16x16x32_bf16 v[40:43], v[100:103], v[186:189], v[40:43]
	v_mfma_f32_16x16x32_bf16 v[28:31], v[68:71], v[198:201], v[28:31]
	v_mfma_f32_16x16x32_bf16 v[24:27], v[100:103], v[198:201], v[24:27]
	v_mfma_f32_16x16x32_bf16 v[20:23], v[68:71], v[208:211], v[20:23]
	v_mfma_f32_16x16x32_bf16 v[8:11], v[100:103], v[208:211], v[8:11]
	v_mfma_f32_16x16x32_bf16 v[48:51], v[154:157], v[174:177], 0
	v_mfma_f32_16x16x32_bf16 v[44:47], v[166:169], v[174:177], 0
	v_mfma_f32_16x16x32_bf16 v[36:39], v[154:157], v[182:185], 0
	v_mfma_f32_16x16x32_bf16 v[32:35], v[166:169], v[182:185], 0
	v_mfma_f32_16x16x32_bf16 v[16:19], v[154:157], v[194:197], 0
	v_mfma_f32_16x16x32_bf16 v[12:15], v[166:169], v[194:197], 0
	v_mfma_f32_16x16x32_bf16 v[4:7], v[154:157], v[204:207], 0
	v_mfma_f32_16x16x32_bf16 v[0:3], v[166:169], v[204:207], 0
	v_mfma_f32_16x16x32_bf16 v[48:51], v[162:165], v[178:181], v[48:51]
	v_mfma_f32_16x16x32_bf16 v[44:47], v[170:173], v[178:181], v[44:47]
	v_mfma_f32_16x16x32_bf16 v[36:39], v[162:165], v[186:189], v[36:39]
	v_mfma_f32_16x16x32_bf16 v[32:35], v[170:173], v[186:189], v[32:35]
	v_mfma_f32_16x16x32_bf16 v[16:19], v[162:165], v[198:201], v[16:19]
	v_mfma_f32_16x16x32_bf16 v[12:15], v[170:173], v[198:201], v[12:15]
	v_mfma_f32_16x16x32_bf16 v[4:7], v[162:165], v[208:211], v[4:7]
	v_mfma_f32_16x16x32_bf16 v[0:3], v[170:173], v[208:211], v[0:3]
	s_setprio 0
	s_barrier
	s_add_i32 s43, 0, 0x18000
	s_add_i32 s44, 0, 0x1c000
	v_add_u32_e32 v100, s43, v159
	v_add_u32_e32 v170, s44, v159
	ds_read_b128 v[64:67], v100
	ds_read_b128 v[68:71], v100 offset:1024
	ds_read_b128 v[72:75], v100 offset:2048
	ds_read_b128 v[100:103], v100 offset:3072
	ds_read_b128 v[154:157], v170
	ds_read_b128 v[162:165], v170 offset:1024
	ds_read_b128 v[166:169], v170 offset:2048
	ds_read_b128 v[170:173], v170 offset:3072
	s_add_u32 s20, s74, 0x120000
	s_addc_u32 s21, s75, 0
	s_mov_b32 m0, s3
	v_lshl_add_u64 v[218:219], s[20:21], 0, v[148:149]
	ds_read_b128 v[174:177], v161 offset:32768
	ds_read_b128 v[178:181], v161 offset:33792
	ds_read_b128 v[182:185], v161 offset:34816
	ds_read_b128 v[186:189], v161 offset:35840
	ds_read_b128 v[194:197], v161 offset:36864
	ds_read_b128 v[198:201], v161 offset:37888
	ds_read_b128 v[204:207], v161 offset:38912
	ds_read_b128 v[208:211], v161 offset:39936
	global_load_lds_dwordx4 v[218:219], off
	v_lshl_add_u64 v[218:219], s[20:21], 0, v[146:147]
	s_mov_b32 m0, s34
	s_nop 0
	global_load_lds_dwordx4 v[218:219], off
	s_waitcnt vmcnt(8)
	s_waitcnt lgkmcnt(0)
	s_barrier
	s_setprio 1
	s_waitcnt lgkmcnt(0)
	v_mfma_f32_16x16x32_bf16 v[140:143], v[64:67], v[174:177], v[140:143]
	v_mfma_f32_16x16x32_bf16 v[136:139], v[72:75], v[174:177], v[136:139]
	v_mfma_f32_16x16x32_bf16 v[132:135], v[64:67], v[182:185], v[132:135]
	v_mfma_f32_16x16x32_bf16 v[120:123], v[72:75], v[182:185], v[120:123]
	v_mfma_f32_16x16x32_bf16 v[108:111], v[64:67], v[194:197], v[108:111]
	v_mfma_f32_16x16x32_bf16 v[104:107], v[72:75], v[194:197], v[104:107]
	v_mfma_f32_16x16x32_bf16 v[96:99], v[64:67], v[204:207], v[96:99]
	v_mfma_f32_16x16x32_bf16 v[84:87], v[72:75], v[204:207], v[84:87]
	v_mfma_f32_16x16x32_bf16 v[140:143], v[68:71], v[178:181], v[140:143]
	v_mfma_f32_16x16x32_bf16 v[136:139], v[100:103], v[178:181], v[136:139]
	v_mfma_f32_16x16x32_bf16 v[132:135], v[68:71], v[186:189], v[132:135]
	v_mfma_f32_16x16x32_bf16 v[120:123], v[100:103], v[186:189], v[120:123]
	v_mfma_f32_16x16x32_bf16 v[108:111], v[68:71], v[198:201], v[108:111]
	v_mfma_f32_16x16x32_bf16 v[104:107], v[100:103], v[198:201], v[104:107]
	v_mfma_f32_16x16x32_bf16 v[96:99], v[68:71], v[208:211], v[96:99]
	v_mfma_f32_16x16x32_bf16 v[84:87], v[100:103], v[208:211], v[84:87]
	v_mfma_f32_16x16x32_bf16 v[128:131], v[154:157], v[174:177], v[128:131]
	v_mfma_f32_16x16x32_bf16 v[124:127], v[166:169], v[174:177], v[124:127]
	v_mfma_f32_16x16x32_bf16 v[116:119], v[154:157], v[182:185], v[116:119]
	v_mfma_f32_16x16x32_bf16 v[112:115], v[166:169], v[182:185], v[112:115]
	v_mfma_f32_16x16x32_bf16 v[92:95], v[154:157], v[194:197], v[92:95]
	v_mfma_f32_16x16x32_bf16 v[88:91], v[166:169], v[194:197], v[88:91]
	v_mfma_f32_16x16x32_bf16 v[80:83], v[154:157], v[204:207], v[80:83]
	v_mfma_f32_16x16x32_bf16 v[76:79], v[166:169], v[204:207], v[76:79]
	v_mfma_f32_16x16x32_bf16 v[128:131], v[162:165], v[178:181], v[128:131]
	v_mfma_f32_16x16x32_bf16 v[124:127], v[170:173], v[178:181], v[124:127]
	v_mfma_f32_16x16x32_bf16 v[116:119], v[162:165], v[186:189], v[116:119]
	v_mfma_f32_16x16x32_bf16 v[112:115], v[170:173], v[186:189], v[112:115]
	v_mfma_f32_16x16x32_bf16 v[92:95], v[162:165], v[198:201], v[92:95]
	v_mfma_f32_16x16x32_bf16 v[88:91], v[170:173], v[198:201], v[88:91]
	v_mfma_f32_16x16x32_bf16 v[80:83], v[162:165], v[208:211], v[80:83]
	v_mfma_f32_16x16x32_bf16 v[76:79], v[170:173], v[208:211], v[76:79]
	s_setprio 0
	s_barrier
; #define PG8_STAGE(bufoff, gbase, voff) do { _Pragma("unroll") for (int _i = 0; _i < 2; ++_i) \
;         __builtin_amdgcn_global_load_lds((const unsigned*)((const char*)(gbase) + (voff)[_i]), (LAS unsigned*)(lds + (bufoff) + ldsw + _i * 8192), 16, 0, 0); } while (0)
; #define PG8_LDA(dst, b, h) do { _Pragma("unroll") for (int m = 0; m < 4; ++m) _Pragma("unroll") for (int k = 0; k < 2; ++k) dst[m][k] = *(const LAS bf16x8*)(lds + PG8_SA(b, h) + aoff + m * 2048 + k * 1024); } while (0)
; #define PG8_LDB(dst, b, h) do { _Pragma("unroll") for (int n = 0; n < 2; ++n) _Pragma("unroll") for (int k = 0; k < 2; ++k) dst[n][k] = *(const LAS bf16x8*)(lds + PG8_SB(b, h) + boff + n * 2048 + k * 1024); } while (0)
; #define PG8_MMA(ai, bj, At, Bt) do { __builtin_amdgcn_s_setprio(1); _Pragma("unroll") for (int m = 0; m < 4; ++m) _Pragma("unroll") for (int n = 0; n < 2; ++n) _Pragma("unroll") for (int k = 0; k < 2; ++k) \
;         acc[ai][bj][m][n] = __builtin_amdgcn_mfma_f32_16x16x32_bf16(Bt[n][k], At[m][k], acc[ai][bj][m][n], 0, 0, 0); __builtin_amdgcn_s_setprio(0); } while (0)
; #define PG8_WAIT_V(n) asm volatile("s_waitcnt vmcnt(" #n ")" ::: "memory")
; #define PG8_WAIT_L(n) asm volatile("s_waitcnt lgkmcnt(" #n ")" ::: "memory")
; #define PG8_BAR __builtin_amdgcn_s_barrier()
; #define PG8_SCHED __builtin_amdgcn_sched_barrier(0)
; template <class Epi>
; __device__ __forceinline__ void gemm_phase(LAS unsigned char* lds, const Gemm g, const Sched& S, const Epi& E, const int tid) {
;     ...
;         for (int t = 0; t < nt; t += 2) {
;             const bool last = (t == nt - 2);
;             const char* a1 = cA + (size_t)(t + 1) * kstep;
;             const char* a2 = last ? nA : cA + (size_t)(t + 2) * kstep; const char* b2 = last ? nB : cB + (size_t)(t + 2) * kstep;
;             const char* a3 = a2 + kstep; const char* b3 = b2 + kstep;
;             PG8_LDB(B0, 0, 0); PG8_LDB(B1, 0, 1); PG8_SCHED; PG8_LDA(At, 0, 0); PG8_STAGE(PG8_SA(1, 1), a1 + hA, voffA);
;             PG8_WAIT_V(8); PG8_WAIT_L(0); PG8_BAR; PG8_MMA(0, 0, At, B0); PG8_MMA(0, 1, At, B1); PG8_BAR; PG8_SCHED;
;     ...
;             PG8_LDA(At, 1, 1); PG8_STAGE(PG8_SB(1, 0), b3, voffB); PG8_STAGE(PG8_SB(1, 1), b3 + hB, voffB); PG8_STAGE(PG8_SA(1, 0), a3, voffA);
;             PG8_WAIT_V(8); PG8_WAIT_L(0); PG8_BAR; PG8_MMA(1, 0, At, B0); PG8_MMA(1, 1, At, B1); PG8_BAR; PG8_SCHED;
;         }
	s_add_i32 s20, s43, s76
	v_lshl_add_u64 v[190:191], v[190:191], 0, s[94:95]
	s_mov_b32 m0, s20
	ds_read_b128 v[174:177], v161 offset:49152
	ds_read_b128 v[178:181], v161 offset:50176
	ds_read_b128 v[182:185], v161 offset:51200
	ds_read_b128 v[186:189], v161 offset:52224
	ds_read_b128 v[194:197], v161 offset:53248
	ds_read_b128 v[198:201], v161 offset:54272
	ds_read_b128 v[204:207], v161 offset:55296
	ds_read_b128 v[208:211], v161 offset:56320
	global_load_lds_dwordx4 v[190:191], off
	s_add_i32 m0, s20, 0x2000
	s_add_u32 s20, s72, 0x40080
	v_lshl_add_u64 v[190:191], v[212:213], 0, s[94:95]
	s_addc_u32 s21, s73, 0
	s_add_i32 s43, s44, s76
	global_load_lds_dwordx4 v[190:191], off
	v_lshl_add_u64 v[190:191], s[20:21], 0, v[192:193]
	s_mov_b32 m0, s43
	s_nop 0
	global_load_lds_dwordx4 v[190:191], off
	v_lshl_add_u64 v[190:191], s[20:21], 0, v[144:145]
	s_add_i32 m0, s43, 0x2000
	s_nop 0
	global_load_lds_dwordx4 v[190:191], off
	v_lshl_add_u64 v[190:191], v[214:215], 0, s[94:95]
	s_mov_b32 m0, s47
	s_nop 0
	global_load_lds_dwordx4 v[190:191], off
	v_lshl_add_u64 v[190:191], v[216:217], 0, s[94:95]
	s_mov_b32 m0, s40
	s_nop 0
	global_load_lds_dwordx4 v[190:191], off
	s_waitcnt vmcnt(8)
	s_waitcnt lgkmcnt(0)
	s_barrier
	s_setprio 1
	s_waitcnt lgkmcnt(0)
	v_mfma_f32_16x16x32_bf16 v[60:63], v[64:67], v[174:177], v[60:63]
	v_mfma_f32_16x16x32_bf16 v[56:59], v[72:75], v[174:177], v[56:59]
	v_mfma_f32_16x16x32_bf16 v[52:55], v[64:67], v[182:185], v[52:55]
	v_mfma_f32_16x16x32_bf16 v[40:43], v[72:75], v[182:185], v[40:43]
	v_mfma_f32_16x16x32_bf16 v[28:31], v[64:67], v[194:197], v[28:31]
	v_mfma_f32_16x16x32_bf16 v[24:27], v[72:75], v[194:197], v[24:27]
	v_mfma_f32_16x16x32_bf16 v[20:23], v[64:67], v[204:207], v[20:23]
	v_mfma_f32_16x16x32_bf16 v[8:11], v[72:75], v[204:207], v[8:11]
	v_mfma_f32_16x16x32_bf16 v[60:63], v[68:71], v[178:181], v[60:63]
	v_mfma_f32_16x16x32_bf16 v[56:59], v[100:103], v[178:181], v[56:59]
	v_mfma_f32_16x16x32_bf16 v[52:55], v[68:71], v[186:189], v[52:55]
	v_mfma_f32_16x16x32_bf16 v[40:43], v[100:103], v[186:189], v[40:43]
	v_mfma_f32_16x16x32_bf16 v[28:31], v[68:71], v[198:201], v[28:31]
	v_mfma_f32_16x16x32_bf16 v[24:27], v[100:103], v[198:201], v[24:27]
	v_mfma_f32_16x16x32_bf16 v[20:23], v[68:71], v[208:211], v[20:23]
	v_mfma_f32_16x16x32_bf16 v[8:11], v[100:103], v[208:211], v[8:11]
	v_mfma_f32_16x16x32_bf16 v[48:51], v[154:157], v[174:177], v[48:51]
	v_mfma_f32_16x16x32_bf16 v[44:47], v[166:169], v[174:177], v[44:47]
	v_mfma_f32_16x16x32_bf16 v[36:39], v[154:157], v[182:185], v[36:39]
	v_mfma_f32_16x16x32_bf16 v[32:35], v[166:169], v[182:185], v[32:35]
	v_mfma_f32_16x16x32_bf16 v[16:19], v[154:157], v[194:197], v[16:19]
	v_mfma_f32_16x16x32_bf16 v[12:15], v[166:169], v[194:197], v[12:15]
	v_mfma_f32_16x16x32_bf16 v[4:7], v[154:157], v[204:207], v[4:7]
	v_mfma_f32_16x16x32_bf16 v[0:3], v[166:169], v[204:207], v[0:3]
	v_mfma_f32_16x16x32_bf16 v[48:51], v[162:165], v[178:181], v[48:51]
	v_mfma_f32_16x16x32_bf16 v[44:47], v[170:173], v[178:181], v[44:47]
	v_mfma_f32_16x16x32_bf16 v[36:39], v[162:165], v[186:189], v[36:39]
	v_mfma_f32_16x16x32_bf16 v[32:35], v[170:173], v[186:189], v[32:35]
	v_mfma_f32_16x16x32_bf16 v[16:19], v[162:165], v[198:201], v[16:19]
	v_mfma_f32_16x16x32_bf16 v[12:15], v[170:173], v[198:201], v[12:15]
	v_mfma_f32_16x16x32_bf16 v[4:7], v[162:165], v[208:211], v[4:7]
	v_mfma_f32_16x16x32_bf16 v[0:3], v[170:173], v[208:211], v[0:3]
	s_add_i32 vcc_hi, vcc_hi, 2
	s_add_u32 s17, s17, 0x100
	s_addc_u32 vcc_lo, vcc_lo, 0
	s_cmp_gt_u32 vcc_hi, 13
	s_mov_b64 s[20:21], s[22:23]
	s_setprio 0
	s_barrier
	s_cbranch_scc1 .Lgk_exit_3
.LBB0_1143:
	s_add_u32 s22, s20, 0x100
	s_addc_u32 s23, s21, 0
	s_add_i32 s43, 0, 0x10000
	s_cmp_eq_u32 vcc_hi, 12
	s_cselect_b32 s75, s7, s23
	s_cselect_b32 s74, s6, s22
	s_cselect_b32 s73, s19, vcc_lo
	s_cselect_b32 s72, s18, s17
	s_add_i32 s44, 0, 0x14000
	v_add_u32_e32 v100, s43, v159
	v_add_u32_e32 v170, s44, v159
	ds_read_b128 v[64:67], v100
	ds_read_b128 v[68:71], v100 offset:1024
	ds_read_b128 v[72:75], v100 offset:2048
	ds_read_b128 v[100:103], v100 offset:3072
	ds_read_b128 v[154:157], v170
	ds_read_b128 v[162:165], v170 offset:1024
	ds_read_b128 v[166:169], v170 offset:2048
	ds_read_b128 v[170:173], v170 offset:3072
	v_lshl_add_u64 v[190:191], s[20:21], 0, v[150:151]
	s_add_i32 m0, s80, 0xc000
	ds_read_b128 v[174:177], v161
	ds_read_b128 v[178:181], v161 offset:1024
	ds_read_b128 v[182:185], v161 offset:2048
	ds_read_b128 v[186:189], v161 offset:3072
	ds_read_b128 v[194:197], v161 offset:4096
	ds_read_b128 v[198:201], v161 offset:5120
	ds_read_b128 v[204:207], v161 offset:6144
	ds_read_b128 v[208:211], v161 offset:7168
	global_load_lds_dwordx4 v[190:191], off
	v_lshl_add_u64 v[190:191], s[20:21], 0, v[152:153]
	s_add_i32 m0, s80, 0xe000
	s_nop 0
	global_load_lds_dwordx4 v[190:191], off
	s_waitcnt vmcnt(8)
	s_waitcnt lgkmcnt(0)
	s_barrier
; #define PG8_STAGE(bufoff, gbase, voff) do { _Pragma("unroll") for (int _i = 0; _i < 2; ++_i) \
;         __builtin_amdgcn_global_load_lds((const unsigned*)((const char*)(gbase) + (voff)[_i]), (LAS unsigned*)(lds + (bufoff) + ldsw + _i * 8192), 16, 0, 0); } while (0)
; #define PG8_LDA(dst, b, h) do { _Pragma("unroll") for (int m = 0; m < 4; ++m) _Pragma("unroll") for (int k = 0; k < 2; ++k) dst[m][k] = *(const LAS bf16x8*)(lds + PG8_SA(b, h) + aoff + m * 2048 + k * 1024); } while (0)
; #define PG8_MMA(ai, bj, At, Bt) do { __builtin_amdgcn_s_setprio(1); _Pragma("unroll") for (int m = 0; m < 4; ++m) _Pragma("unroll") for (int n = 0; n < 2; ++n) _Pragma("unroll") for (int k = 0; k < 2; ++k) \
;         acc[ai][bj][m][n] = __builtin_amdgcn_mfma_f32_16x16x32_bf16(Bt[n][k], At[m][k], acc[ai][bj][m][n], 0, 0, 0); __builtin_amdgcn_s_setprio(0); } while (0)
; #define PG8_WAIT_V(n) asm volatile("s_waitcnt vmcnt(" #n ")" ::: "memory")
; #define PG8_WAIT_L(n) asm volatile("s_waitcnt lgkmcnt(" #n ")" ::: "memory")
; #define PG8_BAR __builtin_amdgcn_s_barrier()
; #define PG8_SCHED __builtin_amdgcn_sched_barrier(0)
; template <class Epi>
; __device__ __forceinline__ void gemm_phase(LAS unsigned char* lds, const Gemm g, const Sched& S, const Epi& E, const int tid) {
;     ...
;             PG8_WAIT_V(8); PG8_WAIT_L(0); PG8_BAR; PG8_MMA(0, 0, At, B0); PG8_MMA(0, 1, At, B1); PG8_BAR; PG8_SCHED;
;             PG8_LDA(At, 0, 1); PG8_STAGE(PG8_SB(0, 0), b2, voffB); PG8_STAGE(PG8_SB(0, 1), b2 + hB, voffB); PG8_STAGE(PG8_SA(0, 0), a2, voffA);
;             PG8_WAIT_V(8); PG8_WAIT_L(0); PG8_BAR; PG8_MMA(1, 0, At, B0); PG8_MMA(1, 1, At, B1); PG8_BAR; PG8_SCHED;
	s_setprio 1
	s_waitcnt lgkmcnt(0)
	v_mfma_f32_16x16x32_bf16 v[140:143], v[64:67], v[174:177], v[140:143]
	v_mfma_f32_16x16x32_bf16 v[136:139], v[72:75], v[174:177], v[136:139]
	v_mfma_f32_16x16x32_bf16 v[132:135], v[64:67], v[182:185], v[132:135]
	v_mfma_f32_16x16x32_bf16 v[120:123], v[72:75], v[182:185], v[120:123]
	v_mfma_f32_16x16x32_bf16 v[108:111], v[64:67], v[194:197], v[108:111]
	v_mfma_f32_16x16x32_bf16 v[104:107], v[72:75], v[194:197], v[104:107]
	v_mfma_f32_16x16x32_bf16 v[96:99], v[64:67], v[204:207], v[96:99]
	v_mfma_f32_16x16x32_bf16 v[84:87], v[72:75], v[204:207], v[84:87]
	v_mfma_f32_16x16x32_bf16 v[140:143], v[68:71], v[178:181], v[140:143]
	v_mfma_f32_16x16x32_bf16 v[136:139], v[100:103], v[178:181], v[136:139]
	v_mfma_f32_16x16x32_bf16 v[132:135], v[68:71], v[186:189], v[132:135]
	v_mfma_f32_16x16x32_bf16 v[120:123], v[100:103], v[186:189], v[120:123]
	v_mfma_f32_16x16x32_bf16 v[108:111], v[68:71], v[198:201], v[108:111]
	v_mfma_f32_16x16x32_bf16 v[104:107], v[100:103], v[198:201], v[104:107]
	v_mfma_f32_16x16x32_bf16 v[96:99], v[68:71], v[208:211], v[96:99]
	v_mfma_f32_16x16x32_bf16 v[84:87], v[100:103], v[208:211], v[84:87]
	v_mfma_f32_16x16x32_bf16 v[128:131], v[154:157], v[174:177], v[128:131]
	v_mfma_f32_16x16x32_bf16 v[124:127], v[166:169], v[174:177], v[124:127]
	v_mfma_f32_16x16x32_bf16 v[116:119], v[154:157], v[182:185], v[116:119]
	v_mfma_f32_16x16x32_bf16 v[112:115], v[166:169], v[182:185], v[112:115]
	v_mfma_f32_16x16x32_bf16 v[92:95], v[154:157], v[194:197], v[92:95]
	v_mfma_f32_16x16x32_bf16 v[88:91], v[166:169], v[194:197], v[88:91]
	v_mfma_f32_16x16x32_bf16 v[80:83], v[154:157], v[204:207], v[80:83]
	v_mfma_f32_16x16x32_bf16 v[76:79], v[166:169], v[204:207], v[76:79]
	v_mfma_f32_16x16x32_bf16 v[128:131], v[162:165], v[178:181], v[128:131]
	v_mfma_f32_16x16x32_bf16 v[124:127], v[170:173], v[178:181], v[124:127]
	v_mfma_f32_16x16x32_bf16 v[116:119], v[162:165], v[186:189], v[116:119]
	v_mfma_f32_16x16x32_bf16 v[112:115], v[170:173], v[186:189], v[112:115]
	v_mfma_f32_16x16x32_bf16 v[92:95], v[162:165], v[198:201], v[92:95]
	v_mfma_f32_16x16x32_bf16 v[88:91], v[170:173], v[198:201], v[88:91]
	v_mfma_f32_16x16x32_bf16 v[80:83], v[162:165], v[208:211], v[80:83]
	v_mfma_f32_16x16x32_bf16 v[76:79], v[170:173], v[208:211], v[76:79]
	s_setprio 0
	s_barrier
	s_add_i32 s20, s43, s76
	v_lshl_add_u64 v[190:191], s[72:73], 0, v[192:193]
	s_mov_b32 m0, s20
	ds_read_b128 v[174:177], v161 offset:16384
	ds_read_b128 v[178:181], v161 offset:17408
	ds_read_b128 v[182:185], v161 offset:18432
	ds_read_b128 v[186:189], v161 offset:19456
	ds_read_b128 v[194:197], v161 offset:20480
	ds_read_b128 v[198:201], v161 offset:21504
	ds_read_b128 v[204:207], v161 offset:22528
	ds_read_b128 v[208:211], v161 offset:23552
	global_load_lds_dwordx4 v[190:191], off
	s_add_i32 m0, s20, 0x2000
	s_add_u32 s20, s72, 0x40000
	v_lshl_add_u64 v[212:213], s[72:73], 0, v[144:145]
	s_addc_u32 s21, s73, 0
	s_add_i32 s43, s44, s76
	global_load_lds_dwordx4 v[212:213], off
	v_lshl_add_u64 v[214:215], s[20:21], 0, v[192:193]
	s_mov_b32 m0, s43
	v_lshl_add_u64 v[216:217], s[74:75], 0, v[146:147]
	global_load_lds_dwordx4 v[214:215], off
	v_lshl_add_u64 v[214:215], s[20:21], 0, v[144:145]
	s_add_i32 m0, s43, 0x2000
	s_nop 0
	global_load_lds_dwordx4 v[214:215], off
	v_lshl_add_u64 v[214:215], s[74:75], 0, v[148:149]
	s_mov_b32 m0, s80
	s_nop 0
	global_load_lds_dwordx4 v[214:215], off
	s_mov_b32 m0, s81
	s_nop 0
	global_load_lds_dwordx4 v[216:217], off
	s_waitcnt vmcnt(8)
	s_waitcnt lgkmcnt(0)
	s_barrier
	s_setprio 1
	s_waitcnt lgkmcnt(0)
	v_mfma_f32_16x16x32_bf16 v[60:63], v[64:67], v[174:177], v[60:63]
	v_mfma_f32_16x16x32_bf16 v[56:59], v[72:75], v[174:177], v[56:59]
	v_mfma_f32_16x16x32_bf16 v[52:55], v[64:67], v[182:185], v[52:55]
	v_mfma_f32_16x16x32_bf16 v[40:43], v[72:75], v[182:185], v[40:43]
	v_mfma_f32_16x16x32_bf16 v[28:31], v[64:67], v[194:197], v[28:31]
	v_mfma_f32_16x16x32_bf16 v[24:27], v[72:75], v[194:197], v[24:27]
	v_mfma_f32_16x16x32_bf16 v[20:23], v[64:67], v[204:207], v[20:23]
	v_mfma_f32_16x16x32_bf16 v[8:11], v[72:75], v[204:207], v[8:11]
	v_mfma_f32_16x16x32_bf16 v[60:63], v[68:71], v[178:181], v[60:63]
	v_mfma_f32_16x16x32_bf16 v[56:59], v[100:103], v[178:181], v[56:59]
	v_mfma_f32_16x16x32_bf16 v[52:55], v[68:71], v[186:189], v[52:55]
	v_mfma_f32_16x16x32_bf16 v[40:43], v[100:103], v[186:189], v[40:43]
	v_mfma_f32_16x16x32_bf16 v[28:31], v[68:71], v[198:201], v[28:31]
	v_mfma_f32_16x16x32_bf16 v[24:27], v[100:103], v[198:201], v[24:27]
	v_mfma_f32_16x16x32_bf16 v[20:23], v[68:71], v[208:211], v[20:23]
	v_mfma_f32_16x16x32_bf16 v[8:11], v[100:103], v[208:211], v[8:11]
	v_mfma_f32_16x16x32_bf16 v[48:51], v[154:157], v[174:177], v[48:51]
	v_mfma_f32_16x16x32_bf16 v[44:47], v[166:169], v[174:177], v[44:47]
	v_mfma_f32_16x16x32_bf16 v[36:39], v[154:157], v[182:185], v[36:39]
	v_mfma_f32_16x16x32_bf16 v[32:35], v[166:169], v[182:185], v[32:35]
	v_mfma_f32_16x16x32_bf16 v[16:19], v[154:157], v[194:197], v[16:19]
	v_mfma_f32_16x16x32_bf16 v[12:15], v[166:169], v[194:197], v[12:15]
	v_mfma_f32_16x16x32_bf16 v[4:7], v[154:157], v[204:207], v[4:7]
	v_mfma_f32_16x16x32_bf16 v[0:3], v[166:169], v[204:207], v[0:3]
	v_mfma_f32_16x16x32_bf16 v[48:51], v[162:165], v[178:181], v[48:51]
	v_mfma_f32_16x16x32_bf16 v[44:47], v[170:173], v[178:181], v[44:47]
	v_mfma_f32_16x16x32_bf16 v[36:39], v[162:165], v[186:189], v[36:39]
	v_mfma_f32_16x16x32_bf16 v[32:35], v[170:173], v[186:189], v[32:35]
	v_mfma_f32_16x16x32_bf16 v[16:19], v[162:165], v[198:201], v[16:19]
	v_mfma_f32_16x16x32_bf16 v[12:15], v[170:173], v[198:201], v[12:15]
	v_mfma_f32_16x16x32_bf16 v[4:7], v[162:165], v[208:211], v[4:7]
	v_mfma_f32_16x16x32_bf16 v[0:3], v[170:173], v[208:211], v[0:3]
	s_setprio 0
	s_barrier
; #define PG8_STAGE(bufoff, gbase, voff) do { _Pragma("unroll") for (int _i = 0; _i < 2; ++_i) \
;         __builtin_amdgcn_global_load_lds((const unsigned*)((const char*)(gbase) + (voff)[_i]), (LAS unsigned*)(lds + (bufoff) + ldsw + _i * 8192), 16, 0, 0); } while (0)
; #define PG8_LDA(dst, b, h) do { _Pragma("unroll") for (int m = 0; m < 4; ++m) _Pragma("unroll") for (int k = 0; k < 2; ++k) dst[m][k] = *(const LAS bf16x8*)(lds + PG8_SA(b, h) + aoff + m * 2048 + k * 1024); } while (0)
; #define PG8_LDB(dst, b, h) do { _Pragma("unroll") for (int n = 0; n < 2; ++n) _Pragma("unroll") for (int k = 0; k < 2; ++k) dst[n][k] = *(const LAS bf16x8*)(lds + PG8_SB(b, h) + boff + n * 2048 + k * 1024); } while (0)
; #define PG8_MMA(ai, bj, At, Bt) do { __builtin_amdgcn_s_setprio(1); _Pragma("unroll") for (int m = 0; m < 4; ++m) _Pragma("unroll") for (int n = 0; n < 2; ++n) _Pragma("unroll") for (int k = 0; k < 2; ++k) \
;         acc[ai][bj][m][n] = __builtin_amdgcn_mfma_f32_16x16x32_bf16(Bt[n][k], At[m][k], acc[ai][bj][m][n], 0, 0, 0); __builtin_amdgcn_s_setprio(0); } while (0)
; #define PG8_WAIT_V(n) asm volatile("s_waitcnt vmcnt(" #n ")" ::: "memory")
; #define PG8_WAIT_L(n) asm volatile("s_waitcnt lgkmcnt(" #n ")" ::: "memory")
; #define PG8_BAR __builtin_amdgcn_s_barrier()
; #define PG8_SCHED __builtin_amdgcn_sched_barrier(0)
; template <class Epi>
; __device__ __forceinline__ void gemm_phase(LAS unsigned char* lds, const Gemm g, const Sched& S, const Epi& E, const int tid) {
;     ...
;             PG8_LDB(B0, 1, 0); PG8_LDB(B1, 1, 1); PG8_SCHED; PG8_LDA(At, 1, 0); PG8_STAGE(PG8_SA(0, 1), a2 + hA, voffA);
;             PG8_WAIT_V(8); PG8_WAIT_L(0); PG8_BAR; PG8_MMA(0, 0, At, B0); PG8_MMA(0, 1, At, B1); PG8_BAR; PG8_SCHED;
	s_add_i32 s43, 0, 0x18000
	s_add_i32 s44, 0, 0x1c000
	v_add_u32_e32 v100, s43, v159
	v_add_u32_e32 v170, s44, v159
	ds_read_b128 v[64:67], v100
	ds_read_b128 v[68:71], v100 offset:1024
	ds_read_b128 v[72:75], v100 offset:2048
	ds_read_b128 v[100:103], v100 offset:3072
	ds_read_b128 v[154:157], v170
	ds_read_b128 v[162:165], v170 offset:1024
	ds_read_b128 v[166:169], v170 offset:2048
	ds_read_b128 v[170:173], v170 offset:3072
	s_add_u32 s20, s74, 0x120000
	s_addc_u32 s21, s75, 0
	s_mov_b32 m0, s3
	v_lshl_add_u64 v[218:219], s[20:21], 0, v[148:149]
	ds_read_b128 v[174:177], v161 offset:32768
	ds_read_b128 v[178:181], v161 offset:33792
	ds_read_b128 v[182:185], v161 offset:34816
	ds_read_b128 v[186:189], v161 offset:35840
	ds_read_b128 v[194:197], v161 offset:36864
	ds_read_b128 v[198:201], v161 offset:37888
	ds_read_b128 v[204:207], v161 offset:38912
	ds_read_b128 v[208:211], v161 offset:39936
	global_load_lds_dwordx4 v[218:219], off
	v_lshl_add_u64 v[218:219], s[20:21], 0, v[146:147]
	s_mov_b32 m0, s34
	s_nop 0
	global_load_lds_dwordx4 v[218:219], off
	s_waitcnt vmcnt(8)
	s_waitcnt lgkmcnt(0)
	s_barrier
	s_setprio 1
	s_waitcnt lgkmcnt(0)
	v_mfma_f32_16x16x32_bf16 v[140:143], v[64:67], v[174:177], v[140:143]
	v_mfma_f32_16x16x32_bf16 v[136:139], v[72:75], v[174:177], v[136:139]
	v_mfma_f32_16x16x32_bf16 v[132:135], v[64:67], v[182:185], v[132:135]
	v_mfma_f32_16x16x32_bf16 v[120:123], v[72:75], v[182:185], v[120:123]
	v_mfma_f32_16x16x32_bf16 v[108:111], v[64:67], v[194:197], v[108:111]
	v_mfma_f32_16x16x32_bf16 v[104:107], v[72:75], v[194:197], v[104:107]
	v_mfma_f32_16x16x32_bf16 v[96:99], v[64:67], v[204:207], v[96:99]
	v_mfma_f32_16x16x32_bf16 v[84:87], v[72:75], v[204:207], v[84:87]
	v_mfma_f32_16x16x32_bf16 v[140:143], v[68:71], v[178:181], v[140:143]
	v_mfma_f32_16x16x32_bf16 v[136:139], v[100:103], v[178:181], v[136:139]
	v_mfma_f32_16x16x32_bf16 v[132:135], v[68:71], v[186:189], v[132:135]
	v_mfma_f32_16x16x32_bf16 v[120:123], v[100:103], v[186:189], v[120:123]
	v_mfma_f32_16x16x32_bf16 v[108:111], v[68:71], v[198:201], v[108:111]
	v_mfma_f32_16x16x32_bf16 v[104:107], v[100:103], v[198:201], v[104:107]
	v_mfma_f32_16x16x32_bf16 v[96:99], v[68:71], v[208:211], v[96:99]
	v_mfma_f32_16x16x32_bf16 v[84:87], v[100:103], v[208:211], v[84:87]
	v_mfma_f32_16x16x32_bf16 v[128:131], v[154:157], v[174:177], v[128:131]
	v_mfma_f32_16x16x32_bf16 v[124:127], v[166:169], v[174:177], v[124:127]
	v_mfma_f32_16x16x32_bf16 v[116:119], v[154:157], v[182:185], v[116:119]
	v_mfma_f32_16x16x32_bf16 v[112:115], v[166:169], v[182:185], v[112:115]
	v_mfma_f32_16x16x32_bf16 v[92:95], v[154:157], v[194:197], v[92:95]
	v_mfma_f32_16x16x32_bf16 v[88:91], v[166:169], v[194:197], v[88:91]
	v_mfma_f32_16x16x32_bf16 v[80:83], v[154:157], v[204:207], v[80:83]
	v_mfma_f32_16x16x32_bf16 v[76:79], v[166:169], v[204:207], v[76:79]
	v_mfma_f32_16x16x32_bf16 v[128:131], v[162:165], v[178:181], v[128:131]
	v_mfma_f32_16x16x32_bf16 v[124:127], v[170:173], v[178:181], v[124:127]
	v_mfma_f32_16x16x32_bf16 v[116:119], v[162:165], v[186:189], v[116:119]
	v_mfma_f32_16x16x32_bf16 v[112:115], v[170:173], v[186:189], v[112:115]
	v_mfma_f32_16x16x32_bf16 v[92:95], v[162:165], v[198:201], v[92:95]
	v_mfma_f32_16x16x32_bf16 v[88:91], v[170:173], v[198:201], v[88:91]
	v_mfma_f32_16x16x32_bf16 v[80:83], v[162:165], v[208:211], v[80:83]
	v_mfma_f32_16x16x32_bf16 v[76:79], v[170:173], v[208:211], v[76:79]
	s_setprio 0
	s_barrier
; #define PG8_STAGE(bufoff, gbase, voff) do { _Pragma("unroll") for (int _i = 0; _i < 2; ++_i) \
;         __builtin_amdgcn_global_load_lds((const unsigned*)((const char*)(gbase) + (voff)[_i]), (LAS unsigned*)(lds + (bufoff) + ldsw + _i * 8192), 16, 0, 0); } while (0)
; #define PG8_LDA(dst, b, h) do { _Pragma("unroll") for (int m = 0; m < 4; ++m) _Pragma("unroll") for (int k = 0; k < 2; ++k) dst[m][k] = *(const LAS bf16x8*)(lds + PG8_SA(b, h) + aoff + m * 2048 + k * 1024); } while (0)
; #define PG8_MMA(ai, bj, At, Bt) do { __builtin_amdgcn_s_setprio(1); _Pragma("unroll") for (int m = 0; m < 4; ++m) _Pragma("unroll") for (int n = 0; n < 2; ++n) _Pragma("unroll") for (int k = 0; k < 2; ++k) \
;         acc[ai][bj][m][n] = __builtin_amdgcn_mfma_f32_16x16x32_bf16(Bt[n][k], At[m][k], acc[ai][bj][m][n], 0, 0, 0); __builtin_amdgcn_s_setprio(0); } while (0)
; #define PG8_WAIT_V(n) asm volatile("s_waitcnt vmcnt(" #n ")" ::: "memory")
; #define PG8_WAIT_L(n) asm volatile("s_waitcnt lgkmcnt(" #n ")" ::: "memory")
; #define PG8_BAR __builtin_amdgcn_s_barrier()
; #define PG8_SCHED __builtin_amdgcn_sched_barrier(0)
; template <class Epi>
; __device__ __forceinline__ void gemm_phase(LAS unsigned char* lds, const Gemm g, const Sched& S, const Epi& E, const int tid) {
;     ...
;         for (int t = 0; t < nt; t += 2) {
;     ...
;             PG8_LDA(At, 1, 1); PG8_STAGE(PG8_SB(1, 0), b3, voffB); PG8_STAGE(PG8_SB(1, 1), b3 + hB, voffB); PG8_STAGE(PG8_SA(1, 0), a3, voffA);
;             PG8_WAIT_V(8); PG8_WAIT_L(0); PG8_BAR; PG8_MMA(1, 0, At, B0); PG8_MMA(1, 1, At, B1); PG8_BAR; PG8_SCHED;
;         }
	s_add_i32 s20, s43, s76
	v_lshl_add_u64 v[190:191], v[190:191], 0, s[94:95]
	s_mov_b32 m0, s20
	ds_read_b128 v[174:177], v161 offset:49152
	ds_read_b128 v[178:181], v161 offset:50176
	ds_read_b128 v[182:185], v161 offset:51200
	ds_read_b128 v[186:189], v161 offset:52224
	ds_read_b128 v[194:197], v161 offset:53248
	ds_read_b128 v[198:201], v161 offset:54272
	ds_read_b128 v[204:207], v161 offset:55296
	ds_read_b128 v[208:211], v161 offset:56320
	global_load_lds_dwordx4 v[190:191], off
	s_add_i32 m0, s20, 0x2000
	s_add_u32 s20, s72, 0x40080
	v_lshl_add_u64 v[190:191], v[212:213], 0, s[94:95]
	s_addc_u32 s21, s73, 0
	s_add_i32 s43, s44, s76
	global_load_lds_dwordx4 v[190:191], off
	v_lshl_add_u64 v[190:191], s[20:21], 0, v[192:193]
	s_mov_b32 m0, s43
	s_nop 0
	global_load_lds_dwordx4 v[190:191], off
	v_lshl_add_u64 v[190:191], s[20:21], 0, v[144:145]
	s_add_i32 m0, s43, 0x2000
	s_nop 0
	global_load_lds_dwordx4 v[190:191], off
	v_lshl_add_u64 v[190:191], v[214:215], 0, s[94:95]
	s_mov_b32 m0, s47
	s_nop 0
	global_load_lds_dwordx4 v[190:191], off
	v_lshl_add_u64 v[190:191], v[216:217], 0, s[94:95]
	s_mov_b32 m0, s40
	s_nop 0
	global_load_lds_dwordx4 v[190:191], off
	s_waitcnt vmcnt(8)
	s_waitcnt lgkmcnt(0)
	s_barrier
	s_setprio 1
	s_waitcnt lgkmcnt(0)
	v_mfma_f32_16x16x32_bf16 v[60:63], v[64:67], v[174:177], v[60:63]
	v_mfma_f32_16x16x32_bf16 v[56:59], v[72:75], v[174:177], v[56:59]
	v_mfma_f32_16x16x32_bf16 v[52:55], v[64:67], v[182:185], v[52:55]
	v_mfma_f32_16x16x32_bf16 v[40:43], v[72:75], v[182:185], v[40:43]
	v_mfma_f32_16x16x32_bf16 v[28:31], v[64:67], v[194:197], v[28:31]
	v_mfma_f32_16x16x32_bf16 v[24:27], v[72:75], v[194:197], v[24:27]
	v_mfma_f32_16x16x32_bf16 v[20:23], v[64:67], v[204:207], v[20:23]
	v_mfma_f32_16x16x32_bf16 v[8:11], v[72:75], v[204:207], v[8:11]
	v_mfma_f32_16x16x32_bf16 v[60:63], v[68:71], v[178:181], v[60:63]
	v_mfma_f32_16x16x32_bf16 v[56:59], v[100:103], v[178:181], v[56:59]
	v_mfma_f32_16x16x32_bf16 v[52:55], v[68:71], v[186:189], v[52:55]
	v_mfma_f32_16x16x32_bf16 v[40:43], v[100:103], v[186:189], v[40:43]
	v_mfma_f32_16x16x32_bf16 v[28:31], v[68:71], v[198:201], v[28:31]
	v_mfma_f32_16x16x32_bf16 v[24:27], v[100:103], v[198:201], v[24:27]
	v_mfma_f32_16x16x32_bf16 v[20:23], v[68:71], v[208:211], v[20:23]
	v_mfma_f32_16x16x32_bf16 v[8:11], v[100:103], v[208:211], v[8:11]
	v_mfma_f32_16x16x32_bf16 v[48:51], v[154:157], v[174:177], v[48:51]
	v_mfma_f32_16x16x32_bf16 v[44:47], v[166:169], v[174:177], v[44:47]
	v_mfma_f32_16x16x32_bf16 v[36:39], v[154:157], v[182:185], v[36:39]
	v_mfma_f32_16x16x32_bf16 v[32:35], v[166:169], v[182:185], v[32:35]
	v_mfma_f32_16x16x32_bf16 v[16:19], v[154:157], v[194:197], v[16:19]
	v_mfma_f32_16x16x32_bf16 v[12:15], v[166:169], v[194:197], v[12:15]
	v_mfma_f32_16x16x32_bf16 v[4:7], v[154:157], v[204:207], v[4:7]
	v_mfma_f32_16x16x32_bf16 v[0:3], v[166:169], v[204:207], v[0:3]
	v_mfma_f32_16x16x32_bf16 v[48:51], v[162:165], v[178:181], v[48:51]
	v_mfma_f32_16x16x32_bf16 v[44:47], v[170:173], v[178:181], v[44:47]
	v_mfma_f32_16x16x32_bf16 v[36:39], v[162:165], v[186:189], v[36:39]
	v_mfma_f32_16x16x32_bf16 v[32:35], v[170:173], v[186:189], v[32:35]
	v_mfma_f32_16x16x32_bf16 v[16:19], v[162:165], v[198:201], v[16:19]
	v_mfma_f32_16x16x32_bf16 v[12:15], v[170:173], v[198:201], v[12:15]
	v_mfma_f32_16x16x32_bf16 v[4:7], v[162:165], v[208:211], v[4:7]
	v_mfma_f32_16x16x32_bf16 v[0:3], v[170:173], v[208:211], v[0:3]
	s_add_i32 vcc_hi, vcc_hi, 2
	s_add_u32 s17, s17, 0x100
	s_addc_u32 vcc_lo, vcc_lo, 0
	s_cmp_gt_u32 vcc_hi, 13
	s_mov_b64 s[20:21], s[22:23]
	s_setprio 0
	s_barrier
	s_cbranch_scc0 .LBB0_1143

; #define PG8_STAGE(bufoff, gbase, voff) do { _Pragma("unroll") for (int _i = 0; _i < 2; ++_i) \
;         __builtin_amdgcn_global_load_lds((const unsigned*)((const char*)(gbase) + (voff)[_i]), (LAS unsigned*)(lds + (bufoff) + ldsw + _i * 8192), 16, 0, 0); } while (0)
; #define PG8_LDA(dst, b, h) do { _Pragma("unroll") for (int m = 0; m < 4; ++m) _Pragma("unroll") for (int k = 0; k < 2; ++k) dst[m][k] = *(const LAS bf16x8*)(lds + PG8_SA(b, h) + aoff + m * 2048 + k * 1024); } while (0)
; #define PG8_LDB(dst, b, h) do { _Pragma("unroll") for (int n = 0; n < 2; ++n) _Pragma("unroll") for (int k = 0; k < 2; ++k) dst[n][k] = *(const LAS bf16x8*)(lds + PG8_SB(b, h) + boff + n * 2048 + k * 1024); } while (0)
; #define PG8_WAIT_V(n) asm volatile("s_waitcnt vmcnt(" #n ")" ::: "memory")
; #define PG8_BAR __builtin_amdgcn_s_barrier()
; template <class Epi>
; __device__ __forceinline__ void gemm_phase(LAS unsigned char* lds, const Gemm g, const Sched& S, const Epi& E, const int tid) {
;     ...
;     PG8_STAGE(PG8_SB(0, 0), cB, voffB); PG8_STAGE(PG8_SB(0, 1), cB + hB, voffB); PG8_STAGE(PG8_SA(0, 0), cA, voffA); PG8_STAGE(PG8_SA(0, 1), cA + hA, voffA);
;     if (wr == 1) PG8_BAR;
;     PG8_WAIT_V(2); PG8_BAR;
;     PG8_STAGE(PG8_SB(1, 0), cB + kstep, voffB); PG8_STAGE(PG8_SA(1, 0), cA + kstep, voffA); PG8_STAGE(PG8_SB(1, 1), cB + hB + kstep, voffB);
;     PG8_WAIT_V(6); PG8_BAR;
;     for (;;) {
;         const bool has_next = S.next(ui + 1, nxt);
;         const char* nA = cA; const char* nB = cB; if (has_next) S.ptrs(nxt, nA, nB);
;         for (int t = 0; t < nt; t += 2) {
;             const bool last = (t == nt - 2);
;             const char* a1 = cA + (size_t)(t + 1) * kstep;
;             const char* a2 = last ? nA : cA + (size_t)(t + 2) * kstep; const char* b2 = last ? nB : cB + (size_t)(t + 2) * kstep;
;             const char* a3 = a2 + kstep; const char* b3 = b2 + kstep;
;             PG8_LDB(B0, 0, 0); PG8_LDB(B1, 0, 1); PG8_SCHED; PG8_LDA(At, 0, 0); PG8_STAGE(PG8_SA(1, 1), a1 + hA, voffA);
;             PG8_WAIT_V(8); PG8_WAIT_L(0); PG8_BAR; PG8_MMA(0, 0, At, B0); PG8_MMA(0, 1, At, B1); PG8_BAR; PG8_SCHED;
;             PG8_LDA(At, 0, 1); PG8_STAGE(PG8_SB(0, 0), b2, voffB); PG8_STAGE(PG8_SB(0, 1), b2 + hB, voffB); PG8_STAGE(PG8_SA(0, 0), a2, voffA);
;             PG8_WAIT_V(8); PG8_WAIT_L(0); PG8_BAR; PG8_MMA(1, 0, At, B0); PG8_MMA(1, 1, At, B1); PG8_BAR; PG8_SCHED;
.LBB0_1335:
	s_add_u32 s20, s20, 0x40080
	s_addc_u32 s21, s21, 0
	s_add_u32 s13, s22, 0x100
	s_addc_u32 s15, s23, 0
	s_mov_b32 s42, -2
	s_add_u32 s22, s20, 0xfffc0080
	s_addc_u32 s23, s21, -1
	s_add_i32 s43, 0, 0x10000
	s_cmp_eq_u32 s42, 12
	s_cselect_b32 s73, s7, s23
	s_cselect_b32 s72, s6, s22
	v_add_u32_e32 v138, s43, v141
	s_cselect_b32 s23, s17, s15
	s_cselect_b32 s22, s16, s13
	s_add_i32 s44, 0, 0x14000
	ds_read_b128 v[144:147], v138
	ds_read_b128 v[148:151], v138 offset:1024
	ds_read_b128 v[152:155], v138 offset:2048
	ds_read_b128 v[156:159], v138 offset:3072
	v_add_u32_e32 v138, s44, v141
	ds_read_b128 v[160:163], v138
	ds_read_b128 v[164:167], v138 offset:1024
	ds_read_b128 v[168:171], v138 offset:2048
	ds_read_b128 v[172:175], v138 offset:3072
	v_lshl_add_u64 v[138:139], s[20:21], 0, v[134:135]
	s_add_i32 m0, s19, 0xc000
	ds_read_b128 v[176:179], v143
	ds_read_b128 v[180:183], v143 offset:1024
	ds_read_b128 v[184:187], v143 offset:2048
	ds_read_b128 v[188:191], v143 offset:3072
	ds_read_b128 v[194:197], v143 offset:4096
	ds_read_b128 v[198:201], v143 offset:5120
	ds_read_b128 v[204:207], v143 offset:6144
	ds_read_b128 v[208:211], v143 offset:7168
	global_load_lds_dwordx4 v[138:139], off
	v_lshl_add_u64 v[138:139], s[20:21], 0, v[136:137]
	s_add_i32 m0, s19, 0xe000
	s_nop 0
	global_load_lds_dwordx4 v[138:139], off
	s_waitcnt vmcnt(8)
	s_waitcnt lgkmcnt(0)
	s_barrier
	s_setprio 1
	s_waitcnt lgkmcnt(0)
	v_mfma_f32_16x16x32_bf16 v[124:127], v[144:147], v[176:179], 0
	v_mfma_f32_16x16x32_bf16 v[120:123], v[152:155], v[176:179], 0
	v_mfma_f32_16x16x32_bf16 v[108:111], v[144:147], v[184:187], 0
	v_mfma_f32_16x16x32_bf16 v[104:107], v[152:155], v[184:187], 0
	v_mfma_f32_16x16x32_bf16 v[92:95], v[144:147], v[194:197], 0
	v_mfma_f32_16x16x32_bf16 v[88:91], v[152:155], v[194:197], 0
	v_mfma_f32_16x16x32_bf16 v[76:79], v[144:147], v[204:207], 0
	v_mfma_f32_16x16x32_bf16 v[72:75], v[152:155], v[204:207], 0
	v_mfma_f32_16x16x32_bf16 v[124:127], v[148:151], v[180:183], v[124:127]
	v_mfma_f32_16x16x32_bf16 v[120:123], v[156:159], v[180:183], v[120:123]
	v_mfma_f32_16x16x32_bf16 v[108:111], v[148:151], v[188:191], v[108:111]
	v_mfma_f32_16x16x32_bf16 v[104:107], v[156:159], v[188:191], v[104:107]
	v_mfma_f32_16x16x32_bf16 v[92:95], v[148:151], v[198:201], v[92:95]
	v_mfma_f32_16x16x32_bf16 v[88:91], v[156:159], v[198:201], v[88:91]
	v_mfma_f32_16x16x32_bf16 v[76:79], v[148:151], v[208:211], v[76:79]
	v_mfma_f32_16x16x32_bf16 v[72:75], v[156:159], v[208:211], v[72:75]
	v_mfma_f32_16x16x32_bf16 v[116:119], v[160:163], v[176:179], 0
	v_mfma_f32_16x16x32_bf16 v[112:115], v[168:171], v[176:179], 0
	v_mfma_f32_16x16x32_bf16 v[100:103], v[160:163], v[184:187], 0
	v_mfma_f32_16x16x32_bf16 v[96:99], v[168:171], v[184:187], 0
	v_mfma_f32_16x16x32_bf16 v[84:87], v[160:163], v[194:197], 0
	v_mfma_f32_16x16x32_bf16 v[80:83], v[168:171], v[194:197], 0
	v_mfma_f32_16x16x32_bf16 v[68:71], v[160:163], v[204:207], 0
	v_mfma_f32_16x16x32_bf16 v[64:67], v[168:171], v[204:207], 0
	v_mfma_f32_16x16x32_bf16 v[116:119], v[164:167], v[180:183], v[116:119]
	v_mfma_f32_16x16x32_bf16 v[112:115], v[172:175], v[180:183], v[112:115]
	v_mfma_f32_16x16x32_bf16 v[100:103], v[164:167], v[188:191], v[100:103]
	v_mfma_f32_16x16x32_bf16 v[96:99], v[172:175], v[188:191], v[96:99]
	v_mfma_f32_16x16x32_bf16 v[84:87], v[164:167], v[198:201], v[84:87]
	v_mfma_f32_16x16x32_bf16 v[80:83], v[172:175], v[198:201], v[80:83]
	v_mfma_f32_16x16x32_bf16 v[68:71], v[164:167], v[208:211], v[68:71]
	v_mfma_f32_16x16x32_bf16 v[64:67], v[172:175], v[208:211], v[64:67]
	s_setprio 0
	s_barrier
	s_add_i32 s43, s43, s35
	v_lshl_add_u64 v[138:139], s[22:23], 0, v[192:193]
	s_mov_b32 m0, s43
	ds_read_b128 v[176:179], v143 offset:16384
	ds_read_b128 v[180:183], v143 offset:17408
	ds_read_b128 v[184:187], v143 offset:18432
	ds_read_b128 v[188:191], v143 offset:19456
	ds_read_b128 v[194:197], v143 offset:20480
	ds_read_b128 v[198:201], v143 offset:21504
	ds_read_b128 v[204:207], v143 offset:22528
	ds_read_b128 v[208:211], v143 offset:23552
	global_load_lds_dwordx4 v[138:139], off
	s_add_i32 m0, s43, 0x2000
	s_add_u32 s76, s22, 0x40000
	v_lshl_add_u64 v[212:213], s[22:23], 0, v[128:129]
	s_addc_u32 s77, s23, 0
	s_add_i32 s43, s44, s35
	global_load_lds_dwordx4 v[212:213], off
	v_lshl_add_u64 v[214:215], s[76:77], 0, v[192:193]
	s_mov_b32 m0, s43
	v_lshl_add_u64 v[216:217], s[72:73], 0, v[130:131]
	global_load_lds_dwordx4 v[214:215], off
	v_lshl_add_u64 v[214:215], s[76:77], 0, v[128:129]
	s_add_i32 m0, s43, 0x2000
	s_nop 0
	global_load_lds_dwordx4 v[214:215], off
	v_lshl_add_u64 v[214:215], s[72:73], 0, v[132:133]
	s_mov_b32 m0, s19
	s_nop 0
	global_load_lds_dwordx4 v[214:215], off
	s_mov_b32 m0, s39
	s_nop 0
	global_load_lds_dwordx4 v[216:217], off
	s_waitcnt vmcnt(8)
	s_waitcnt lgkmcnt(0)
	s_barrier
; #define PG8_STAGE(bufoff, gbase, voff) do { _Pragma("unroll") for (int _i = 0; _i < 2; ++_i) \
;         __builtin_amdgcn_global_load_lds((const unsigned*)((const char*)(gbase) + (voff)[_i]), (LAS unsigned*)(lds + (bufoff) + ldsw + _i * 8192), 16, 0, 0); } while (0)
; #define PG8_LDA(dst, b, h) do { _Pragma("unroll") for (int m = 0; m < 4; ++m) _Pragma("unroll") for (int k = 0; k < 2; ++k) dst[m][k] = *(const LAS bf16x8*)(lds + PG8_SA(b, h) + aoff + m * 2048 + k * 1024); } while (0)
; #define PG8_LDB(dst, b, h) do { _Pragma("unroll") for (int n = 0; n < 2; ++n) _Pragma("unroll") for (int k = 0; k < 2; ++k) dst[n][k] = *(const LAS bf16x8*)(lds + PG8_SB(b, h) + boff + n * 2048 + k * 1024); } while (0)
; #define PG8_MMA(ai, bj, At, Bt) do { __builtin_amdgcn_s_setprio(1); _Pragma("unroll") for (int m = 0; m < 4; ++m) _Pragma("unroll") for (int n = 0; n < 2; ++n) _Pragma("unroll") for (int k = 0; k < 2; ++k) \
;         acc[ai][bj][m][n] = __builtin_amdgcn_mfma_f32_16x16x32_bf16(Bt[n][k], At[m][k], acc[ai][bj][m][n], 0, 0, 0); __builtin_amdgcn_s_setprio(0); } while (0)
; #define PG8_WAIT_V(n) asm volatile("s_waitcnt vmcnt(" #n ")" ::: "memory")
; #define PG8_WAIT_L(n) asm volatile("s_waitcnt lgkmcnt(" #n ")" ::: "memory")
; #define PG8_BAR __builtin_amdgcn_s_barrier()
; #define PG8_SCHED __builtin_amdgcn_sched_barrier(0)
; template <class Epi>
; __device__ __forceinline__ void gemm_phase(LAS unsigned char* lds, const Gemm g, const Sched& S, const Epi& E, const int tid) {
;     ...
;             PG8_WAIT_V(8); PG8_WAIT_L(0); PG8_BAR; PG8_MMA(1, 0, At, B0); PG8_MMA(1, 1, At, B1); PG8_BAR; PG8_SCHED;
;             PG8_LDB(B0, 1, 0); PG8_LDB(B1, 1, 1); PG8_SCHED; PG8_LDA(At, 1, 0); PG8_STAGE(PG8_SA(0, 1), a2 + hA, voffA);
;             PG8_WAIT_V(8); PG8_WAIT_L(0); PG8_BAR; PG8_MMA(0, 0, At, B0); PG8_MMA(0, 1, At, B1); PG8_BAR; PG8_SCHED;
	s_setprio 1
	s_waitcnt lgkmcnt(0)
	v_mfma_f32_16x16x32_bf16 v[60:63], v[144:147], v[176:179], 0
	v_mfma_f32_16x16x32_bf16 v[56:59], v[152:155], v[176:179], 0
	v_mfma_f32_16x16x32_bf16 v[44:47], v[144:147], v[184:187], 0
	v_mfma_f32_16x16x32_bf16 v[40:43], v[152:155], v[184:187], 0
	v_mfma_f32_16x16x32_bf16 v[28:31], v[144:147], v[194:197], 0
	v_mfma_f32_16x16x32_bf16 v[24:27], v[152:155], v[194:197], 0
	v_mfma_f32_16x16x32_bf16 v[12:15], v[144:147], v[204:207], 0
	v_mfma_f32_16x16x32_bf16 v[8:11], v[152:155], v[204:207], 0
	v_mfma_f32_16x16x32_bf16 v[60:63], v[148:151], v[180:183], v[60:63]
	v_mfma_f32_16x16x32_bf16 v[56:59], v[156:159], v[180:183], v[56:59]
	v_mfma_f32_16x16x32_bf16 v[44:47], v[148:151], v[188:191], v[44:47]
	v_mfma_f32_16x16x32_bf16 v[40:43], v[156:159], v[188:191], v[40:43]
	v_mfma_f32_16x16x32_bf16 v[28:31], v[148:151], v[198:201], v[28:31]
	v_mfma_f32_16x16x32_bf16 v[24:27], v[156:159], v[198:201], v[24:27]
	v_mfma_f32_16x16x32_bf16 v[12:15], v[148:151], v[208:211], v[12:15]
	v_mfma_f32_16x16x32_bf16 v[8:11], v[156:159], v[208:211], v[8:11]
	v_mfma_f32_16x16x32_bf16 v[52:55], v[160:163], v[176:179], 0
	v_mfma_f32_16x16x32_bf16 v[48:51], v[168:171], v[176:179], 0
	v_mfma_f32_16x16x32_bf16 v[36:39], v[160:163], v[184:187], 0
	v_mfma_f32_16x16x32_bf16 v[32:35], v[168:171], v[184:187], 0
	v_mfma_f32_16x16x32_bf16 v[20:23], v[160:163], v[194:197], 0
	v_mfma_f32_16x16x32_bf16 v[16:19], v[168:171], v[194:197], 0
	v_mfma_f32_16x16x32_bf16 v[4:7], v[160:163], v[204:207], 0
	v_mfma_f32_16x16x32_bf16 v[0:3], v[168:171], v[204:207], 0
	v_mfma_f32_16x16x32_bf16 v[52:55], v[164:167], v[180:183], v[52:55]
	v_mfma_f32_16x16x32_bf16 v[48:51], v[172:175], v[180:183], v[48:51]
	v_mfma_f32_16x16x32_bf16 v[36:39], v[164:167], v[188:191], v[36:39]
	v_mfma_f32_16x16x32_bf16 v[32:35], v[172:175], v[188:191], v[32:35]
	v_mfma_f32_16x16x32_bf16 v[20:23], v[164:167], v[198:201], v[20:23]
	v_mfma_f32_16x16x32_bf16 v[16:19], v[172:175], v[198:201], v[16:19]
	v_mfma_f32_16x16x32_bf16 v[4:7], v[164:167], v[208:211], v[4:7]
	v_mfma_f32_16x16x32_bf16 v[0:3], v[172:175], v[208:211], v[0:3]
	s_setprio 0
	s_barrier
	s_add_i32 s43, 0, 0x18000
	s_add_i32 s44, 0, 0x1c000
	v_add_u32_e32 v156, s43, v141
	v_add_u32_e32 v172, s44, v141
	ds_read_b128 v[144:147], v156
	ds_read_b128 v[148:151], v156 offset:1024
	ds_read_b128 v[152:155], v156 offset:2048
	ds_read_b128 v[156:159], v156 offset:3072
	ds_read_b128 v[160:163], v172
	ds_read_b128 v[164:167], v172 offset:1024
	ds_read_b128 v[168:171], v172 offset:2048
	ds_read_b128 v[172:175], v172 offset:3072
	s_add_u32 s72, s72, 0x40000
	s_addc_u32 s73, s73, 0
	s_mov_b32 m0, s40
	v_lshl_add_u64 v[218:219], s[72:73], 0, v[132:133]
	ds_read_b128 v[176:179], v143 offset:32768
	ds_read_b128 v[180:183], v143 offset:33792
	ds_read_b128 v[184:187], v143 offset:34816
	ds_read_b128 v[188:191], v143 offset:35840
	ds_read_b128 v[194:197], v143 offset:36864
	ds_read_b128 v[198:201], v143 offset:37888
	ds_read_b128 v[204:207], v143 offset:38912
	ds_read_b128 v[208:211], v143 offset:39936
	global_load_lds_dwordx4 v[218:219], off
	v_lshl_add_u64 v[218:219], s[72:73], 0, v[130:131]
	s_mov_b32 m0, s45
	s_nop 0
	global_load_lds_dwordx4 v[218:219], off
	s_waitcnt vmcnt(8)
	s_waitcnt lgkmcnt(0)
	s_barrier
	s_setprio 1
	s_waitcnt lgkmcnt(0)
	v_mfma_f32_16x16x32_bf16 v[124:127], v[144:147], v[176:179], v[124:127]
	v_mfma_f32_16x16x32_bf16 v[120:123], v[152:155], v[176:179], v[120:123]
	v_mfma_f32_16x16x32_bf16 v[108:111], v[144:147], v[184:187], v[108:111]
	v_mfma_f32_16x16x32_bf16 v[104:107], v[152:155], v[184:187], v[104:107]
	v_mfma_f32_16x16x32_bf16 v[92:95], v[144:147], v[194:197], v[92:95]
	v_mfma_f32_16x16x32_bf16 v[88:91], v[152:155], v[194:197], v[88:91]
	v_mfma_f32_16x16x32_bf16 v[76:79], v[144:147], v[204:207], v[76:79]
	v_mfma_f32_16x16x32_bf16 v[72:75], v[152:155], v[204:207], v[72:75]
	v_mfma_f32_16x16x32_bf16 v[124:127], v[148:151], v[180:183], v[124:127]
	v_mfma_f32_16x16x32_bf16 v[120:123], v[156:159], v[180:183], v[120:123]
	v_mfma_f32_16x16x32_bf16 v[108:111], v[148:151], v[188:191], v[108:111]
	v_mfma_f32_16x16x32_bf16 v[104:107], v[156:159], v[188:191], v[104:107]
	v_mfma_f32_16x16x32_bf16 v[92:95], v[148:151], v[198:201], v[92:95]
	v_mfma_f32_16x16x32_bf16 v[88:91], v[156:159], v[198:201], v[88:91]
	v_mfma_f32_16x16x32_bf16 v[76:79], v[148:151], v[208:211], v[76:79]
	v_mfma_f32_16x16x32_bf16 v[72:75], v[156:159], v[208:211], v[72:75]
	v_mfma_f32_16x16x32_bf16 v[116:119], v[160:163], v[176:179], v[116:119]
	v_mfma_f32_16x16x32_bf16 v[112:115], v[168:171], v[176:179], v[112:115]
	v_mfma_f32_16x16x32_bf16 v[100:103], v[160:163], v[184:187], v[100:103]
	v_mfma_f32_16x16x32_bf16 v[96:99], v[168:171], v[184:187], v[96:99]
	v_mfma_f32_16x16x32_bf16 v[84:87], v[160:163], v[194:197], v[84:87]
	v_mfma_f32_16x16x32_bf16 v[80:83], v[168:171], v[194:197], v[80:83]
	v_mfma_f32_16x16x32_bf16 v[68:71], v[160:163], v[204:207], v[68:71]
	v_mfma_f32_16x16x32_bf16 v[64:67], v[168:171], v[204:207], v[64:67]
	v_mfma_f32_16x16x32_bf16 v[116:119], v[164:167], v[180:183], v[116:119]
	v_mfma_f32_16x16x32_bf16 v[112:115], v[172:175], v[180:183], v[112:115]
	v_mfma_f32_16x16x32_bf16 v[100:103], v[164:167], v[188:191], v[100:103]
	v_mfma_f32_16x16x32_bf16 v[96:99], v[172:175], v[188:191], v[96:99]
	v_mfma_f32_16x16x32_bf16 v[84:87], v[164:167], v[198:201], v[84:87]
	v_mfma_f32_16x16x32_bf16 v[80:83], v[172:175], v[198:201], v[80:83]
	v_mfma_f32_16x16x32_bf16 v[68:71], v[164:167], v[208:211], v[68:71]
	v_mfma_f32_16x16x32_bf16 v[64:67], v[172:175], v[208:211], v[64:67]
	s_setprio 0
	s_barrier
; #define PG8_STAGE(bufoff, gbase, voff) do { _Pragma("unroll") for (int _i = 0; _i < 2; ++_i) \
;         __builtin_amdgcn_global_load_lds((const unsigned*)((const char*)(gbase) + (voff)[_i]), (LAS unsigned*)(lds + (bufoff) + ldsw + _i * 8192), 16, 0, 0); } while (0)
; #define PG8_LDA(dst, b, h) do { _Pragma("unroll") for (int m = 0; m < 4; ++m) _Pragma("unroll") for (int k = 0; k < 2; ++k) dst[m][k] = *(const LAS bf16x8*)(lds + PG8_SA(b, h) + aoff + m * 2048 + k * 1024); } while (0)
; #define PG8_LDB(dst, b, h) do { _Pragma("unroll") for (int n = 0; n < 2; ++n) _Pragma("unroll") for (int k = 0; k < 2; ++k) dst[n][k] = *(const LAS bf16x8*)(lds + PG8_SB(b, h) + boff + n * 2048 + k * 1024); } while (0)
; #define PG8_MMA(ai, bj, At, Bt) do { __builtin_amdgcn_s_setprio(1); _Pragma("unroll") for (int m = 0; m < 4; ++m) _Pragma("unroll") for (int n = 0; n < 2; ++n) _Pragma("unroll") for (int k = 0; k < 2; ++k) \
;         acc[ai][bj][m][n] = __builtin_amdgcn_mfma_f32_16x16x32_bf16(Bt[n][k], At[m][k], acc[ai][bj][m][n], 0, 0, 0); __builtin_amdgcn_s_setprio(0); } while (0)
; #define PG8_WAIT_V(n) asm volatile("s_waitcnt vmcnt(" #n ")" ::: "memory")
; #define PG8_WAIT_L(n) asm volatile("s_waitcnt lgkmcnt(" #n ")" ::: "memory")
; #define PG8_BAR __builtin_amdgcn_s_barrier()
; #define PG8_SCHED __builtin_amdgcn_sched_barrier(0)
; template <class Epi>
; __device__ __forceinline__ void gemm_phase(LAS unsigned char* lds, const Gemm g, const Sched& S, const Epi& E, const int tid) {
;     ...
;         for (int t = 0; t < nt; t += 2) {
;             const bool last = (t == nt - 2);
;             const char* a1 = cA + (size_t)(t + 1) * kstep;
;             const char* a2 = last ? nA : cA + (size_t)(t + 2) * kstep; const char* b2 = last ? nB : cB + (size_t)(t + 2) * kstep;
;             const char* a3 = a2 + kstep; const char* b3 = b2 + kstep;
;             PG8_LDB(B0, 0, 0); PG8_LDB(B1, 0, 1); PG8_SCHED; PG8_LDA(At, 0, 0); PG8_STAGE(PG8_SA(1, 1), a1 + hA, voffA);
;             PG8_WAIT_V(8); PG8_WAIT_L(0); PG8_BAR; PG8_MMA(0, 0, At, B0); PG8_MMA(0, 1, At, B1); PG8_BAR; PG8_SCHED;
;     ...
;             PG8_LDA(At, 1, 1); PG8_STAGE(PG8_SB(1, 0), b3, voffB); PG8_STAGE(PG8_SB(1, 1), b3 + hB, voffB); PG8_STAGE(PG8_SA(1, 0), a3, voffA);
;             PG8_WAIT_V(8); PG8_WAIT_L(0); PG8_BAR; PG8_MMA(1, 0, At, B0); PG8_MMA(1, 1, At, B1); PG8_BAR; PG8_SCHED;
;         }
	s_add_i32 s43, s43, s35
	v_lshl_add_u64 v[138:139], v[138:139], 0, s[94:95]
	s_mov_b32 m0, s43
	ds_read_b128 v[176:179], v143 offset:49152
	ds_read_b128 v[180:183], v143 offset:50176
	ds_read_b128 v[184:187], v143 offset:51200
	ds_read_b128 v[188:191], v143 offset:52224
	ds_read_b128 v[194:197], v143 offset:53248
	ds_read_b128 v[198:201], v143 offset:54272
	ds_read_b128 v[204:207], v143 offset:55296
	ds_read_b128 v[208:211], v143 offset:56320
	global_load_lds_dwordx4 v[138:139], off
	s_add_i32 m0, s43, 0x2000
	s_add_u32 s22, s22, 0x40080
	v_lshl_add_u64 v[138:139], v[212:213], 0, s[94:95]
	s_addc_u32 s23, s23, 0
	s_add_i32 s43, s44, s35
	global_load_lds_dwordx4 v[138:139], off
	v_lshl_add_u64 v[138:139], s[22:23], 0, v[192:193]
	s_mov_b32 m0, s43
	s_nop 0
	global_load_lds_dwordx4 v[138:139], off
	v_lshl_add_u64 v[138:139], s[22:23], 0, v[128:129]
	s_add_i32 m0, s43, 0x2000
	s_nop 0
	global_load_lds_dwordx4 v[138:139], off
	v_lshl_add_u64 v[138:139], v[214:215], 0, s[94:95]
	s_mov_b32 m0, s47
	s_nop 0
	global_load_lds_dwordx4 v[138:139], off
	v_lshl_add_u64 v[138:139], v[216:217], 0, s[94:95]
	s_mov_b32 m0, s51
	s_nop 0
	global_load_lds_dwordx4 v[138:139], off
	s_waitcnt vmcnt(8)
	s_waitcnt lgkmcnt(0)
	s_barrier
	s_setprio 1
	s_waitcnt lgkmcnt(0)
	v_mfma_f32_16x16x32_bf16 v[60:63], v[144:147], v[176:179], v[60:63]
	v_mfma_f32_16x16x32_bf16 v[56:59], v[152:155], v[176:179], v[56:59]
	v_mfma_f32_16x16x32_bf16 v[44:47], v[144:147], v[184:187], v[44:47]
	v_mfma_f32_16x16x32_bf16 v[40:43], v[152:155], v[184:187], v[40:43]
	v_mfma_f32_16x16x32_bf16 v[28:31], v[144:147], v[194:197], v[28:31]
	v_mfma_f32_16x16x32_bf16 v[24:27], v[152:155], v[194:197], v[24:27]
	v_mfma_f32_16x16x32_bf16 v[12:15], v[144:147], v[204:207], v[12:15]
	v_mfma_f32_16x16x32_bf16 v[8:11], v[152:155], v[204:207], v[8:11]
	v_mfma_f32_16x16x32_bf16 v[60:63], v[148:151], v[180:183], v[60:63]
	v_mfma_f32_16x16x32_bf16 v[56:59], v[156:159], v[180:183], v[56:59]
	v_mfma_f32_16x16x32_bf16 v[44:47], v[148:151], v[188:191], v[44:47]
	v_mfma_f32_16x16x32_bf16 v[40:43], v[156:159], v[188:191], v[40:43]
	v_mfma_f32_16x16x32_bf16 v[28:31], v[148:151], v[198:201], v[28:31]
	v_mfma_f32_16x16x32_bf16 v[24:27], v[156:159], v[198:201], v[24:27]
	v_mfma_f32_16x16x32_bf16 v[12:15], v[148:151], v[208:211], v[12:15]
	v_mfma_f32_16x16x32_bf16 v[8:11], v[156:159], v[208:211], v[8:11]
	v_mfma_f32_16x16x32_bf16 v[52:55], v[160:163], v[176:179], v[52:55]
	v_mfma_f32_16x16x32_bf16 v[48:51], v[168:171], v[176:179], v[48:51]
	v_mfma_f32_16x16x32_bf16 v[36:39], v[160:163], v[184:187], v[36:39]
	v_mfma_f32_16x16x32_bf16 v[32:35], v[168:171], v[184:187], v[32:35]
	v_mfma_f32_16x16x32_bf16 v[20:23], v[160:163], v[194:197], v[20:23]
	v_mfma_f32_16x16x32_bf16 v[16:19], v[168:171], v[194:197], v[16:19]
	v_mfma_f32_16x16x32_bf16 v[4:7], v[160:163], v[204:207], v[4:7]
	v_mfma_f32_16x16x32_bf16 v[0:3], v[168:171], v[204:207], v[0:3]
	v_mfma_f32_16x16x32_bf16 v[52:55], v[164:167], v[180:183], v[52:55]
	v_mfma_f32_16x16x32_bf16 v[48:51], v[172:175], v[180:183], v[48:51]
	v_mfma_f32_16x16x32_bf16 v[36:39], v[164:167], v[188:191], v[36:39]
	v_mfma_f32_16x16x32_bf16 v[32:35], v[172:175], v[188:191], v[32:35]
	v_mfma_f32_16x16x32_bf16 v[20:23], v[164:167], v[198:201], v[20:23]
	v_mfma_f32_16x16x32_bf16 v[16:19], v[172:175], v[198:201], v[16:19]
	v_mfma_f32_16x16x32_bf16 v[4:7], v[164:167], v[208:211], v[4:7]
	v_mfma_f32_16x16x32_bf16 v[0:3], v[172:175], v[208:211], v[0:3]
	s_add_i32 s42, s42, 2
	s_add_u32 s20, s20, 0x100
	s_addc_u32 s21, s21, 0
	s_add_u32 s13, s13, 0x100
	s_addc_u32 s15, s15, 0
	s_cmp_gt_u32 s42, 13
	s_setprio 0
	s_barrier
	s_cbranch_scc1 .Lgk_exit_4
.LBB0_1336:
	s_add_u32 s22, s20, 0xfffc0080
	s_addc_u32 s23, s21, -1
	s_add_i32 s43, 0, 0x10000
	s_cmp_eq_u32 s42, 12
	s_cselect_b32 s73, s7, s23
	s_cselect_b32 s72, s6, s22
	v_add_u32_e32 v138, s43, v141
	s_cselect_b32 s23, s17, s15
	s_cselect_b32 s22, s16, s13
	s_add_i32 s44, 0, 0x14000
	ds_read_b128 v[144:147], v138
	ds_read_b128 v[148:151], v138 offset:1024
	ds_read_b128 v[152:155], v138 offset:2048
	ds_read_b128 v[156:159], v138 offset:3072
	v_add_u32_e32 v138, s44, v141
	ds_read_b128 v[160:163], v138
	ds_read_b128 v[164:167], v138 offset:1024
	ds_read_b128 v[168:171], v138 offset:2048
	ds_read_b128 v[172:175], v138 offset:3072
	v_lshl_add_u64 v[138:139], s[20:21], 0, v[134:135]
	s_add_i32 m0, s19, 0xc000
	ds_read_b128 v[176:179], v143
	ds_read_b128 v[180:183], v143 offset:1024
	ds_read_b128 v[184:187], v143 offset:2048
	ds_read_b128 v[188:191], v143 offset:3072
	ds_read_b128 v[194:197], v143 offset:4096
	ds_read_b128 v[198:201], v143 offset:5120
	ds_read_b128 v[204:207], v143 offset:6144
	ds_read_b128 v[208:211], v143 offset:7168
	global_load_lds_dwordx4 v[138:139], off
	v_lshl_add_u64 v[138:139], s[20:21], 0, v[136:137]
	s_add_i32 m0, s19, 0xe000
	s_nop 0
	global_load_lds_dwordx4 v[138:139], off
	s_waitcnt vmcnt(8)
	s_waitcnt lgkmcnt(0)
	s_barrier
; #define PG8_STAGE(bufoff, gbase, voff) do { _Pragma("unroll") for (int _i = 0; _i < 2; ++_i) \
;         __builtin_amdgcn_global_load_lds((const unsigned*)((const char*)(gbase) + (voff)[_i]), (LAS unsigned*)(lds + (bufoff) + ldsw + _i * 8192), 16, 0, 0); } while (0)
; #define PG8_LDA(dst, b, h) do { _Pragma("unroll") for (int m = 0; m < 4; ++m) _Pragma("unroll") for (int k = 0; k < 2; ++k) dst[m][k] = *(const LAS bf16x8*)(lds + PG8_SA(b, h) + aoff + m * 2048 + k * 1024); } while (0)
; #define PG8_MMA(ai, bj, At, Bt) do { __builtin_amdgcn_s_setprio(1); _Pragma("unroll") for (int m = 0; m < 4; ++m) _Pragma("unroll") for (int n = 0; n < 2; ++n) _Pragma("unroll") for (int k = 0; k < 2; ++k) \
;         acc[ai][bj][m][n] = __builtin_amdgcn_mfma_f32_16x16x32_bf16(Bt[n][k], At[m][k], acc[ai][bj][m][n], 0, 0, 0); __builtin_amdgcn_s_setprio(0); } while (0)
; #define PG8_WAIT_V(n) asm volatile("s_waitcnt vmcnt(" #n ")" ::: "memory")
; #define PG8_WAIT_L(n) asm volatile("s_waitcnt lgkmcnt(" #n ")" ::: "memory")
; #define PG8_BAR __builtin_amdgcn_s_barrier()
; #define PG8_SCHED __builtin_amdgcn_sched_barrier(0)
; template <class Epi>
; __device__ __forceinline__ void gemm_phase(LAS unsigned char* lds, const Gemm g, const Sched& S, const Epi& E, const int tid) {
;     ...
;             PG8_WAIT_V(8); PG8_WAIT_L(0); PG8_BAR; PG8_MMA(0, 0, At, B0); PG8_MMA(0, 1, At, B1); PG8_BAR; PG8_SCHED;
;             PG8_LDA(At, 0, 1); PG8_STAGE(PG8_SB(0, 0), b2, voffB); PG8_STAGE(PG8_SB(0, 1), b2 + hB, voffB); PG8_STAGE(PG8_SA(0, 0), a2, voffA);
;             PG8_WAIT_V(8); PG8_WAIT_L(0); PG8_BAR; PG8_MMA(1, 0, At, B0); PG8_MMA(1, 1, At, B1); PG8_BAR; PG8_SCHED;
	s_setprio 1
	s_waitcnt lgkmcnt(0)
	v_mfma_f32_16x16x32_bf16 v[124:127], v[144:147], v[176:179], v[124:127]
	v_mfma_f32_16x16x32_bf16 v[120:123], v[152:155], v[176:179], v[120:123]
	v_mfma_f32_16x16x32_bf16 v[108:111], v[144:147], v[184:187], v[108:111]
	v_mfma_f32_16x16x32_bf16 v[104:107], v[152:155], v[184:187], v[104:107]
	v_mfma_f32_16x16x32_bf16 v[92:95], v[144:147], v[194:197], v[92:95]
	v_mfma_f32_16x16x32_bf16 v[88:91], v[152:155], v[194:197], v[88:91]
	v_mfma_f32_16x16x32_bf16 v[76:79], v[144:147], v[204:207], v[76:79]
	v_mfma_f32_16x16x32_bf16 v[72:75], v[152:155], v[204:207], v[72:75]
	v_mfma_f32_16x16x32_bf16 v[124:127], v[148:151], v[180:183], v[124:127]
	v_mfma_f32_16x16x32_bf16 v[120:123], v[156:159], v[180:183], v[120:123]
	v_mfma_f32_16x16x32_bf16 v[108:111], v[148:151], v[188:191], v[108:111]
	v_mfma_f32_16x16x32_bf16 v[104:107], v[156:159], v[188:191], v[104:107]
	v_mfma_f32_16x16x32_bf16 v[92:95], v[148:151], v[198:201], v[92:95]
	v_mfma_f32_16x16x32_bf16 v[88:91], v[156:159], v[198:201], v[88:91]
	v_mfma_f32_16x16x32_bf16 v[76:79], v[148:151], v[208:211], v[76:79]
	v_mfma_f32_16x16x32_bf16 v[72:75], v[156:159], v[208:211], v[72:75]
	v_mfma_f32_16x16x32_bf16 v[116:119], v[160:163], v[176:179], v[116:119]
	v_mfma_f32_16x16x32_bf16 v[112:115], v[168:171], v[176:179], v[112:115]
	v_mfma_f32_16x16x32_bf16 v[100:103], v[160:163], v[184:187], v[100:103]
	v_mfma_f32_16x16x32_bf16 v[96:99], v[168:171], v[184:187], v[96:99]
	v_mfma_f32_16x16x32_bf16 v[84:87], v[160:163], v[194:197], v[84:87]
	v_mfma_f32_16x16x32_bf16 v[80:83], v[168:171], v[194:197], v[80:83]
	v_mfma_f32_16x16x32_bf16 v[68:71], v[160:163], v[204:207], v[68:71]
	v_mfma_f32_16x16x32_bf16 v[64:67], v[168:171], v[204:207], v[64:67]
	v_mfma_f32_16x16x32_bf16 v[116:119], v[164:167], v[180:183], v[116:119]
	v_mfma_f32_16x16x32_bf16 v[112:115], v[172:175], v[180:183], v[112:115]
	v_mfma_f32_16x16x32_bf16 v[100:103], v[164:167], v[188:191], v[100:103]
	v_mfma_f32_16x16x32_bf16 v[96:99], v[172:175], v[188:191], v[96:99]
	v_mfma_f32_16x16x32_bf16 v[84:87], v[164:167], v[198:201], v[84:87]
	v_mfma_f32_16x16x32_bf16 v[80:83], v[172:175], v[198:201], v[80:83]
	v_mfma_f32_16x16x32_bf16 v[68:71], v[164:167], v[208:211], v[68:71]
	v_mfma_f32_16x16x32_bf16 v[64:67], v[172:175], v[208:211], v[64:67]
	s_setprio 0
	s_barrier
	s_add_i32 s43, s43, s35
	v_lshl_add_u64 v[138:139], s[22:23], 0, v[192:193]
	s_mov_b32 m0, s43
	ds_read_b128 v[176:179], v143 offset:16384
	ds_read_b128 v[180:183], v143 offset:17408
	ds_read_b128 v[184:187], v143 offset:18432
	ds_read_b128 v[188:191], v143 offset:19456
	ds_read_b128 v[194:197], v143 offset:20480
	ds_read_b128 v[198:201], v143 offset:21504
	ds_read_b128 v[204:207], v143 offset:22528
	ds_read_b128 v[208:211], v143 offset:23552
	global_load_lds_dwordx4 v[138:139], off
	s_add_i32 m0, s43, 0x2000
	s_add_u32 s76, s22, 0x40000
	v_lshl_add_u64 v[212:213], s[22:23], 0, v[128:129]
	s_addc_u32 s77, s23, 0
	s_add_i32 s43, s44, s35
	global_load_lds_dwordx4 v[212:213], off
	v_lshl_add_u64 v[214:215], s[76:77], 0, v[192:193]
	s_mov_b32 m0, s43
	v_lshl_add_u64 v[216:217], s[72:73], 0, v[130:131]
	global_load_lds_dwordx4 v[214:215], off
	v_lshl_add_u64 v[214:215], s[76:77], 0, v[128:129]
	s_add_i32 m0, s43, 0x2000
	s_nop 0
	global_load_lds_dwordx4 v[214:215], off
	v_lshl_add_u64 v[214:215], s[72:73], 0, v[132:133]
	s_mov_b32 m0, s19
	s_nop 0
	global_load_lds_dwordx4 v[214:215], off
	s_mov_b32 m0, s39
	s_nop 0
	global_load_lds_dwordx4 v[216:217], off
	s_waitcnt vmcnt(8)
	s_waitcnt lgkmcnt(0)
	s_barrier
	s_setprio 1
	s_waitcnt lgkmcnt(0)
	v_mfma_f32_16x16x32_bf16 v[60:63], v[144:147], v[176:179], v[60:63]
	v_mfma_f32_16x16x32_bf16 v[56:59], v[152:155], v[176:179], v[56:59]
	v_mfma_f32_16x16x32_bf16 v[44:47], v[144:147], v[184:187], v[44:47]
	v_mfma_f32_16x16x32_bf16 v[40:43], v[152:155], v[184:187], v[40:43]
	v_mfma_f32_16x16x32_bf16 v[28:31], v[144:147], v[194:197], v[28:31]
	v_mfma_f32_16x16x32_bf16 v[24:27], v[152:155], v[194:197], v[24:27]
	v_mfma_f32_16x16x32_bf16 v[12:15], v[144:147], v[204:207], v[12:15]
	v_mfma_f32_16x16x32_bf16 v[8:11], v[152:155], v[204:207], v[8:11]
	v_mfma_f32_16x16x32_bf16 v[60:63], v[148:151], v[180:183], v[60:63]
	v_mfma_f32_16x16x32_bf16 v[56:59], v[156:159], v[180:183], v[56:59]
	v_mfma_f32_16x16x32_bf16 v[44:47], v[148:151], v[188:191], v[44:47]
	v_mfma_f32_16x16x32_bf16 v[40:43], v[156:159], v[188:191], v[40:43]
	v_mfma_f32_16x16x32_bf16 v[28:31], v[148:151], v[198:201], v[28:31]
	v_mfma_f32_16x16x32_bf16 v[24:27], v[156:159], v[198:201], v[24:27]
	v_mfma_f32_16x16x32_bf16 v[12:15], v[148:151], v[208:211], v[12:15]
	v_mfma_f32_16x16x32_bf16 v[8:11], v[156:159], v[208:211], v[8:11]
	v_mfma_f32_16x16x32_bf16 v[52:55], v[160:163], v[176:179], v[52:55]
	v_mfma_f32_16x16x32_bf16 v[48:51], v[168:171], v[176:179], v[48:51]
	v_mfma_f32_16x16x32_bf16 v[36:39], v[160:163], v[184:187], v[36:39]
	v_mfma_f32_16x16x32_bf16 v[32:35], v[168:171], v[184:187], v[32:35]
	v_mfma_f32_16x16x32_bf16 v[20:23], v[160:163], v[194:197], v[20:23]
	v_mfma_f32_16x16x32_bf16 v[16:19], v[168:171], v[194:197], v[16:19]
	v_mfma_f32_16x16x32_bf16 v[4:7], v[160:163], v[204:207], v[4:7]
	v_mfma_f32_16x16x32_bf16 v[0:3], v[168:171], v[204:207], v[0:3]
	v_mfma_f32_16x16x32_bf16 v[52:55], v[164:167], v[180:183], v[52:55]
	v_mfma_f32_16x16x32_bf16 v[48:51], v[172:175], v[180:183], v[48:51]
	v_mfma_f32_16x16x32_bf16 v[36:39], v[164:167], v[188:191], v[36:39]
	v_mfma_f32_16x16x32_bf16 v[32:35], v[172:175], v[188:191], v[32:35]
	v_mfma_f32_16x16x32_bf16 v[20:23], v[164:167], v[198:201], v[20:23]
	v_mfma_f32_16x16x32_bf16 v[16:19], v[172:175], v[198:201], v[16:19]
	v_mfma_f32_16x16x32_bf16 v[4:7], v[164:167], v[208:211], v[4:7]
	v_mfma_f32_16x16x32_bf16 v[0:3], v[172:175], v[208:211], v[0:3]
	s_setprio 0
	s_barrier
; #define PG8_STAGE(bufoff, gbase, voff) do { _Pragma("unroll") for (int _i = 0; _i < 2; ++_i) \
;         __builtin_amdgcn_global_load_lds((const unsigned*)((const char*)(gbase) + (voff)[_i]), (LAS unsigned*)(lds + (bufoff) + ldsw + _i * 8192), 16, 0, 0); } while (0)
; #define PG8_LDA(dst, b, h) do { _Pragma("unroll") for (int m = 0; m < 4; ++m) _Pragma("unroll") for (int k = 0; k < 2; ++k) dst[m][k] = *(const LAS bf16x8*)(lds + PG8_SA(b, h) + aoff + m * 2048 + k * 1024); } while (0)
; #define PG8_LDB(dst, b, h) do { _Pragma("unroll") for (int n = 0; n < 2; ++n) _Pragma("unroll") for (int k = 0; k < 2; ++k) dst[n][k] = *(const LAS bf16x8*)(lds + PG8_SB(b, h) + boff + n * 2048 + k * 1024); } while (0)
; #define PG8_MMA(ai, bj, At, Bt) do { __builtin_amdgcn_s_setprio(1); _Pragma("unroll") for (int m = 0; m < 4; ++m) _Pragma("unroll") for (int n = 0; n < 2; ++n) _Pragma("unroll") for (int k = 0; k < 2; ++k) \
;         acc[ai][bj][m][n] = __builtin_amdgcn_mfma_f32_16x16x32_bf16(Bt[n][k], At[m][k], acc[ai][bj][m][n], 0, 0, 0); __builtin_amdgcn_s_setprio(0); } while (0)
; #define PG8_WAIT_V(n) asm volatile("s_waitcnt vmcnt(" #n ")" ::: "memory")
; #define PG8_WAIT_L(n) asm volatile("s_waitcnt lgkmcnt(" #n ")" ::: "memory")
; #define PG8_BAR __builtin_amdgcn_s_barrier()
; #define PG8_SCHED __builtin_amdgcn_sched_barrier(0)
; template <class Epi>
; __device__ __forceinline__ void gemm_phase(LAS unsigned char* lds, const Gemm g, const Sched& S, const Epi& E, const int tid) {
;     ...
;             PG8_LDB(B0, 1, 0); PG8_LDB(B1, 1, 1); PG8_SCHED; PG8_LDA(At, 1, 0); PG8_STAGE(PG8_SA(0, 1), a2 + hA, voffA);
;             PG8_WAIT_V(8); PG8_WAIT_L(0); PG8_BAR; PG8_MMA(0, 0, At, B0); PG8_MMA(0, 1, At, B1); PG8_BAR; PG8_SCHED;
	s_add_i32 s43, 0, 0x18000
	s_add_i32 s44, 0, 0x1c000
	v_add_u32_e32 v156, s43, v141
	v_add_u32_e32 v172, s44, v141
	ds_read_b128 v[144:147], v156
	ds_read_b128 v[148:151], v156 offset:1024
	ds_read_b128 v[152:155], v156 offset:2048
	ds_read_b128 v[156:159], v156 offset:3072
	ds_read_b128 v[160:163], v172
	ds_read_b128 v[164:167], v172 offset:1024
	ds_read_b128 v[168:171], v172 offset:2048
	ds_read_b128 v[172:175], v172 offset:3072
	s_add_u32 s72, s72, 0x40000
	s_addc_u32 s73, s73, 0
	s_mov_b32 m0, s40
	v_lshl_add_u64 v[218:219], s[72:73], 0, v[132:133]
	ds_read_b128 v[176:179], v143 offset:32768
	ds_read_b128 v[180:183], v143 offset:33792
	ds_read_b128 v[184:187], v143 offset:34816
	ds_read_b128 v[188:191], v143 offset:35840
	ds_read_b128 v[194:197], v143 offset:36864
	ds_read_b128 v[198:201], v143 offset:37888
	ds_read_b128 v[204:207], v143 offset:38912
	ds_read_b128 v[208:211], v143 offset:39936
	global_load_lds_dwordx4 v[218:219], off
	v_lshl_add_u64 v[218:219], s[72:73], 0, v[130:131]
	s_mov_b32 m0, s45
	s_nop 0
	global_load_lds_dwordx4 v[218:219], off
	s_waitcnt vmcnt(8)
	s_waitcnt lgkmcnt(0)
	s_barrier
	s_setprio 1
	s_waitcnt lgkmcnt(0)
	v_mfma_f32_16x16x32_bf16 v[124:127], v[144:147], v[176:179], v[124:127]
	v_mfma_f32_16x16x32_bf16 v[120:123], v[152:155], v[176:179], v[120:123]
	v_mfma_f32_16x16x32_bf16 v[108:111], v[144:147], v[184:187], v[108:111]
	v_mfma_f32_16x16x32_bf16 v[104:107], v[152:155], v[184:187], v[104:107]
	v_mfma_f32_16x16x32_bf16 v[92:95], v[144:147], v[194:197], v[92:95]
	v_mfma_f32_16x16x32_bf16 v[88:91], v[152:155], v[194:197], v[88:91]
	v_mfma_f32_16x16x32_bf16 v[76:79], v[144:147], v[204:207], v[76:79]
	v_mfma_f32_16x16x32_bf16 v[72:75], v[152:155], v[204:207], v[72:75]
	v_mfma_f32_16x16x32_bf16 v[124:127], v[148:151], v[180:183], v[124:127]
	v_mfma_f32_16x16x32_bf16 v[120:123], v[156:159], v[180:183], v[120:123]
	v_mfma_f32_16x16x32_bf16 v[108:111], v[148:151], v[188:191], v[108:111]
	v_mfma_f32_16x16x32_bf16 v[104:107], v[156:159], v[188:191], v[104:107]
	v_mfma_f32_16x16x32_bf16 v[92:95], v[148:151], v[198:201], v[92:95]
	v_mfma_f32_16x16x32_bf16 v[88:91], v[156:159], v[198:201], v[88:91]
	v_mfma_f32_16x16x32_bf16 v[76:79], v[148:151], v[208:211], v[76:79]
	v_mfma_f32_16x16x32_bf16 v[72:75], v[156:159], v[208:211], v[72:75]
	v_mfma_f32_16x16x32_bf16 v[116:119], v[160:163], v[176:179], v[116:119]
	v_mfma_f32_16x16x32_bf16 v[112:115], v[168:171], v[176:179], v[112:115]
	v_mfma_f32_16x16x32_bf16 v[100:103], v[160:163], v[184:187], v[100:103]
	v_mfma_f32_16x16x32_bf16 v[96:99], v[168:171], v[184:187], v[96:99]
	v_mfma_f32_16x16x32_bf16 v[84:87], v[160:163], v[194:197], v[84:87]
	v_mfma_f32_16x16x32_bf16 v[80:83], v[168:171], v[194:197], v[80:83]
	v_mfma_f32_16x16x32_bf16 v[68:71], v[160:163], v[204:207], v[68:71]
	v_mfma_f32_16x16x32_bf16 v[64:67], v[168:171], v[204:207], v[64:67]
	v_mfma_f32_16x16x32_bf16 v[116:119], v[164:167], v[180:183], v[116:119]
	v_mfma_f32_16x16x32_bf16 v[112:115], v[172:175], v[180:183], v[112:115]
	v_mfma_f32_16x16x32_bf16 v[100:103], v[164:167], v[188:191], v[100:103]
	v_mfma_f32_16x16x32_bf16 v[96:99], v[172:175], v[188:191], v[96:99]
	v_mfma_f32_16x16x32_bf16 v[84:87], v[164:167], v[198:201], v[84:87]
	v_mfma_f32_16x16x32_bf16 v[80:83], v[172:175], v[198:201], v[80:83]
	v_mfma_f32_16x16x32_bf16 v[68:71], v[164:167], v[208:211], v[68:71]
	v_mfma_f32_16x16x32_bf16 v[64:67], v[172:175], v[208:211], v[64:67]
	s_setprio 0
	s_barrier
; #define PG8_STAGE(bufoff, gbase, voff) do { _Pragma("unroll") for (int _i = 0; _i < 2; ++_i) \
;         __builtin_amdgcn_global_load_lds((const unsigned*)((const char*)(gbase) + (voff)[_i]), (LAS unsigned*)(lds + (bufoff) + ldsw + _i * 8192), 16, 0, 0); } while (0)
; #define PG8_LDA(dst, b, h) do { _Pragma("unroll") for (int m = 0; m < 4; ++m) _Pragma("unroll") for (int k = 0; k < 2; ++k) dst[m][k] = *(const LAS bf16x8*)(lds + PG8_SA(b, h) + aoff + m * 2048 + k * 1024); } while (0)
; #define PG8_MMA(ai, bj, At, Bt) do { __builtin_amdgcn_s_setprio(1); _Pragma("unroll") for (int m = 0; m < 4; ++m) _Pragma("unroll") for (int n = 0; n < 2; ++n) _Pragma("unroll") for (int k = 0; k < 2; ++k) \
;         acc[ai][bj][m][n] = __builtin_amdgcn_mfma_f32_16x16x32_bf16(Bt[n][k], At[m][k], acc[ai][bj][m][n], 0, 0, 0); __builtin_amdgcn_s_setprio(0); } while (0)
; #define PG8_WAIT_V(n) asm volatile("s_waitcnt vmcnt(" #n ")" ::: "memory")
; #define PG8_WAIT_L(n) asm volatile("s_waitcnt lgkmcnt(" #n ")" ::: "memory")
; #define PG8_BAR __builtin_amdgcn_s_barrier()
; #define PG8_SCHED __builtin_amdgcn_sched_barrier(0)
; template <class Epi>
; __device__ __forceinline__ void gemm_phase(LAS unsigned char* lds, const Gemm g, const Sched& S, const Epi& E, const int tid) {
;     ...
;         for (int t = 0; t < nt; t += 2) {
;     ...
;             PG8_LDA(At, 1, 1); PG8_STAGE(PG8_SB(1, 0), b3, voffB); PG8_STAGE(PG8_SB(1, 1), b3 + hB, voffB); PG8_STAGE(PG8_SA(1, 0), a3, voffA);
;             PG8_WAIT_V(8); PG8_WAIT_L(0); PG8_BAR; PG8_MMA(1, 0, At, B0); PG8_MMA(1, 1, At, B1); PG8_BAR; PG8_SCHED;
;         }
	s_add_i32 s43, s43, s35
	v_lshl_add_u64 v[138:139], v[138:139], 0, s[94:95]
	s_mov_b32 m0, s43
	ds_read_b128 v[176:179], v143 offset:49152
	ds_read_b128 v[180:183], v143 offset:50176
	ds_read_b128 v[184:187], v143 offset:51200
	ds_read_b128 v[188:191], v143 offset:52224
	ds_read_b128 v[194:197], v143 offset:53248
	ds_read_b128 v[198:201], v143 offset:54272
	ds_read_b128 v[204:207], v143 offset:55296
	ds_read_b128 v[208:211], v143 offset:56320
	global_load_lds_dwordx4 v[138:139], off
	s_add_i32 m0, s43, 0x2000
	s_add_u32 s22, s22, 0x40080
	v_lshl_add_u64 v[138:139], v[212:213], 0, s[94:95]
	s_addc_u32 s23, s23, 0
	s_add_i32 s43, s44, s35
	global_load_lds_dwordx4 v[138:139], off
	v_lshl_add_u64 v[138:139], s[22:23], 0, v[192:193]
	s_mov_b32 m0, s43
	s_nop 0
	global_load_lds_dwordx4 v[138:139], off
	v_lshl_add_u64 v[138:139], s[22:23], 0, v[128:129]
	s_add_i32 m0, s43, 0x2000
	s_nop 0
	global_load_lds_dwordx4 v[138:139], off
	v_lshl_add_u64 v[138:139], v[214:215], 0, s[94:95]
	s_mov_b32 m0, s47
	s_nop 0
	global_load_lds_dwordx4 v[138:139], off
	v_lshl_add_u64 v[138:139], v[216:217], 0, s[94:95]
	s_mov_b32 m0, s51
	s_nop 0
	global_load_lds_dwordx4 v[138:139], off
	s_waitcnt vmcnt(8)
	s_waitcnt lgkmcnt(0)
	s_barrier
	s_setprio 1
	s_waitcnt lgkmcnt(0)
	v_mfma_f32_16x16x32_bf16 v[60:63], v[144:147], v[176:179], v[60:63]
	v_mfma_f32_16x16x32_bf16 v[56:59], v[152:155], v[176:179], v[56:59]
	v_mfma_f32_16x16x32_bf16 v[44:47], v[144:147], v[184:187], v[44:47]
	v_mfma_f32_16x16x32_bf16 v[40:43], v[152:155], v[184:187], v[40:43]
	v_mfma_f32_16x16x32_bf16 v[28:31], v[144:147], v[194:197], v[28:31]
	v_mfma_f32_16x16x32_bf16 v[24:27], v[152:155], v[194:197], v[24:27]
	v_mfma_f32_16x16x32_bf16 v[12:15], v[144:147], v[204:207], v[12:15]
	v_mfma_f32_16x16x32_bf16 v[8:11], v[152:155], v[204:207], v[8:11]
	v_mfma_f32_16x16x32_bf16 v[60:63], v[148:151], v[180:183], v[60:63]
	v_mfma_f32_16x16x32_bf16 v[56:59], v[156:159], v[180:183], v[56:59]
	v_mfma_f32_16x16x32_bf16 v[44:47], v[148:151], v[188:191], v[44:47]
	v_mfma_f32_16x16x32_bf16 v[40:43], v[156:159], v[188:191], v[40:43]
	v_mfma_f32_16x16x32_bf16 v[28:31], v[148:151], v[198:201], v[28:31]
	v_mfma_f32_16x16x32_bf16 v[24:27], v[156:159], v[198:201], v[24:27]
	v_mfma_f32_16x16x32_bf16 v[12:15], v[148:151], v[208:211], v[12:15]
	v_mfma_f32_16x16x32_bf16 v[8:11], v[156:159], v[208:211], v[8:11]
	v_mfma_f32_16x16x32_bf16 v[52:55], v[160:163], v[176:179], v[52:55]
	v_mfma_f32_16x16x32_bf16 v[48:51], v[168:171], v[176:179], v[48:51]
	v_mfma_f32_16x16x32_bf16 v[36:39], v[160:163], v[184:187], v[36:39]
	v_mfma_f32_16x16x32_bf16 v[32:35], v[168:171], v[184:187], v[32:35]
	v_mfma_f32_16x16x32_bf16 v[20:23], v[160:163], v[194:197], v[20:23]
	v_mfma_f32_16x16x32_bf16 v[16:19], v[168:171], v[194:197], v[16:19]
	v_mfma_f32_16x16x32_bf16 v[4:7], v[160:163], v[204:207], v[4:7]
	v_mfma_f32_16x16x32_bf16 v[0:3], v[168:171], v[204:207], v[0:3]
	v_mfma_f32_16x16x32_bf16 v[52:55], v[164:167], v[180:183], v[52:55]
	v_mfma_f32_16x16x32_bf16 v[48:51], v[172:175], v[180:183], v[48:51]
	v_mfma_f32_16x16x32_bf16 v[36:39], v[164:167], v[188:191], v[36:39]
	v_mfma_f32_16x16x32_bf16 v[32:35], v[172:175], v[188:191], v[32:35]
	v_mfma_f32_16x16x32_bf16 v[20:23], v[164:167], v[198:201], v[20:23]
	v_mfma_f32_16x16x32_bf16 v[16:19], v[172:175], v[198:201], v[16:19]
	v_mfma_f32_16x16x32_bf16 v[4:7], v[164:167], v[208:211], v[4:7]
	v_mfma_f32_16x16x32_bf16 v[0:3], v[172:175], v[208:211], v[0:3]
	s_add_i32 s42, s42, 2
	s_add_u32 s20, s20, 0x100
	s_addc_u32 s21, s21, 0
	s_add_u32 s13, s13, 0x100
	s_addc_u32 s15, s15, 0
	s_cmp_gt_u32 s42, 13
	s_setprio 0
	s_barrier
	s_cbranch_scc0 .LBB0_1336

; #define PG8_STAGE(bufoff, gbase, voff) do { _Pragma("unroll") for (int _i = 0; _i < 2; ++_i) \
;         __builtin_amdgcn_global_load_lds((const unsigned*)((const char*)(gbase) + (voff)[_i]), (LAS unsigned*)(lds + (bufoff) + ldsw + _i * 8192), 16, 0, 0); } while (0)
; #define PG8_LDA(dst, b, h) do { _Pragma("unroll") for (int m = 0; m < 4; ++m) _Pragma("unroll") for (int k = 0; k < 2; ++k) dst[m][k] = *(const LAS bf16x8*)(lds + PG8_SA(b, h) + aoff + m * 2048 + k * 1024); } while (0)
; #define PG8_LDB(dst, b, h) do { _Pragma("unroll") for (int n = 0; n < 2; ++n) _Pragma("unroll") for (int k = 0; k < 2; ++k) dst[n][k] = *(const LAS bf16x8*)(lds + PG8_SB(b, h) + boff + n * 2048 + k * 1024); } while (0)
; #define PG8_WAIT_V(n) asm volatile("s_waitcnt vmcnt(" #n ")" ::: "memory")
; #define PG8_BAR __builtin_amdgcn_s_barrier()
; template <class Epi>
; __device__ __forceinline__ void gemm_phase(LAS unsigned char* lds, const Gemm g, const Sched& S, const Epi& E, const int tid) {
;     ...
;     PG8_STAGE(PG8_SB(0, 0), cB, voffB); PG8_STAGE(PG8_SB(0, 1), cB + hB, voffB); PG8_STAGE(PG8_SA(0, 0), cA, voffA); PG8_STAGE(PG8_SA(0, 1), cA + hA, voffA);
;     if (wr == 1) PG8_BAR;
;     PG8_WAIT_V(2); PG8_BAR;
;     PG8_STAGE(PG8_SB(1, 0), cB + kstep, voffB); PG8_STAGE(PG8_SA(1, 0), cA + kstep, voffA); PG8_STAGE(PG8_SB(1, 1), cB + hB + kstep, voffB);
;     PG8_WAIT_V(6); PG8_BAR;
;     for (;;) {
;         const bool has_next = S.next(ui + 1, nxt);
;         const char* nA = cA; const char* nB = cB; if (has_next) S.ptrs(nxt, nA, nB);
;         for (int t = 0; t < nt; t += 2) {
;             const bool last = (t == nt - 2);
;             const char* a1 = cA + (size_t)(t + 1) * kstep;
;             const char* a2 = last ? nA : cA + (size_t)(t + 2) * kstep; const char* b2 = last ? nB : cB + (size_t)(t + 2) * kstep;
;             const char* a3 = a2 + kstep; const char* b3 = b2 + kstep;
;             PG8_LDB(B0, 0, 0); PG8_LDB(B1, 0, 1); PG8_SCHED; PG8_LDA(At, 0, 0); PG8_STAGE(PG8_SA(1, 1), a1 + hA, voffA);
;             PG8_WAIT_V(8); PG8_WAIT_L(0); PG8_BAR; PG8_MMA(0, 0, At, B0); PG8_MMA(0, 1, At, B1); PG8_BAR; PG8_SCHED;
;             PG8_LDA(At, 0, 1); PG8_STAGE(PG8_SB(0, 0), b2, voffB); PG8_STAGE(PG8_SB(0, 1), b2 + hB, voffB); PG8_STAGE(PG8_SA(0, 0), a2, voffA);
;             PG8_WAIT_V(8); PG8_WAIT_L(0); PG8_BAR; PG8_MMA(1, 0, At, B0); PG8_MMA(1, 1, At, B1); PG8_BAR; PG8_SCHED;
.LBB0_1410:
	s_add_u32 s80, s18, 0x100
	s_addc_u32 s81, s19, 0
	s_mov_b32 vcc_lo, -2
	s_add_u32 s18, s16, 0x100
	s_addc_u32 s19, s17, 0
	s_add_i32 s43, 0, 0x10000
	s_cmp_eq_u32 vcc_lo, 40
	s_cselect_b32 s23, s7, s19
	s_cselect_b32 s22, s6, s18
	s_cselect_b32 s21, s15, s81
	s_cselect_b32 s20, s14, s80
	s_add_i32 s44, 0, 0x14000
	v_add_u32_e32 v92, s43, v157
	v_add_u32_e32 v154, s44, v157
	ds_read_b128 v[64:67], v92
	ds_read_b128 v[68:71], v92 offset:1024
	ds_read_b128 v[80:83], v92 offset:2048
	ds_read_b128 v[92:95], v92 offset:3072
	ds_read_b128 v[160:163], v154
	ds_read_b128 v[164:167], v154 offset:1024
	ds_read_b128 v[168:171], v154 offset:2048
	ds_read_b128 v[172:175], v154 offset:3072
	v_lshl_add_u64 v[154:155], s[16:17], 0, v[150:151]
	s_add_i32 m0, s40, 0xc000
	ds_read_b128 v[176:179], v159
	ds_read_b128 v[180:183], v159 offset:1024
	ds_read_b128 v[184:187], v159 offset:2048
	ds_read_b128 v[188:191], v159 offset:3072
	ds_read_b128 v[194:197], v159 offset:4096
	ds_read_b128 v[198:201], v159 offset:5120
	ds_read_b128 v[204:207], v159 offset:6144
	ds_read_b128 v[208:211], v159 offset:7168
	global_load_lds_dwordx4 v[154:155], off
	v_lshl_add_u64 v[154:155], s[16:17], 0, v[152:153]
	s_add_i32 m0, s40, 0xe000
	s_nop 0
	global_load_lds_dwordx4 v[154:155], off
	s_waitcnt vmcnt(8)
	s_waitcnt lgkmcnt(0)
	s_barrier
	s_setprio 1
	s_waitcnt lgkmcnt(0)
	v_mfma_f32_16x16x32_bf16 v[140:143], v[64:67], v[176:179], 0
	v_mfma_f32_16x16x32_bf16 v[136:139], v[80:83], v[176:179], 0
	v_mfma_f32_16x16x32_bf16 v[132:135], v[64:67], v[184:187], 0
	v_mfma_f32_16x16x32_bf16 v[128:131], v[80:83], v[184:187], 0
	v_mfma_f32_16x16x32_bf16 v[108:111], v[64:67], v[194:197], 0
	v_mfma_f32_16x16x32_bf16 v[104:107], v[80:83], v[194:197], 0
	v_mfma_f32_16x16x32_bf16 v[100:103], v[64:67], v[204:207], 0
	v_mfma_f32_16x16x32_bf16 v[96:99], v[80:83], v[204:207], 0
	v_mfma_f32_16x16x32_bf16 v[140:143], v[68:71], v[180:183], v[140:143]
	v_mfma_f32_16x16x32_bf16 v[136:139], v[92:95], v[180:183], v[136:139]
	v_mfma_f32_16x16x32_bf16 v[132:135], v[68:71], v[188:191], v[132:135]
	v_mfma_f32_16x16x32_bf16 v[128:131], v[92:95], v[188:191], v[128:131]
	v_mfma_f32_16x16x32_bf16 v[108:111], v[68:71], v[198:201], v[108:111]
	v_mfma_f32_16x16x32_bf16 v[104:107], v[92:95], v[198:201], v[104:107]
	v_mfma_f32_16x16x32_bf16 v[100:103], v[68:71], v[208:211], v[100:103]
	v_mfma_f32_16x16x32_bf16 v[96:99], v[92:95], v[208:211], v[96:99]
	v_mfma_f32_16x16x32_bf16 v[124:127], v[160:163], v[176:179], 0
	v_mfma_f32_16x16x32_bf16 v[120:123], v[168:171], v[176:179], 0
	v_mfma_f32_16x16x32_bf16 v[116:119], v[160:163], v[184:187], 0
	v_mfma_f32_16x16x32_bf16 v[112:115], v[168:171], v[184:187], 0
	v_mfma_f32_16x16x32_bf16 v[88:91], v[160:163], v[194:197], 0
	v_mfma_f32_16x16x32_bf16 v[84:87], v[168:171], v[194:197], 0
	v_mfma_f32_16x16x32_bf16 v[76:79], v[160:163], v[204:207], 0
	v_mfma_f32_16x16x32_bf16 v[72:75], v[168:171], v[204:207], 0
	v_mfma_f32_16x16x32_bf16 v[124:127], v[164:167], v[180:183], v[124:127]
	v_mfma_f32_16x16x32_bf16 v[120:123], v[172:175], v[180:183], v[120:123]
	v_mfma_f32_16x16x32_bf16 v[116:119], v[164:167], v[188:191], v[116:119]
	v_mfma_f32_16x16x32_bf16 v[112:115], v[172:175], v[188:191], v[112:115]
	v_mfma_f32_16x16x32_bf16 v[88:91], v[164:167], v[198:201], v[88:91]
	v_mfma_f32_16x16x32_bf16 v[84:87], v[172:175], v[198:201], v[84:87]
	v_mfma_f32_16x16x32_bf16 v[76:79], v[164:167], v[208:211], v[76:79]
	v_mfma_f32_16x16x32_bf16 v[72:75], v[172:175], v[208:211], v[72:75]
	s_setprio 0
	s_barrier
	s_add_i32 s16, s43, s39
	v_lshl_add_u64 v[154:155], s[20:21], 0, v[192:193]
	s_mov_b32 m0, s16
	ds_read_b128 v[176:179], v159 offset:16384
	ds_read_b128 v[180:183], v159 offset:17408
	ds_read_b128 v[184:187], v159 offset:18432
	ds_read_b128 v[188:191], v159 offset:19456
	ds_read_b128 v[194:197], v159 offset:20480
	ds_read_b128 v[198:201], v159 offset:21504
	ds_read_b128 v[204:207], v159 offset:22528
	ds_read_b128 v[208:211], v159 offset:23552
	global_load_lds_dwordx4 v[154:155], off
	s_add_i32 m0, s16, 0x2000
	s_add_u32 s16, s20, 0xb0000
	v_lshl_add_u64 v[212:213], s[20:21], 0, v[144:145]
	s_addc_u32 s17, s21, 0
	s_add_i32 s43, s44, s39
	global_load_lds_dwordx4 v[212:213], off
	v_lshl_add_u64 v[214:215], s[16:17], 0, v[192:193]
	s_mov_b32 m0, s43
	v_lshl_add_u64 v[216:217], s[22:23], 0, v[146:147]
	global_load_lds_dwordx4 v[214:215], off
	v_lshl_add_u64 v[214:215], s[16:17], 0, v[144:145]
	s_add_i32 m0, s43, 0x2000
	s_nop 0
	global_load_lds_dwordx4 v[214:215], off
	v_lshl_add_u64 v[214:215], s[22:23], 0, v[148:149]
	s_mov_b32 m0, s40
	s_nop 0
	global_load_lds_dwordx4 v[214:215], off
	s_mov_b32 m0, s73
	s_nop 0
	global_load_lds_dwordx4 v[216:217], off
	s_waitcnt vmcnt(8)
	s_waitcnt lgkmcnt(0)
	s_barrier
; #define PG8_STAGE(bufoff, gbase, voff) do { _Pragma("unroll") for (int _i = 0; _i < 2; ++_i) \
;         __builtin_amdgcn_global_load_lds((const unsigned*)((const char*)(gbase) + (voff)[_i]), (LAS unsigned*)(lds + (bufoff) + ldsw + _i * 8192), 16, 0, 0); } while (0)
; #define PG8_LDA(dst, b, h) do { _Pragma("unroll") for (int m = 0; m < 4; ++m) _Pragma("unroll") for (int k = 0; k < 2; ++k) dst[m][k] = *(const LAS bf16x8*)(lds + PG8_SA(b, h) + aoff + m * 2048 + k * 1024); } while (0)
; #define PG8_LDB(dst, b, h) do { _Pragma("unroll") for (int n = 0; n < 2; ++n) _Pragma("unroll") for (int k = 0; k < 2; ++k) dst[n][k] = *(const LAS bf16x8*)(lds + PG8_SB(b, h) + boff + n * 2048 + k * 1024); } while (0)
; #define PG8_MMA(ai, bj, At, Bt) do { __builtin_amdgcn_s_setprio(1); _Pragma("unroll") for (int m = 0; m < 4; ++m) _Pragma("unroll") for (int n = 0; n < 2; ++n) _Pragma("unroll") for (int k = 0; k < 2; ++k) \
;         acc[ai][bj][m][n] = __builtin_amdgcn_mfma_f32_16x16x32_bf16(Bt[n][k], At[m][k], acc[ai][bj][m][n], 0, 0, 0); __builtin_amdgcn_s_setprio(0); } while (0)
; #define PG8_WAIT_V(n) asm volatile("s_waitcnt vmcnt(" #n ")" ::: "memory")
; #define PG8_WAIT_L(n) asm volatile("s_waitcnt lgkmcnt(" #n ")" ::: "memory")
; #define PG8_BAR __builtin_amdgcn_s_barrier()
; #define PG8_SCHED __builtin_amdgcn_sched_barrier(0)
; template <class Epi>
; __device__ __forceinline__ void gemm_phase(LAS unsigned char* lds, const Gemm g, const Sched& S, const Epi& E, const int tid) {
;     ...
;             PG8_WAIT_V(8); PG8_WAIT_L(0); PG8_BAR; PG8_MMA(1, 0, At, B0); PG8_MMA(1, 1, At, B1); PG8_BAR; PG8_SCHED;
;             PG8_LDB(B0, 1, 0); PG8_LDB(B1, 1, 1); PG8_SCHED; PG8_LDA(At, 1, 0); PG8_STAGE(PG8_SA(0, 1), a2 + hA, voffA);
;             PG8_WAIT_V(8); PG8_WAIT_L(0); PG8_BAR; PG8_MMA(0, 0, At, B0); PG8_MMA(0, 1, At, B1); PG8_BAR; PG8_SCHED;
	s_setprio 1
	s_waitcnt lgkmcnt(0)
	v_mfma_f32_16x16x32_bf16 v[60:63], v[64:67], v[176:179], 0
	v_mfma_f32_16x16x32_bf16 v[56:59], v[80:83], v[176:179], 0
	v_mfma_f32_16x16x32_bf16 v[52:55], v[64:67], v[184:187], 0
	v_mfma_f32_16x16x32_bf16 v[48:51], v[80:83], v[184:187], 0
	v_mfma_f32_16x16x32_bf16 v[28:31], v[64:67], v[194:197], 0
	v_mfma_f32_16x16x32_bf16 v[24:27], v[80:83], v[194:197], 0
	v_mfma_f32_16x16x32_bf16 v[16:19], v[64:67], v[204:207], 0
	v_mfma_f32_16x16x32_bf16 v[8:11], v[80:83], v[204:207], 0
	v_mfma_f32_16x16x32_bf16 v[60:63], v[68:71], v[180:183], v[60:63]
	v_mfma_f32_16x16x32_bf16 v[56:59], v[92:95], v[180:183], v[56:59]
	v_mfma_f32_16x16x32_bf16 v[52:55], v[68:71], v[188:191], v[52:55]
	v_mfma_f32_16x16x32_bf16 v[48:51], v[92:95], v[188:191], v[48:51]
	v_mfma_f32_16x16x32_bf16 v[28:31], v[68:71], v[198:201], v[28:31]
	v_mfma_f32_16x16x32_bf16 v[24:27], v[92:95], v[198:201], v[24:27]
	v_mfma_f32_16x16x32_bf16 v[16:19], v[68:71], v[208:211], v[16:19]
	v_mfma_f32_16x16x32_bf16 v[8:11], v[92:95], v[208:211], v[8:11]
	v_mfma_f32_16x16x32_bf16 v[44:47], v[160:163], v[176:179], 0
	v_mfma_f32_16x16x32_bf16 v[40:43], v[168:171], v[176:179], 0
	v_mfma_f32_16x16x32_bf16 v[36:39], v[160:163], v[184:187], 0
	v_mfma_f32_16x16x32_bf16 v[32:35], v[168:171], v[184:187], 0
	v_mfma_f32_16x16x32_bf16 v[20:23], v[160:163], v[194:197], 0
	v_mfma_f32_16x16x32_bf16 v[12:15], v[168:171], v[194:197], 0
	v_mfma_f32_16x16x32_bf16 v[4:7], v[160:163], v[204:207], 0
	v_mfma_f32_16x16x32_bf16 v[0:3], v[168:171], v[204:207], 0
	v_mfma_f32_16x16x32_bf16 v[44:47], v[164:167], v[180:183], v[44:47]
	v_mfma_f32_16x16x32_bf16 v[40:43], v[172:175], v[180:183], v[40:43]
	v_mfma_f32_16x16x32_bf16 v[36:39], v[164:167], v[188:191], v[36:39]
	v_mfma_f32_16x16x32_bf16 v[32:35], v[172:175], v[188:191], v[32:35]
	v_mfma_f32_16x16x32_bf16 v[20:23], v[164:167], v[198:201], v[20:23]
	v_mfma_f32_16x16x32_bf16 v[12:15], v[172:175], v[198:201], v[12:15]
	v_mfma_f32_16x16x32_bf16 v[4:7], v[164:167], v[208:211], v[4:7]
	v_mfma_f32_16x16x32_bf16 v[0:3], v[172:175], v[208:211], v[0:3]
	s_setprio 0
	s_barrier
	s_add_i32 s43, 0, 0x18000
	s_add_i32 s44, 0, 0x1c000
	v_add_u32_e32 v92, s43, v157
	v_add_u32_e32 v172, s44, v157
	ds_read_b128 v[64:67], v92
	ds_read_b128 v[68:71], v92 offset:1024
	ds_read_b128 v[80:83], v92 offset:2048
	ds_read_b128 v[92:95], v92 offset:3072
	ds_read_b128 v[160:163], v172
	ds_read_b128 v[164:167], v172 offset:1024
	ds_read_b128 v[168:171], v172 offset:2048
	ds_read_b128 v[172:175], v172 offset:3072
	s_add_u32 s16, s22, 0xb0000
	s_addc_u32 s17, s23, 0
	s_mov_b32 m0, s74
	v_lshl_add_u64 v[218:219], s[16:17], 0, v[148:149]
	ds_read_b128 v[176:179], v159 offset:32768
	ds_read_b128 v[180:183], v159 offset:33792
	ds_read_b128 v[184:187], v159 offset:34816
	ds_read_b128 v[188:191], v159 offset:35840
	ds_read_b128 v[194:197], v159 offset:36864
	ds_read_b128 v[198:201], v159 offset:37888
	ds_read_b128 v[204:207], v159 offset:38912
	ds_read_b128 v[208:211], v159 offset:39936
	global_load_lds_dwordx4 v[218:219], off
	v_lshl_add_u64 v[218:219], s[16:17], 0, v[146:147]
	s_mov_b32 m0, s75
	s_nop 0
	global_load_lds_dwordx4 v[218:219], off
	s_waitcnt vmcnt(8)
	s_waitcnt lgkmcnt(0)
	s_barrier
	s_setprio 1
	s_waitcnt lgkmcnt(0)
	v_mfma_f32_16x16x32_bf16 v[140:143], v[64:67], v[176:179], v[140:143]
	v_mfma_f32_16x16x32_bf16 v[136:139], v[80:83], v[176:179], v[136:139]
	v_mfma_f32_16x16x32_bf16 v[132:135], v[64:67], v[184:187], v[132:135]
	v_mfma_f32_16x16x32_bf16 v[128:131], v[80:83], v[184:187], v[128:131]
	v_mfma_f32_16x16x32_bf16 v[108:111], v[64:67], v[194:197], v[108:111]
	v_mfma_f32_16x16x32_bf16 v[104:107], v[80:83], v[194:197], v[104:107]
	v_mfma_f32_16x16x32_bf16 v[100:103], v[64:67], v[204:207], v[100:103]
	v_mfma_f32_16x16x32_bf16 v[96:99], v[80:83], v[204:207], v[96:99]
	v_mfma_f32_16x16x32_bf16 v[140:143], v[68:71], v[180:183], v[140:143]
	v_mfma_f32_16x16x32_bf16 v[136:139], v[92:95], v[180:183], v[136:139]
	v_mfma_f32_16x16x32_bf16 v[132:135], v[68:71], v[188:191], v[132:135]
	v_mfma_f32_16x16x32_bf16 v[128:131], v[92:95], v[188:191], v[128:131]
	v_mfma_f32_16x16x32_bf16 v[108:111], v[68:71], v[198:201], v[108:111]
	v_mfma_f32_16x16x32_bf16 v[104:107], v[92:95], v[198:201], v[104:107]
	v_mfma_f32_16x16x32_bf16 v[100:103], v[68:71], v[208:211], v[100:103]
	v_mfma_f32_16x16x32_bf16 v[96:99], v[92:95], v[208:211], v[96:99]
	v_mfma_f32_16x16x32_bf16 v[124:127], v[160:163], v[176:179], v[124:127]
	v_mfma_f32_16x16x32_bf16 v[120:123], v[168:171], v[176:179], v[120:123]
	v_mfma_f32_16x16x32_bf16 v[116:119], v[160:163], v[184:187], v[116:119]
	v_mfma_f32_16x16x32_bf16 v[112:115], v[168:171], v[184:187], v[112:115]
	v_mfma_f32_16x16x32_bf16 v[88:91], v[160:163], v[194:197], v[88:91]
	v_mfma_f32_16x16x32_bf16 v[84:87], v[168:171], v[194:197], v[84:87]
	v_mfma_f32_16x16x32_bf16 v[76:79], v[160:163], v[204:207], v[76:79]
	v_mfma_f32_16x16x32_bf16 v[72:75], v[168:171], v[204:207], v[72:75]
	v_mfma_f32_16x16x32_bf16 v[124:127], v[164:167], v[180:183], v[124:127]
	v_mfma_f32_16x16x32_bf16 v[120:123], v[172:175], v[180:183], v[120:123]
	v_mfma_f32_16x16x32_bf16 v[116:119], v[164:167], v[188:191], v[116:119]
	v_mfma_f32_16x16x32_bf16 v[112:115], v[172:175], v[188:191], v[112:115]
	v_mfma_f32_16x16x32_bf16 v[88:91], v[164:167], v[198:201], v[88:91]
	v_mfma_f32_16x16x32_bf16 v[84:87], v[172:175], v[198:201], v[84:87]
	v_mfma_f32_16x16x32_bf16 v[76:79], v[164:167], v[208:211], v[76:79]
	v_mfma_f32_16x16x32_bf16 v[72:75], v[172:175], v[208:211], v[72:75]
	s_setprio 0
	s_barrier
; #define PG8_STAGE(bufoff, gbase, voff) do { _Pragma("unroll") for (int _i = 0; _i < 2; ++_i) \
;         __builtin_amdgcn_global_load_lds((const unsigned*)((const char*)(gbase) + (voff)[_i]), (LAS unsigned*)(lds + (bufoff) + ldsw + _i * 8192), 16, 0, 0); } while (0)
; #define PG8_LDA(dst, b, h) do { _Pragma("unroll") for (int m = 0; m < 4; ++m) _Pragma("unroll") for (int k = 0; k < 2; ++k) dst[m][k] = *(const LAS bf16x8*)(lds + PG8_SA(b, h) + aoff + m * 2048 + k * 1024); } while (0)
; #define PG8_LDB(dst, b, h) do { _Pragma("unroll") for (int n = 0; n < 2; ++n) _Pragma("unroll") for (int k = 0; k < 2; ++k) dst[n][k] = *(const LAS bf16x8*)(lds + PG8_SB(b, h) + boff + n * 2048 + k * 1024); } while (0)
; #define PG8_MMA(ai, bj, At, Bt) do { __builtin_amdgcn_s_setprio(1); _Pragma("unroll") for (int m = 0; m < 4; ++m) _Pragma("unroll") for (int n = 0; n < 2; ++n) _Pragma("unroll") for (int k = 0; k < 2; ++k) \
;         acc[ai][bj][m][n] = __builtin_amdgcn_mfma_f32_16x16x32_bf16(Bt[n][k], At[m][k], acc[ai][bj][m][n], 0, 0, 0); __builtin_amdgcn_s_setprio(0); } while (0)
; #define PG8_WAIT_V(n) asm volatile("s_waitcnt vmcnt(" #n ")" ::: "memory")
; #define PG8_WAIT_L(n) asm volatile("s_waitcnt lgkmcnt(" #n ")" ::: "memory")
; #define PG8_BAR __builtin_amdgcn_s_barrier()
; #define PG8_SCHED __builtin_amdgcn_sched_barrier(0)
; template <class Epi>
; __device__ __forceinline__ void gemm_phase(LAS unsigned char* lds, const Gemm g, const Sched& S, const Epi& E, const int tid) {
;     ...
;         for (int t = 0; t < nt; t += 2) {
;             const bool last = (t == nt - 2);
;             const char* a1 = cA + (size_t)(t + 1) * kstep;
;             const char* a2 = last ? nA : cA + (size_t)(t + 2) * kstep; const char* b2 = last ? nB : cB + (size_t)(t + 2) * kstep;
;             const char* a3 = a2 + kstep; const char* b3 = b2 + kstep;
;             PG8_LDB(B0, 0, 0); PG8_LDB(B1, 0, 1); PG8_SCHED; PG8_LDA(At, 0, 0); PG8_STAGE(PG8_SA(1, 1), a1 + hA, voffA);
;             PG8_WAIT_V(8); PG8_WAIT_L(0); PG8_BAR; PG8_MMA(0, 0, At, B0); PG8_MMA(0, 1, At, B1); PG8_BAR; PG8_SCHED;
;     ...
;             PG8_LDA(At, 1, 1); PG8_STAGE(PG8_SB(1, 0), b3, voffB); PG8_STAGE(PG8_SB(1, 1), b3 + hB, voffB); PG8_STAGE(PG8_SA(1, 0), a3, voffA);
;             PG8_WAIT_V(8); PG8_WAIT_L(0); PG8_BAR; PG8_MMA(1, 0, At, B0); PG8_MMA(1, 1, At, B1); PG8_BAR; PG8_SCHED;
;         }
	s_add_i32 s16, s43, s39
	v_lshl_add_u64 v[154:155], v[154:155], 0, s[94:95]
	s_mov_b32 m0, s16
	ds_read_b128 v[176:179], v159 offset:49152
	ds_read_b128 v[180:183], v159 offset:50176
	ds_read_b128 v[184:187], v159 offset:51200
	ds_read_b128 v[188:191], v159 offset:52224
	ds_read_b128 v[194:197], v159 offset:53248
	ds_read_b128 v[198:201], v159 offset:54272
	ds_read_b128 v[204:207], v159 offset:55296
	ds_read_b128 v[208:211], v159 offset:56320
	global_load_lds_dwordx4 v[154:155], off
	s_add_i32 m0, s16, 0x2000
	s_add_u32 s16, s20, 0xb0080
	v_lshl_add_u64 v[154:155], v[212:213], 0, s[94:95]
	s_addc_u32 s17, s21, 0
	s_add_i32 s20, s44, s39
	global_load_lds_dwordx4 v[154:155], off
	v_lshl_add_u64 v[154:155], s[16:17], 0, v[192:193]
	s_mov_b32 m0, s20
	s_nop 0
	global_load_lds_dwordx4 v[154:155], off
	v_lshl_add_u64 v[154:155], s[16:17], 0, v[144:145]
	s_add_i32 m0, s20, 0x2000
	s_nop 0
	global_load_lds_dwordx4 v[154:155], off
	v_lshl_add_u64 v[154:155], v[214:215], 0, s[94:95]
	s_mov_b32 m0, s51
	s_nop 0
	global_load_lds_dwordx4 v[154:155], off
	v_lshl_add_u64 v[154:155], v[216:217], 0, s[94:95]
	s_mov_b32 m0, s76
	s_nop 0
	global_load_lds_dwordx4 v[154:155], off
	s_waitcnt vmcnt(8)
	s_waitcnt lgkmcnt(0)
	s_barrier
	s_setprio 1
	s_waitcnt lgkmcnt(0)
	v_mfma_f32_16x16x32_bf16 v[60:63], v[64:67], v[176:179], v[60:63]
	v_mfma_f32_16x16x32_bf16 v[56:59], v[80:83], v[176:179], v[56:59]
	v_mfma_f32_16x16x32_bf16 v[52:55], v[64:67], v[184:187], v[52:55]
	v_mfma_f32_16x16x32_bf16 v[48:51], v[80:83], v[184:187], v[48:51]
	v_mfma_f32_16x16x32_bf16 v[28:31], v[64:67], v[194:197], v[28:31]
	v_mfma_f32_16x16x32_bf16 v[24:27], v[80:83], v[194:197], v[24:27]
	v_mfma_f32_16x16x32_bf16 v[16:19], v[64:67], v[204:207], v[16:19]
	v_mfma_f32_16x16x32_bf16 v[8:11], v[80:83], v[204:207], v[8:11]
	v_mfma_f32_16x16x32_bf16 v[60:63], v[68:71], v[180:183], v[60:63]
	v_mfma_f32_16x16x32_bf16 v[56:59], v[92:95], v[180:183], v[56:59]
	v_mfma_f32_16x16x32_bf16 v[52:55], v[68:71], v[188:191], v[52:55]
	v_mfma_f32_16x16x32_bf16 v[48:51], v[92:95], v[188:191], v[48:51]
	v_mfma_f32_16x16x32_bf16 v[28:31], v[68:71], v[198:201], v[28:31]
	v_mfma_f32_16x16x32_bf16 v[24:27], v[92:95], v[198:201], v[24:27]
	v_mfma_f32_16x16x32_bf16 v[16:19], v[68:71], v[208:211], v[16:19]
	v_mfma_f32_16x16x32_bf16 v[8:11], v[92:95], v[208:211], v[8:11]
	v_mfma_f32_16x16x32_bf16 v[44:47], v[160:163], v[176:179], v[44:47]
	v_mfma_f32_16x16x32_bf16 v[40:43], v[168:171], v[176:179], v[40:43]
	v_mfma_f32_16x16x32_bf16 v[36:39], v[160:163], v[184:187], v[36:39]
	v_mfma_f32_16x16x32_bf16 v[32:35], v[168:171], v[184:187], v[32:35]
	v_mfma_f32_16x16x32_bf16 v[20:23], v[160:163], v[194:197], v[20:23]
	v_mfma_f32_16x16x32_bf16 v[12:15], v[168:171], v[194:197], v[12:15]
	v_mfma_f32_16x16x32_bf16 v[4:7], v[160:163], v[204:207], v[4:7]
	v_mfma_f32_16x16x32_bf16 v[0:3], v[168:171], v[204:207], v[0:3]
	v_mfma_f32_16x16x32_bf16 v[44:47], v[164:167], v[180:183], v[44:47]
	v_mfma_f32_16x16x32_bf16 v[40:43], v[172:175], v[180:183], v[40:43]
	v_mfma_f32_16x16x32_bf16 v[36:39], v[164:167], v[188:191], v[36:39]
	v_mfma_f32_16x16x32_bf16 v[32:35], v[172:175], v[188:191], v[32:35]
	v_mfma_f32_16x16x32_bf16 v[20:23], v[164:167], v[198:201], v[20:23]
	v_mfma_f32_16x16x32_bf16 v[12:15], v[172:175], v[198:201], v[12:15]
	v_mfma_f32_16x16x32_bf16 v[4:7], v[164:167], v[208:211], v[4:7]
	v_mfma_f32_16x16x32_bf16 v[0:3], v[172:175], v[208:211], v[0:3]
	s_add_i32 vcc_lo, vcc_lo, 2
	s_add_u32 s80, s80, 0x100
	s_addc_u32 s81, s81, 0
	s_cmp_gt_u32 vcc_lo, 41
	s_mov_b64 s[16:17], s[18:19]
	s_setprio 0
	s_barrier
	s_cbranch_scc1 .Lgk_exit_5
.LBB0_1411:
	s_add_u32 s18, s16, 0x100
	s_addc_u32 s19, s17, 0
	s_add_i32 s43, 0, 0x10000
	s_cmp_eq_u32 vcc_lo, 40
	s_cselect_b32 s23, s7, s19
	s_cselect_b32 s22, s6, s18
	s_cselect_b32 s21, s15, s81
	s_cselect_b32 s20, s14, s80
	s_add_i32 s44, 0, 0x14000
	v_add_u32_e32 v92, s43, v157
	v_add_u32_e32 v154, s44, v157
	ds_read_b128 v[64:67], v92
	ds_read_b128 v[68:71], v92 offset:1024
	ds_read_b128 v[80:83], v92 offset:2048
	ds_read_b128 v[92:95], v92 offset:3072
	ds_read_b128 v[160:163], v154
	ds_read_b128 v[164:167], v154 offset:1024
	ds_read_b128 v[168:171], v154 offset:2048
	ds_read_b128 v[172:175], v154 offset:3072
	v_lshl_add_u64 v[154:155], s[16:17], 0, v[150:151]
	s_add_i32 m0, s40, 0xc000
	ds_read_b128 v[176:179], v159
	ds_read_b128 v[180:183], v159 offset:1024
	ds_read_b128 v[184:187], v159 offset:2048
	ds_read_b128 v[188:191], v159 offset:3072
	ds_read_b128 v[194:197], v159 offset:4096
	ds_read_b128 v[198:201], v159 offset:5120
	ds_read_b128 v[204:207], v159 offset:6144
	ds_read_b128 v[208:211], v159 offset:7168
	global_load_lds_dwordx4 v[154:155], off
	v_lshl_add_u64 v[154:155], s[16:17], 0, v[152:153]
	s_add_i32 m0, s40, 0xe000
	s_nop 0
	global_load_lds_dwordx4 v[154:155], off
	s_waitcnt vmcnt(8)
	s_waitcnt lgkmcnt(0)
	s_barrier
; #define PG8_STAGE(bufoff, gbase, voff) do { _Pragma("unroll") for (int _i = 0; _i < 2; ++_i) \
;         __builtin_amdgcn_global_load_lds((const unsigned*)((const char*)(gbase) + (voff)[_i]), (LAS unsigned*)(lds + (bufoff) + ldsw + _i * 8192), 16, 0, 0); } while (0)
; #define PG8_LDA(dst, b, h) do { _Pragma("unroll") for (int m = 0; m < 4; ++m) _Pragma("unroll") for (int k = 0; k < 2; ++k) dst[m][k] = *(const LAS bf16x8*)(lds + PG8_SA(b, h) + aoff + m * 2048 + k * 1024); } while (0)
; #define PG8_MMA(ai, bj, At, Bt) do { __builtin_amdgcn_s_setprio(1); _Pragma("unroll") for (int m = 0; m < 4; ++m) _Pragma("unroll") for (int n = 0; n < 2; ++n) _Pragma("unroll") for (int k = 0; k < 2; ++k) \
;         acc[ai][bj][m][n] = __builtin_amdgcn_mfma_f32_16x16x32_bf16(Bt[n][k], At[m][k], acc[ai][bj][m][n], 0, 0, 0); __builtin_amdgcn_s_setprio(0); } while (0)
; #define PG8_WAIT_V(n) asm volatile("s_waitcnt vmcnt(" #n ")" ::: "memory")
; #define PG8_WAIT_L(n) asm volatile("s_waitcnt lgkmcnt(" #n ")" ::: "memory")
; #define PG8_BAR __builtin_amdgcn_s_barrier()
; #define PG8_SCHED __builtin_amdgcn_sched_barrier(0)
; template <class Epi>
; __device__ __forceinline__ void gemm_phase(LAS unsigned char* lds, const Gemm g, const Sched& S, const Epi& E, const int tid) {
;     ...
;             PG8_WAIT_V(8); PG8_WAIT_L(0); PG8_BAR; PG8_MMA(0, 0, At, B0); PG8_MMA(0, 1, At, B1); PG8_BAR; PG8_SCHED;
;             PG8_LDA(At, 0, 1); PG8_STAGE(PG8_SB(0, 0), b2, voffB); PG8_STAGE(PG8_SB(0, 1), b2 + hB, voffB); PG8_STAGE(PG8_SA(0, 0), a2, voffA);
;             PG8_WAIT_V(8); PG8_WAIT_L(0); PG8_BAR; PG8_MMA(1, 0, At, B0); PG8_MMA(1, 1, At, B1); PG8_BAR; PG8_SCHED;
	s_setprio 1
	s_waitcnt lgkmcnt(0)
	v_mfma_f32_16x16x32_bf16 v[140:143], v[64:67], v[176:179], v[140:143]
	v_mfma_f32_16x16x32_bf16 v[136:139], v[80:83], v[176:179], v[136:139]
	v_mfma_f32_16x16x32_bf16 v[132:135], v[64:67], v[184:187], v[132:135]
	v_mfma_f32_16x16x32_bf16 v[128:131], v[80:83], v[184:187], v[128:131]
	v_mfma_f32_16x16x32_bf16 v[108:111], v[64:67], v[194:197], v[108:111]
	v_mfma_f32_16x16x32_bf16 v[104:107], v[80:83], v[194:197], v[104:107]
	v_mfma_f32_16x16x32_bf16 v[100:103], v[64:67], v[204:207], v[100:103]
	v_mfma_f32_16x16x32_bf16 v[96:99], v[80:83], v[204:207], v[96:99]
	v_mfma_f32_16x16x32_bf16 v[140:143], v[68:71], v[180:183], v[140:143]
	v_mfma_f32_16x16x32_bf16 v[136:139], v[92:95], v[180:183], v[136:139]
	v_mfma_f32_16x16x32_bf16 v[132:135], v[68:71], v[188:191], v[132:135]
	v_mfma_f32_16x16x32_bf16 v[128:131], v[92:95], v[188:191], v[128:131]
	v_mfma_f32_16x16x32_bf16 v[108:111], v[68:71], v[198:201], v[108:111]
	v_mfma_f32_16x16x32_bf16 v[104:107], v[92:95], v[198:201], v[104:107]
	v_mfma_f32_16x16x32_bf16 v[100:103], v[68:71], v[208:211], v[100:103]
	v_mfma_f32_16x16x32_bf16 v[96:99], v[92:95], v[208:211], v[96:99]
	v_mfma_f32_16x16x32_bf16 v[124:127], v[160:163], v[176:179], v[124:127]
	v_mfma_f32_16x16x32_bf16 v[120:123], v[168:171], v[176:179], v[120:123]
	v_mfma_f32_16x16x32_bf16 v[116:119], v[160:163], v[184:187], v[116:119]
	v_mfma_f32_16x16x32_bf16 v[112:115], v[168:171], v[184:187], v[112:115]
	v_mfma_f32_16x16x32_bf16 v[88:91], v[160:163], v[194:197], v[88:91]
	v_mfma_f32_16x16x32_bf16 v[84:87], v[168:171], v[194:197], v[84:87]
	v_mfma_f32_16x16x32_bf16 v[76:79], v[160:163], v[204:207], v[76:79]
	v_mfma_f32_16x16x32_bf16 v[72:75], v[168:171], v[204:207], v[72:75]
	v_mfma_f32_16x16x32_bf16 v[124:127], v[164:167], v[180:183], v[124:127]
	v_mfma_f32_16x16x32_bf16 v[120:123], v[172:175], v[180:183], v[120:123]
	v_mfma_f32_16x16x32_bf16 v[116:119], v[164:167], v[188:191], v[116:119]
	v_mfma_f32_16x16x32_bf16 v[112:115], v[172:175], v[188:191], v[112:115]
	v_mfma_f32_16x16x32_bf16 v[88:91], v[164:167], v[198:201], v[88:91]
	v_mfma_f32_16x16x32_bf16 v[84:87], v[172:175], v[198:201], v[84:87]
	v_mfma_f32_16x16x32_bf16 v[76:79], v[164:167], v[208:211], v[76:79]
	v_mfma_f32_16x16x32_bf16 v[72:75], v[172:175], v[208:211], v[72:75]
	s_setprio 0
	s_barrier
	s_add_i32 s16, s43, s39
	v_lshl_add_u64 v[154:155], s[20:21], 0, v[192:193]
	s_mov_b32 m0, s16
	ds_read_b128 v[176:179], v159 offset:16384
	ds_read_b128 v[180:183], v159 offset:17408
	ds_read_b128 v[184:187], v159 offset:18432
	ds_read_b128 v[188:191], v159 offset:19456
	ds_read_b128 v[194:197], v159 offset:20480
	ds_read_b128 v[198:201], v159 offset:21504
	ds_read_b128 v[204:207], v159 offset:22528
	ds_read_b128 v[208:211], v159 offset:23552
	global_load_lds_dwordx4 v[154:155], off
	s_add_i32 m0, s16, 0x2000
	s_add_u32 s16, s20, 0xb0000
	v_lshl_add_u64 v[212:213], s[20:21], 0, v[144:145]
	s_addc_u32 s17, s21, 0
	s_add_i32 s43, s44, s39
	global_load_lds_dwordx4 v[212:213], off
	v_lshl_add_u64 v[214:215], s[16:17], 0, v[192:193]
	s_mov_b32 m0, s43
	v_lshl_add_u64 v[216:217], s[22:23], 0, v[146:147]
	global_load_lds_dwordx4 v[214:215], off
	v_lshl_add_u64 v[214:215], s[16:17], 0, v[144:145]
	s_add_i32 m0, s43, 0x2000
	s_nop 0
	global_load_lds_dwordx4 v[214:215], off
	v_lshl_add_u64 v[214:215], s[22:23], 0, v[148:149]
	s_mov_b32 m0, s40
	s_nop 0
	global_load_lds_dwordx4 v[214:215], off
	s_mov_b32 m0, s73
	s_nop 0
	global_load_lds_dwordx4 v[216:217], off
	s_waitcnt vmcnt(8)
	s_waitcnt lgkmcnt(0)
	s_barrier
	s_setprio 1
	s_waitcnt lgkmcnt(0)
	v_mfma_f32_16x16x32_bf16 v[60:63], v[64:67], v[176:179], v[60:63]
	v_mfma_f32_16x16x32_bf16 v[56:59], v[80:83], v[176:179], v[56:59]
	v_mfma_f32_16x16x32_bf16 v[52:55], v[64:67], v[184:187], v[52:55]
	v_mfma_f32_16x16x32_bf16 v[48:51], v[80:83], v[184:187], v[48:51]
	v_mfma_f32_16x16x32_bf16 v[28:31], v[64:67], v[194:197], v[28:31]
	v_mfma_f32_16x16x32_bf16 v[24:27], v[80:83], v[194:197], v[24:27]
	v_mfma_f32_16x16x32_bf16 v[16:19], v[64:67], v[204:207], v[16:19]
	v_mfma_f32_16x16x32_bf16 v[8:11], v[80:83], v[204:207], v[8:11]
	v_mfma_f32_16x16x32_bf16 v[60:63], v[68:71], v[180:183], v[60:63]
	v_mfma_f32_16x16x32_bf16 v[56:59], v[92:95], v[180:183], v[56:59]
	v_mfma_f32_16x16x32_bf16 v[52:55], v[68:71], v[188:191], v[52:55]
	v_mfma_f32_16x16x32_bf16 v[48:51], v[92:95], v[188:191], v[48:51]
	v_mfma_f32_16x16x32_bf16 v[28:31], v[68:71], v[198:201], v[28:31]
	v_mfma_f32_16x16x32_bf16 v[24:27], v[92:95], v[198:201], v[24:27]
	v_mfma_f32_16x16x32_bf16 v[16:19], v[68:71], v[208:211], v[16:19]
	v_mfma_f32_16x16x32_bf16 v[8:11], v[92:95], v[208:211], v[8:11]
	v_mfma_f32_16x16x32_bf16 v[44:47], v[160:163], v[176:179], v[44:47]
	v_mfma_f32_16x16x32_bf16 v[40:43], v[168:171], v[176:179], v[40:43]
	v_mfma_f32_16x16x32_bf16 v[36:39], v[160:163], v[184:187], v[36:39]
	v_mfma_f32_16x16x32_bf16 v[32:35], v[168:171], v[184:187], v[32:35]
	v_mfma_f32_16x16x32_bf16 v[20:23], v[160:163], v[194:197], v[20:23]
	v_mfma_f32_16x16x32_bf16 v[12:15], v[168:171], v[194:197], v[12:15]
	v_mfma_f32_16x16x32_bf16 v[4:7], v[160:163], v[204:207], v[4:7]
	v_mfma_f32_16x16x32_bf16 v[0:3], v[168:171], v[204:207], v[0:3]
	v_mfma_f32_16x16x32_bf16 v[44:47], v[164:167], v[180:183], v[44:47]
	v_mfma_f32_16x16x32_bf16 v[40:43], v[172:175], v[180:183], v[40:43]
	v_mfma_f32_16x16x32_bf16 v[36:39], v[164:167], v[188:191], v[36:39]
	v_mfma_f32_16x16x32_bf16 v[32:35], v[172:175], v[188:191], v[32:35]
	v_mfma_f32_16x16x32_bf16 v[20:23], v[164:167], v[198:201], v[20:23]
	v_mfma_f32_16x16x32_bf16 v[12:15], v[172:175], v[198:201], v[12:15]
	v_mfma_f32_16x16x32_bf16 v[4:7], v[164:167], v[208:211], v[4:7]
	v_mfma_f32_16x16x32_bf16 v[0:3], v[172:175], v[208:211], v[0:3]
	s_setprio 0
	s_barrier
; #define PG8_STAGE(bufoff, gbase, voff) do { _Pragma("unroll") for (int _i = 0; _i < 2; ++_i) \
;         __builtin_amdgcn_global_load_lds((const unsigned*)((const char*)(gbase) + (voff)[_i]), (LAS unsigned*)(lds + (bufoff) + ldsw + _i * 8192), 16, 0, 0); } while (0)
; #define PG8_LDA(dst, b, h) do { _Pragma("unroll") for (int m = 0; m < 4; ++m) _Pragma("unroll") for (int k = 0; k < 2; ++k) dst[m][k] = *(const LAS bf16x8*)(lds + PG8_SA(b, h) + aoff + m * 2048 + k * 1024); } while (0)
; #define PG8_LDB(dst, b, h) do { _Pragma("unroll") for (int n = 0; n < 2; ++n) _Pragma("unroll") for (int k = 0; k < 2; ++k) dst[n][k] = *(const LAS bf16x8*)(lds + PG8_SB(b, h) + boff + n * 2048 + k * 1024); } while (0)
; #define PG8_WAIT_V(n) asm volatile("s_waitcnt vmcnt(" #n ")" ::: "memory")
; #define PG8_WAIT_L(n) asm volatile("s_waitcnt lgkmcnt(" #n ")" ::: "memory")
; template <class Epi>
; __device__ __forceinline__ void gemm_phase(LAS unsigned char* lds, const Gemm g, const Sched& S, const Epi& E, const int tid) {
;     ...
;         for (int t = 0; t < nt; t += 2) {
;             const bool last = (t == nt - 2);
;             const char* a1 = cA + (size_t)(t + 1) * kstep;
;             const char* a2 = last ? nA : cA + (size_t)(t + 2) * kstep; const char* b2 = last ? nB : cB + (size_t)(t + 2) * kstep;
;             const char* a3 = a2 + kstep; const char* b3 = b2 + kstep;
;             PG8_LDB(B0, 0, 0); PG8_LDB(B1, 0, 1); PG8_SCHED; PG8_LDA(At, 0, 0); PG8_STAGE(PG8_SA(1, 1), a1 + hA, voffA);
;             PG8_WAIT_V(8); PG8_WAIT_L(0); PG8_BAR; PG8_MMA(0, 0, At, B0); PG8_MMA(0, 1, At, B1); PG8_BAR; PG8_SCHED;
;             PG8_LDA(At, 0, 1); PG8_STAGE(PG8_SB(0, 0), b2, voffB); PG8_STAGE(PG8_SB(0, 1), b2 + hB, voffB); PG8_STAGE(PG8_SA(0, 0), a2, voffA);
;             PG8_WAIT_V(8); PG8_WAIT_L(0); PG8_BAR; PG8_MMA(1, 0, At, B0); PG8_MMA(1, 1, At, B1); PG8_BAR; PG8_SCHED;
;             PG8_LDB(B0, 1, 0); PG8_LDB(B1, 1, 1); PG8_SCHED; PG8_LDA(At, 1, 0); PG8_STAGE(PG8_SA(0, 1), a2 + hA, voffA);
;             PG8_WAIT_V(8); PG8_WAIT_L(0); PG8_BAR; PG8_MMA(0, 0, At, B0); PG8_MMA(0, 1, At, B1); PG8_BAR; PG8_SCHED;
;             PG8_LDA(At, 1, 1); PG8_STAGE(PG8_SB(1, 0), b3, voffB); PG8_STAGE(PG8_SB(1, 1), b3 + hB, voffB); PG8_STAGE(PG8_SA(1, 0), a3, voffA);
;             PG8_WAIT_V(8); PG8_WAIT_L(0); PG8_BAR; PG8_MMA(1, 0, At, B0); PG8_MMA(1, 1, At, B1); PG8_BAR; PG8_SCHED;
	s_add_i32 s43, 0, 0x18000
	s_add_i32 s44, 0, 0x1c000
	v_add_u32_e32 v92, s43, v157
	v_add_u32_e32 v172, s44, v157
	ds_read_b128 v[64:67], v92
	ds_read_b128 v[68:71], v92 offset:1024
	ds_read_b128 v[80:83], v92 offset:2048
	ds_read_b128 v[92:95], v92 offset:3072
	ds_read_b128 v[160:163], v172
	ds_read_b128 v[164:167], v172 offset:1024
	ds_read_b128 v[168:171], v172 offset:2048
	ds_read_b128 v[172:175], v172 offset:3072
	s_add_u32 s16, s22, 0xb0000
	s_addc_u32 s17, s23, 0
	s_mov_b32 m0, s74
	v_lshl_add_u64 v[218:219], s[16:17], 0, v[148:149]
	ds_read_b128 v[176:179], v159 offset:32768
	ds_read_b128 v[180:183], v159 offset:33792
	ds_read_b128 v[184:187], v159 offset:34816
	ds_read_b128 v[188:191], v159 offset:35840
	ds_read_b128 v[194:197], v159 offset:36864
	ds_read_b128 v[198:201], v159 offset:37888
	ds_read_b128 v[204:207], v159 offset:38912
	ds_read_b128 v[208:211], v159 offset:39936
	global_load_lds_dwordx4 v[218:219], off
	v_lshl_add_u64 v[218:219], s[16:17], 0, v[146:147]
	s_mov_b32 m0, s75
	s_nop 0
	global_load_lds_dwordx4 v[218:219], off
	s_waitcnt vmcnt(8)
	s_waitcnt lgkmcnt(0)
	s_barrier
	s_setprio 1
	s_waitcnt lgkmcnt(0)
	v_mfma_f32_16x16x32_bf16 v[140:143], v[64:67], v[176:179], v[140:143]
	v_mfma_f32_16x16x32_bf16 v[136:139], v[80:83], v[176:179], v[136:139]
	v_mfma_f32_16x16x32_bf16 v[132:135], v[64:67], v[184:187], v[132:135]
	v_mfma_f32_16x16x32_bf16 v[128:131], v[80:83], v[184:187], v[128:131]
	v_mfma_f32_16x16x32_bf16 v[108:111], v[64:67], v[194:197], v[108:111]
	v_mfma_f32_16x16x32_bf16 v[104:107], v[80:83], v[194:197], v[104:107]
	v_mfma_f32_16x16x32_bf16 v[100:103], v[64:67], v[204:207], v[100:103]
	v_mfma_f32_16x16x32_bf16 v[96:99], v[80:83], v[204:207], v[96:99]
	v_mfma_f32_16x16x32_bf16 v[140:143], v[68:71], v[180:183], v[140:143]
	v_mfma_f32_16x16x32_bf16 v[136:139], v[92:95], v[180:183], v[136:139]
	v_mfma_f32_16x16x32_bf16 v[132:135], v[68:71], v[188:191], v[132:135]
	v_mfma_f32_16x16x32_bf16 v[128:131], v[92:95], v[188:191], v[128:131]
	v_mfma_f32_16x16x32_bf16 v[108:111], v[68:71], v[198:201], v[108:111]
	v_mfma_f32_16x16x32_bf16 v[104:107], v[92:95], v[198:201], v[104:107]
	v_mfma_f32_16x16x32_bf16 v[100:103], v[68:71], v[208:211], v[100:103]
	v_mfma_f32_16x16x32_bf16 v[96:99], v[92:95], v[208:211], v[96:99]
	v_mfma_f32_16x16x32_bf16 v[124:127], v[160:163], v[176:179], v[124:127]
	v_mfma_f32_16x16x32_bf16 v[120:123], v[168:171], v[176:179], v[120:123]
	v_mfma_f32_16x16x32_bf16 v[116:119], v[160:163], v[184:187], v[116:119]
	v_mfma_f32_16x16x32_bf16 v[112:115], v[168:171], v[184:187], v[112:115]
	v_mfma_f32_16x16x32_bf16 v[88:91], v[160:163], v[194:197], v[88:91]
	v_mfma_f32_16x16x32_bf16 v[84:87], v[168:171], v[194:197], v[84:87]
	v_mfma_f32_16x16x32_bf16 v[76:79], v[160:163], v[204:207], v[76:79]
	v_mfma_f32_16x16x32_bf16 v[72:75], v[168:171], v[204:207], v[72:75]
	v_mfma_f32_16x16x32_bf16 v[124:127], v[164:167], v[180:183], v[124:127]
	v_mfma_f32_16x16x32_bf16 v[120:123], v[172:175], v[180:183], v[120:123]
	v_mfma_f32_16x16x32_bf16 v[116:119], v[164:167], v[188:191], v[116:119]
	v_mfma_f32_16x16x32_bf16 v[112:115], v[172:175], v[188:191], v[112:115]
	v_mfma_f32_16x16x32_bf16 v[88:91], v[164:167], v[198:201], v[88:91]
	v_mfma_f32_16x16x32_bf16 v[84:87], v[172:175], v[198:201], v[84:87]
	v_mfma_f32_16x16x32_bf16 v[76:79], v[164:167], v[208:211], v[76:79]
	v_mfma_f32_16x16x32_bf16 v[72:75], v[172:175], v[208:211], v[72:75]
	s_setprio 0
	s_barrier
	s_add_i32 s16, s43, s39
	v_lshl_add_u64 v[154:155], v[154:155], 0, s[94:95]
	s_mov_b32 m0, s16
	ds_read_b128 v[176:179], v159 offset:49152
	ds_read_b128 v[180:183], v159 offset:50176
	ds_read_b128 v[184:187], v159 offset:51200
	ds_read_b128 v[188:191], v159 offset:52224
	ds_read_b128 v[194:197], v159 offset:53248
	ds_read_b128 v[198:201], v159 offset:54272
	ds_read_b128 v[204:207], v159 offset:55296
	ds_read_b128 v[208:211], v159 offset:56320
	global_load_lds_dwordx4 v[154:155], off
	s_add_i32 m0, s16, 0x2000
	s_add_u32 s16, s20, 0xb0080
	v_lshl_add_u64 v[154:155], v[212:213], 0, s[94:95]
	s_addc_u32 s17, s21, 0
	s_add_i32 s20, s44, s39
	global_load_lds_dwordx4 v[154:155], off
	v_lshl_add_u64 v[154:155], s[16:17], 0, v[192:193]
	s_mov_b32 m0, s20
	s_nop 0
	global_load_lds_dwordx4 v[154:155], off
	v_lshl_add_u64 v[154:155], s[16:17], 0, v[144:145]
	s_add_i32 m0, s20, 0x2000
	s_nop 0
	global_load_lds_dwordx4 v[154:155], off
	v_lshl_add_u64 v[154:155], v[214:215], 0, s[94:95]
	s_mov_b32 m0, s51
	s_nop 0
	global_load_lds_dwordx4 v[154:155], off
	v_lshl_add_u64 v[154:155], v[216:217], 0, s[94:95]
	s_mov_b32 m0, s76
	s_nop 0
	global_load_lds_dwordx4 v[154:155], off
	s_waitcnt vmcnt(8)
	s_waitcnt lgkmcnt(0)
	s_barrier
	s_setprio 1
	s_waitcnt lgkmcnt(0)
	v_mfma_f32_16x16x32_bf16 v[60:63], v[64:67], v[176:179], v[60:63]
	v_mfma_f32_16x16x32_bf16 v[56:59], v[80:83], v[176:179], v[56:59]
	v_mfma_f32_16x16x32_bf16 v[52:55], v[64:67], v[184:187], v[52:55]
	v_mfma_f32_16x16x32_bf16 v[48:51], v[80:83], v[184:187], v[48:51]
	v_mfma_f32_16x16x32_bf16 v[28:31], v[64:67], v[194:197], v[28:31]
	v_mfma_f32_16x16x32_bf16 v[24:27], v[80:83], v[194:197], v[24:27]
	v_mfma_f32_16x16x32_bf16 v[16:19], v[64:67], v[204:207], v[16:19]
	v_mfma_f32_16x16x32_bf16 v[8:11], v[80:83], v[204:207], v[8:11]
	v_mfma_f32_16x16x32_bf16 v[60:63], v[68:71], v[180:183], v[60:63]
	v_mfma_f32_16x16x32_bf16 v[56:59], v[92:95], v[180:183], v[56:59]
	v_mfma_f32_16x16x32_bf16 v[52:55], v[68:71], v[188:191], v[52:55]
	v_mfma_f32_16x16x32_bf16 v[48:51], v[92:95], v[188:191], v[48:51]
	v_mfma_f32_16x16x32_bf16 v[28:31], v[68:71], v[198:201], v[28:31]
	v_mfma_f32_16x16x32_bf16 v[24:27], v[92:95], v[198:201], v[24:27]
	v_mfma_f32_16x16x32_bf16 v[16:19], v[68:71], v[208:211], v[16:19]
	v_mfma_f32_16x16x32_bf16 v[8:11], v[92:95], v[208:211], v[8:11]
	v_mfma_f32_16x16x32_bf16 v[44:47], v[160:163], v[176:179], v[44:47]
	v_mfma_f32_16x16x32_bf16 v[40:43], v[168:171], v[176:179], v[40:43]
	v_mfma_f32_16x16x32_bf16 v[36:39], v[160:163], v[184:187], v[36:39]
	v_mfma_f32_16x16x32_bf16 v[32:35], v[168:171], v[184:187], v[32:35]
	v_mfma_f32_16x16x32_bf16 v[20:23], v[160:163], v[194:197], v[20:23]
	v_mfma_f32_16x16x32_bf16 v[12:15], v[168:171], v[194:197], v[12:15]
	v_mfma_f32_16x16x32_bf16 v[4:7], v[160:163], v[204:207], v[4:7]
	v_mfma_f32_16x16x32_bf16 v[0:3], v[168:171], v[204:207], v[0:3]
	v_mfma_f32_16x16x32_bf16 v[44:47], v[164:167], v[180:183], v[44:47]
	v_mfma_f32_16x16x32_bf16 v[40:43], v[172:175], v[180:183], v[40:43]
	v_mfma_f32_16x16x32_bf16 v[36:39], v[164:167], v[188:191], v[36:39]
	v_mfma_f32_16x16x32_bf16 v[32:35], v[172:175], v[188:191], v[32:35]
	v_mfma_f32_16x16x32_bf16 v[20:23], v[164:167], v[198:201], v[20:23]
	v_mfma_f32_16x16x32_bf16 v[12:15], v[172:175], v[198:201], v[12:15]
	v_mfma_f32_16x16x32_bf16 v[4:7], v[164:167], v[208:211], v[4:7]
	v_mfma_f32_16x16x32_bf16 v[0:3], v[172:175], v[208:211], v[0:3]
	s_add_i32 vcc_lo, vcc_lo, 2
	s_add_u32 s80, s80, 0x100
	s_addc_u32 s81, s81, 0
	s_cmp_gt_u32 vcc_lo, 41
	s_mov_b64 s[16:17], s[18:19]
	s_setprio 0
	s_barrier
	s_cbranch_scc0 .LBB0_1411
